# v91 lineage (head-merged pointer selects, no VALU address ops in K-loops) + barrier-boundary setprio placement
# speedup vs baseline: 1.0065x; 1.0008x over previous
.LBB0_161:
	s_add_u32 s86, s69, s6
	s_addc_u32 s87, s70, s7
	s_add_u32 s88, s71, s8
	s_addc_u32 s89, s72, s9
	s_ashr_i32 s23, s22, 31
	s_lshl_b64 s[6:7], s[22:23], 19
	s_add_u32 s24, s34, s6
	s_addc_u32 s25, s35, s7
	s_and_b64 s[8:9], s[0:1], exec
	s_cselect_b32 s23, s25, s43
	s_cselect_b32 s90, s24, s42
	s_ashr_i32 s21, s20, 31
	s_lshl_b64 s[8:9], s[20:21], 19
	s_add_u32 s26, s17, s8
	s_addc_u32 s27, s19, s9
	s_and_b64 s[48:49], s[0:1], exec
	s_cselect_b32 s21, s27, s39
	s_cselect_b32 s91, s26, s38
	s_add_u32 s48, s90, 0x80
	s_addc_u32 s49, s23, 0
	s_add_u32 s54, s91, 0x80
	s_addc_u32 s55, s21, 0
	v_lshl_add_u64 v[128:129], s[42:43], 0, v[150:151]
	v_lshl_add_u64 v[130:131], s[42:43], 0, v[152:153]
	s_mov_b32 s92, 0
	s_mov_b64 s[56:57], 0
	v_add_u32_e32 v232, 0x10000, v171
	s_add_u32 s64, s42, s56
	s_addc_u32 s65, s43, s57
	s_mov_b64 s[100:101], s[64:65]
	s_add_u32 s94, s38, s56
	s_addc_u32 s93, s39, s57
	s_add_u32 s58, s64, 0x180
	s_addc_u32 s59, s65, 0
	s_add_u32 s60, s94, 0x180
	s_addc_u32 s61, s93, 0
	s_add_u32 s64, s64, 0x100
	s_addc_u32 s65, s65, 0
	s_add_u32 s62, s94, 0x100
	s_addc_u32 s63, s93, 0
	s_cmpk_eq_i32 s56, 0x700
	s_cselect_b32 s58, s48, s58
	s_cselect_b32 s59, s49, s59
	s_cselect_b32 s60, s54, s60
	s_cselect_b32 s61, s55, s61
	s_cselect_b32 s64, s90, s64
	s_cselect_b32 s65, s23, s65
	s_cselect_b32 s62, s91, s62
	s_cselect_b32 s63, s21, s63
	ds_read_b128 v[132:135], v232
	ds_read_b128 v[158:161], v232 offset:1024
	ds_read_b128 v[162:165], v232 offset:2048
	ds_read_b128 v[166:169], v232 offset:3072
	ds_read_b128 v[184:187], v232 offset:16384
	ds_read_b128 v[188:191], v232 offset:17408
	ds_read_b128 v[192:195], v232 offset:18432
	ds_read_b128 v[196:199], v232 offset:19456
	s_add_i32 m0, s29, 0xc000
	ds_read_b128 v[200:203], v181
	ds_read_b128 v[204:207], v181 offset:1024
	ds_read_b128 v[208:211], v181 offset:2048
	ds_read_b128 v[212:215], v181 offset:3072
	ds_read_b128 v[216:219], v181 offset:4096
	ds_read_b128 v[220:223], v181 offset:5120
	ds_read_b128 v[224:227], v181 offset:6144
	global_load_lds_dwordx4 v150, s[100:101]
	s_add_i32 m0, s29, 0xe000
	ds_read_b128 v[228:231], v181 offset:7168
	global_load_lds_dwordx4 v152, s[100:101]
	s_waitcnt vmcnt(8)
	s_waitcnt lgkmcnt(0)
	s_setprio 1
	s_barrier
	v_mfma_f32_16x16x32_bf16 v[124:127], v[132:135], v[200:203], 0
	v_mfma_f32_16x16x32_bf16 v[120:123], v[162:165], v[200:203], 0
	v_mfma_f32_16x16x32_bf16 v[108:111], v[132:135], v[208:211], 0
	v_mfma_f32_16x16x32_bf16 v[104:107], v[162:165], v[208:211], 0
	v_mfma_f32_16x16x32_bf16 v[92:95], v[132:135], v[216:219], 0
	v_mfma_f32_16x16x32_bf16 v[88:91], v[162:165], v[216:219], 0
	v_mfma_f32_16x16x32_bf16 v[76:79], v[132:135], v[224:227], 0
	v_mfma_f32_16x16x32_bf16 v[72:75], v[162:165], v[224:227], 0
	v_mfma_f32_16x16x32_bf16 v[124:127], v[158:161], v[204:207], v[124:127]
	v_mfma_f32_16x16x32_bf16 v[120:123], v[166:169], v[204:207], v[120:123]
	v_mfma_f32_16x16x32_bf16 v[108:111], v[158:161], v[212:215], v[108:111]
	v_mfma_f32_16x16x32_bf16 v[104:107], v[166:169], v[212:215], v[104:107]
	v_mfma_f32_16x16x32_bf16 v[92:95], v[158:161], v[220:223], v[92:95]
	v_mfma_f32_16x16x32_bf16 v[88:91], v[166:169], v[220:223], v[88:91]
	v_mfma_f32_16x16x32_bf16 v[76:79], v[158:161], v[228:231], v[76:79]
	v_mfma_f32_16x16x32_bf16 v[72:75], v[166:169], v[228:231], v[72:75]
	s_setprio 0
	s_setprio 1
	v_mfma_f32_16x16x32_bf16 v[116:119], v[184:187], v[200:203], 0
	v_mfma_f32_16x16x32_bf16 v[112:115], v[192:195], v[200:203], 0
	v_mfma_f32_16x16x32_bf16 v[100:103], v[184:187], v[208:211], 0
	v_mfma_f32_16x16x32_bf16 v[96:99], v[192:195], v[208:211], 0
	v_mfma_f32_16x16x32_bf16 v[84:87], v[184:187], v[216:219], 0
	v_mfma_f32_16x16x32_bf16 v[80:83], v[192:195], v[216:219], 0
	v_mfma_f32_16x16x32_bf16 v[68:71], v[184:187], v[224:227], 0
	v_mfma_f32_16x16x32_bf16 v[64:67], v[192:195], v[224:227], 0
	v_mfma_f32_16x16x32_bf16 v[116:119], v[188:191], v[204:207], v[116:119]
	v_mfma_f32_16x16x32_bf16 v[112:115], v[196:199], v[204:207], v[112:115]
	v_mfma_f32_16x16x32_bf16 v[100:103], v[188:191], v[212:215], v[100:103]
	v_mfma_f32_16x16x32_bf16 v[96:99], v[196:199], v[212:215], v[96:99]
	v_mfma_f32_16x16x32_bf16 v[84:87], v[188:191], v[220:223], v[84:87]
	v_mfma_f32_16x16x32_bf16 v[80:83], v[196:199], v[220:223], v[80:83]
	v_mfma_f32_16x16x32_bf16 v[68:71], v[188:191], v[228:231], v[68:71]
	v_mfma_f32_16x16x32_bf16 v[64:67], v[196:199], v[228:231], v[64:67]
	s_barrier
	s_setprio 0
	s_add_i32 s10, s82, s66
	s_mov_b32 m0, s10
	ds_read_b128 v[200:203], v181 offset:16384
	ds_read_b128 v[204:207], v181 offset:17408
	ds_read_b128 v[208:211], v181 offset:18432
	global_load_lds_dwordx4 v138, s[62:63]
	s_add_i32 m0, s10, 0x2000
	ds_read_b128 v[212:215], v181 offset:19456
	global_load_lds_dwordx4 v142, s[62:63]
	s_add_u32 s62, s62, 0x40000
	s_addc_u32 s63, s63, 0
	s_add_i32 s10, s83, s66
	s_mov_b32 m0, s10
	ds_read_b128 v[216:219], v181 offset:20480
	global_load_lds_dwordx4 v138, s[62:63]
	s_add_i32 m0, s10, 0x2000
	ds_read_b128 v[220:223], v181 offset:21504
	global_load_lds_dwordx4 v142, s[62:63]
	s_mov_b32 m0, s29
	ds_read_b128 v[224:227], v181 offset:22528
	global_load_lds_dwordx4 v136, s[64:65]
	s_mov_b32 m0, s31
	ds_read_b128 v[228:231], v181 offset:23552
	global_load_lds_dwordx4 v140, s[64:65]
	s_waitcnt vmcnt(8)
	s_waitcnt lgkmcnt(0)
	s_setprio 1
	s_barrier
	v_mfma_f32_16x16x32_bf16 v[60:63], v[132:135], v[200:203], 0
	v_mfma_f32_16x16x32_bf16 v[56:59], v[162:165], v[200:203], 0
	v_mfma_f32_16x16x32_bf16 v[44:47], v[132:135], v[208:211], 0
	v_mfma_f32_16x16x32_bf16 v[40:43], v[162:165], v[208:211], 0
	v_mfma_f32_16x16x32_bf16 v[28:31], v[132:135], v[216:219], 0
	v_mfma_f32_16x16x32_bf16 v[24:27], v[162:165], v[216:219], 0
	v_mfma_f32_16x16x32_bf16 v[12:15], v[132:135], v[224:227], 0
	v_mfma_f32_16x16x32_bf16 v[8:11], v[162:165], v[224:227], 0
	v_mfma_f32_16x16x32_bf16 v[60:63], v[158:161], v[204:207], v[60:63]
	v_mfma_f32_16x16x32_bf16 v[56:59], v[166:169], v[204:207], v[56:59]
	v_mfma_f32_16x16x32_bf16 v[44:47], v[158:161], v[212:215], v[44:47]
	v_mfma_f32_16x16x32_bf16 v[40:43], v[166:169], v[212:215], v[40:43]
	v_mfma_f32_16x16x32_bf16 v[28:31], v[158:161], v[220:223], v[28:31]
	v_mfma_f32_16x16x32_bf16 v[24:27], v[166:169], v[220:223], v[24:27]
	v_mfma_f32_16x16x32_bf16 v[12:15], v[158:161], v[228:231], v[12:15]
	v_mfma_f32_16x16x32_bf16 v[8:11], v[166:169], v[228:231], v[8:11]
	s_setprio 0
	s_setprio 1
	v_mfma_f32_16x16x32_bf16 v[52:55], v[184:187], v[200:203], 0
	v_mfma_f32_16x16x32_bf16 v[48:51], v[192:195], v[200:203], 0
	v_mfma_f32_16x16x32_bf16 v[36:39], v[184:187], v[208:211], 0
	v_mfma_f32_16x16x32_bf16 v[32:35], v[192:195], v[208:211], 0
	v_mfma_f32_16x16x32_bf16 v[20:23], v[184:187], v[216:219], 0
	v_mfma_f32_16x16x32_bf16 v[16:19], v[192:195], v[216:219], 0
	v_mfma_f32_16x16x32_bf16 v[4:7], v[184:187], v[224:227], 0
	v_mfma_f32_16x16x32_bf16 v[0:3], v[192:195], v[224:227], 0
	v_mfma_f32_16x16x32_bf16 v[52:55], v[188:191], v[204:207], v[52:55]
	v_mfma_f32_16x16x32_bf16 v[48:51], v[196:199], v[204:207], v[48:51]
	v_mfma_f32_16x16x32_bf16 v[36:39], v[188:191], v[212:215], v[36:39]
	v_mfma_f32_16x16x32_bf16 v[32:35], v[196:199], v[212:215], v[32:35]
	v_mfma_f32_16x16x32_bf16 v[20:23], v[188:191], v[220:223], v[20:23]
	v_mfma_f32_16x16x32_bf16 v[16:19], v[196:199], v[220:223], v[16:19]
	v_mfma_f32_16x16x32_bf16 v[4:7], v[188:191], v[228:231], v[4:7]
	v_mfma_f32_16x16x32_bf16 v[0:3], v[196:199], v[228:231], v[0:3]
	s_barrier
	s_setprio 0
	s_add_i32 s10, 0, 0x18000
	s_add_i32 s93, 0, 0x1c000
	ds_read_b128 v[132:135], v232 offset:32768
	ds_read_b128 v[158:161], v232 offset:33792
	ds_read_b128 v[162:165], v232 offset:34816
	ds_read_b128 v[166:169], v232 offset:35840
	ds_read_b128 v[184:187], v232 offset:49152
	ds_read_b128 v[188:191], v232 offset:50176
	ds_read_b128 v[192:195], v232 offset:51200
	ds_read_b128 v[196:199], v232 offset:52224
	s_add_u32 s62, s64, 0x40000
	s_addc_u32 s63, s65, 0
	s_mov_b32 m0, s67
	ds_read_b128 v[200:203], v181 offset:32768
	ds_read_b128 v[204:207], v181 offset:33792
	ds_read_b128 v[208:211], v181 offset:34816
	ds_read_b128 v[212:215], v181 offset:35840
	ds_read_b128 v[216:219], v181 offset:36864
	ds_read_b128 v[220:223], v181 offset:37888
	ds_read_b128 v[224:227], v181 offset:38912
	global_load_lds_dwordx4 v136, s[62:63]
	s_mov_b32 m0, s68
	ds_read_b128 v[228:231], v181 offset:39936
	global_load_lds_dwordx4 v140, s[62:63]
	s_waitcnt vmcnt(8)
	s_waitcnt lgkmcnt(0)
	s_setprio 1
	s_barrier
	v_mfma_f32_16x16x32_bf16 v[124:127], v[132:135], v[200:203], v[124:127]
	v_mfma_f32_16x16x32_bf16 v[120:123], v[162:165], v[200:203], v[120:123]
	v_mfma_f32_16x16x32_bf16 v[108:111], v[132:135], v[208:211], v[108:111]
	v_mfma_f32_16x16x32_bf16 v[104:107], v[162:165], v[208:211], v[104:107]
	v_mfma_f32_16x16x32_bf16 v[92:95], v[132:135], v[216:219], v[92:95]
	v_mfma_f32_16x16x32_bf16 v[88:91], v[162:165], v[216:219], v[88:91]
	v_mfma_f32_16x16x32_bf16 v[76:79], v[132:135], v[224:227], v[76:79]
	v_mfma_f32_16x16x32_bf16 v[72:75], v[162:165], v[224:227], v[72:75]
	v_mfma_f32_16x16x32_bf16 v[124:127], v[158:161], v[204:207], v[124:127]
	v_mfma_f32_16x16x32_bf16 v[120:123], v[166:169], v[204:207], v[120:123]
	v_mfma_f32_16x16x32_bf16 v[108:111], v[158:161], v[212:215], v[108:111]
	v_mfma_f32_16x16x32_bf16 v[104:107], v[166:169], v[212:215], v[104:107]
	v_mfma_f32_16x16x32_bf16 v[92:95], v[158:161], v[220:223], v[92:95]
	v_mfma_f32_16x16x32_bf16 v[88:91], v[166:169], v[220:223], v[88:91]
	v_mfma_f32_16x16x32_bf16 v[76:79], v[158:161], v[228:231], v[76:79]
	v_mfma_f32_16x16x32_bf16 v[72:75], v[166:169], v[228:231], v[72:75]
	s_setprio 0
	s_setprio 1
	v_mfma_f32_16x16x32_bf16 v[116:119], v[184:187], v[200:203], v[116:119]
	v_mfma_f32_16x16x32_bf16 v[112:115], v[192:195], v[200:203], v[112:115]
	v_mfma_f32_16x16x32_bf16 v[100:103], v[184:187], v[208:211], v[100:103]
	v_mfma_f32_16x16x32_bf16 v[96:99], v[192:195], v[208:211], v[96:99]
	v_mfma_f32_16x16x32_bf16 v[84:87], v[184:187], v[216:219], v[84:87]
	v_mfma_f32_16x16x32_bf16 v[80:83], v[192:195], v[216:219], v[80:83]
	v_mfma_f32_16x16x32_bf16 v[68:71], v[184:187], v[224:227], v[68:71]
	v_mfma_f32_16x16x32_bf16 v[64:67], v[192:195], v[224:227], v[64:67]
	v_mfma_f32_16x16x32_bf16 v[116:119], v[188:191], v[204:207], v[116:119]
	v_mfma_f32_16x16x32_bf16 v[112:115], v[196:199], v[204:207], v[112:115]
	v_mfma_f32_16x16x32_bf16 v[100:103], v[188:191], v[212:215], v[100:103]
	v_mfma_f32_16x16x32_bf16 v[96:99], v[196:199], v[212:215], v[96:99]
	v_mfma_f32_16x16x32_bf16 v[84:87], v[188:191], v[220:223], v[84:87]
	v_mfma_f32_16x16x32_bf16 v[80:83], v[196:199], v[220:223], v[80:83]
	v_mfma_f32_16x16x32_bf16 v[68:71], v[188:191], v[228:231], v[68:71]
	v_mfma_f32_16x16x32_bf16 v[64:67], v[196:199], v[228:231], v[64:67]
	s_barrier
	s_setprio 0
	s_add_i32 s10, s10, s66
	s_mov_b32 m0, s10
	ds_read_b128 v[200:203], v181 offset:49152
	ds_read_b128 v[204:207], v181 offset:50176
	ds_read_b128 v[208:211], v181 offset:51200
	global_load_lds_dwordx4 v138, s[60:61]
	s_add_i32 m0, s10, 0x2000
	ds_read_b128 v[212:215], v181 offset:52224
	global_load_lds_dwordx4 v142, s[60:61]
	s_add_u32 s60, s60, 0x40000
	s_addc_u32 s61, s61, 0
	s_add_i32 s10, s93, s66
	s_mov_b32 m0, s10
	ds_read_b128 v[216:219], v181 offset:53248
	global_load_lds_dwordx4 v138, s[60:61]
	s_add_i32 m0, s10, 0x2000
	ds_read_b128 v[220:223], v181 offset:54272
	global_load_lds_dwordx4 v142, s[60:61]
	s_mov_b32 m0, s73
	ds_read_b128 v[224:227], v181 offset:55296
	global_load_lds_dwordx4 v136, s[58:59]
	s_mov_b32 m0, s78
	ds_read_b128 v[228:231], v181 offset:56320
	global_load_lds_dwordx4 v140, s[58:59]
	s_waitcnt vmcnt(8)
	s_waitcnt lgkmcnt(0)
	s_setprio 1
	s_barrier
	v_mfma_f32_16x16x32_bf16 v[60:63], v[132:135], v[200:203], v[60:63]
	v_mfma_f32_16x16x32_bf16 v[56:59], v[162:165], v[200:203], v[56:59]
	v_mfma_f32_16x16x32_bf16 v[44:47], v[132:135], v[208:211], v[44:47]
	v_mfma_f32_16x16x32_bf16 v[40:43], v[162:165], v[208:211], v[40:43]
	v_mfma_f32_16x16x32_bf16 v[28:31], v[132:135], v[216:219], v[28:31]
	v_mfma_f32_16x16x32_bf16 v[24:27], v[162:165], v[216:219], v[24:27]
	v_mfma_f32_16x16x32_bf16 v[12:15], v[132:135], v[224:227], v[12:15]
	v_mfma_f32_16x16x32_bf16 v[8:11], v[162:165], v[224:227], v[8:11]
	v_mfma_f32_16x16x32_bf16 v[60:63], v[158:161], v[204:207], v[60:63]
	v_mfma_f32_16x16x32_bf16 v[56:59], v[166:169], v[204:207], v[56:59]
	v_mfma_f32_16x16x32_bf16 v[44:47], v[158:161], v[212:215], v[44:47]
	v_mfma_f32_16x16x32_bf16 v[40:43], v[166:169], v[212:215], v[40:43]
	v_mfma_f32_16x16x32_bf16 v[28:31], v[158:161], v[220:223], v[28:31]
	v_mfma_f32_16x16x32_bf16 v[24:27], v[166:169], v[220:223], v[24:27]
	v_mfma_f32_16x16x32_bf16 v[12:15], v[158:161], v[228:231], v[12:15]
	v_mfma_f32_16x16x32_bf16 v[8:11], v[166:169], v[228:231], v[8:11]
	s_setprio 0
	s_setprio 1
	v_mfma_f32_16x16x32_bf16 v[52:55], v[184:187], v[200:203], v[52:55]
	v_mfma_f32_16x16x32_bf16 v[48:51], v[192:195], v[200:203], v[48:51]
	v_mfma_f32_16x16x32_bf16 v[36:39], v[184:187], v[208:211], v[36:39]
	v_mfma_f32_16x16x32_bf16 v[32:35], v[192:195], v[208:211], v[32:35]
	v_mfma_f32_16x16x32_bf16 v[20:23], v[184:187], v[216:219], v[20:23]
	v_mfma_f32_16x16x32_bf16 v[16:19], v[192:195], v[216:219], v[16:19]
	v_mfma_f32_16x16x32_bf16 v[4:7], v[184:187], v[224:227], v[4:7]
	v_mfma_f32_16x16x32_bf16 v[0:3], v[192:195], v[224:227], v[0:3]
	v_mfma_f32_16x16x32_bf16 v[52:55], v[188:191], v[204:207], v[52:55]
	v_mfma_f32_16x16x32_bf16 v[48:51], v[196:199], v[204:207], v[48:51]
	v_mfma_f32_16x16x32_bf16 v[36:39], v[188:191], v[212:215], v[36:39]
	v_mfma_f32_16x16x32_bf16 v[32:35], v[196:199], v[212:215], v[32:35]
	v_mfma_f32_16x16x32_bf16 v[20:23], v[188:191], v[220:223], v[20:23]
	v_mfma_f32_16x16x32_bf16 v[16:19], v[196:199], v[220:223], v[16:19]
	v_mfma_f32_16x16x32_bf16 v[4:7], v[188:191], v[228:231], v[4:7]
	v_mfma_f32_16x16x32_bf16 v[0:3], v[196:199], v[228:231], v[0:3]
	s_barrier
	s_setprio 0
	s_add_i32 s10, s92, 2
	s_add_u32 s56, s56, 0x100
	s_addc_u32 s57, s57, 0
	s_cmp_gt_u32 s92, 13
	s_mov_b32 s92, s10
	s_cbranch_scc1 .LBB0_169
	s_branch .LBB0_163
.LBB0_162:
	ds_read_b128 v[132:135], v232
	ds_read_b128 v[158:161], v232 offset:1024
	ds_read_b128 v[162:165], v232 offset:2048
	ds_read_b128 v[166:169], v232 offset:3072
	ds_read_b128 v[184:187], v232 offset:16384
	ds_read_b128 v[188:191], v232 offset:17408
	ds_read_b128 v[192:195], v232 offset:18432
	ds_read_b128 v[196:199], v232 offset:19456
	s_add_i32 m0, s29, 0xc000
	ds_read_b128 v[200:203], v181
	ds_read_b128 v[204:207], v181 offset:1024
	ds_read_b128 v[208:211], v181 offset:2048
	ds_read_b128 v[212:215], v181 offset:3072
	ds_read_b128 v[216:219], v181 offset:4096
	ds_read_b128 v[220:223], v181 offset:5120
	ds_read_b128 v[224:227], v181 offset:6144
	global_load_lds_dwordx4 v150, s[100:101]
	s_add_i32 m0, s29, 0xe000
	ds_read_b128 v[228:231], v181 offset:7168
	global_load_lds_dwordx4 v152, s[100:101]
	s_waitcnt vmcnt(8)
	s_waitcnt lgkmcnt(0)
	s_setprio 1
	s_barrier
	v_mfma_f32_16x16x32_bf16 v[124:127], v[132:135], v[200:203], v[124:127]
	v_mfma_f32_16x16x32_bf16 v[120:123], v[162:165], v[200:203], v[120:123]
	v_mfma_f32_16x16x32_bf16 v[108:111], v[132:135], v[208:211], v[108:111]
	v_mfma_f32_16x16x32_bf16 v[104:107], v[162:165], v[208:211], v[104:107]
	v_mfma_f32_16x16x32_bf16 v[92:95], v[132:135], v[216:219], v[92:95]
	v_mfma_f32_16x16x32_bf16 v[88:91], v[162:165], v[216:219], v[88:91]
	v_mfma_f32_16x16x32_bf16 v[76:79], v[132:135], v[224:227], v[76:79]
	v_mfma_f32_16x16x32_bf16 v[72:75], v[162:165], v[224:227], v[72:75]
	v_mfma_f32_16x16x32_bf16 v[124:127], v[158:161], v[204:207], v[124:127]
	v_mfma_f32_16x16x32_bf16 v[120:123], v[166:169], v[204:207], v[120:123]
	v_mfma_f32_16x16x32_bf16 v[108:111], v[158:161], v[212:215], v[108:111]
	v_mfma_f32_16x16x32_bf16 v[104:107], v[166:169], v[212:215], v[104:107]
	v_mfma_f32_16x16x32_bf16 v[92:95], v[158:161], v[220:223], v[92:95]
	v_mfma_f32_16x16x32_bf16 v[88:91], v[166:169], v[220:223], v[88:91]
	v_mfma_f32_16x16x32_bf16 v[76:79], v[158:161], v[228:231], v[76:79]
	v_mfma_f32_16x16x32_bf16 v[72:75], v[166:169], v[228:231], v[72:75]
	s_setprio 0
	s_setprio 1
	v_mfma_f32_16x16x32_bf16 v[116:119], v[184:187], v[200:203], v[116:119]
	v_mfma_f32_16x16x32_bf16 v[112:115], v[192:195], v[200:203], v[112:115]
	v_mfma_f32_16x16x32_bf16 v[100:103], v[184:187], v[208:211], v[100:103]
	v_mfma_f32_16x16x32_bf16 v[96:99], v[192:195], v[208:211], v[96:99]
	v_mfma_f32_16x16x32_bf16 v[84:87], v[184:187], v[216:219], v[84:87]
	v_mfma_f32_16x16x32_bf16 v[80:83], v[192:195], v[216:219], v[80:83]
	v_mfma_f32_16x16x32_bf16 v[68:71], v[184:187], v[224:227], v[68:71]
	v_mfma_f32_16x16x32_bf16 v[64:67], v[192:195], v[224:227], v[64:67]
	v_mfma_f32_16x16x32_bf16 v[116:119], v[188:191], v[204:207], v[116:119]
	v_mfma_f32_16x16x32_bf16 v[112:115], v[196:199], v[204:207], v[112:115]
	v_mfma_f32_16x16x32_bf16 v[100:103], v[188:191], v[212:215], v[100:103]
	v_mfma_f32_16x16x32_bf16 v[96:99], v[196:199], v[212:215], v[96:99]
	v_mfma_f32_16x16x32_bf16 v[84:87], v[188:191], v[220:223], v[84:87]
	v_mfma_f32_16x16x32_bf16 v[80:83], v[196:199], v[220:223], v[80:83]
	v_mfma_f32_16x16x32_bf16 v[68:71], v[188:191], v[228:231], v[68:71]
	v_mfma_f32_16x16x32_bf16 v[64:67], v[196:199], v[228:231], v[64:67]
	s_barrier
	s_setprio 0
	s_add_i32 s10, s82, s66
	s_mov_b32 m0, s10
	ds_read_b128 v[200:203], v181 offset:16384
	ds_read_b128 v[204:207], v181 offset:17408
	ds_read_b128 v[208:211], v181 offset:18432
	global_load_lds_dwordx4 v138, s[62:63]
	s_add_i32 m0, s10, 0x2000
	ds_read_b128 v[212:215], v181 offset:19456
	global_load_lds_dwordx4 v142, s[62:63]
	s_add_u32 s62, s62, 0x40000
	s_addc_u32 s63, s63, 0
	s_add_i32 s10, s83, s66
	s_mov_b32 m0, s10
	ds_read_b128 v[216:219], v181 offset:20480
	global_load_lds_dwordx4 v138, s[62:63]
	s_add_i32 m0, s10, 0x2000
	ds_read_b128 v[220:223], v181 offset:21504
	global_load_lds_dwordx4 v142, s[62:63]
	s_mov_b32 m0, s29
	ds_read_b128 v[224:227], v181 offset:22528
	global_load_lds_dwordx4 v136, s[64:65]
	s_mov_b32 m0, s31
	ds_read_b128 v[228:231], v181 offset:23552
	global_load_lds_dwordx4 v140, s[64:65]
	s_waitcnt vmcnt(8)
	s_waitcnt lgkmcnt(0)
	s_setprio 1
	s_barrier
	v_mfma_f32_16x16x32_bf16 v[60:63], v[132:135], v[200:203], v[60:63]
	v_mfma_f32_16x16x32_bf16 v[56:59], v[162:165], v[200:203], v[56:59]
	v_mfma_f32_16x16x32_bf16 v[44:47], v[132:135], v[208:211], v[44:47]
	v_mfma_f32_16x16x32_bf16 v[40:43], v[162:165], v[208:211], v[40:43]
	v_mfma_f32_16x16x32_bf16 v[28:31], v[132:135], v[216:219], v[28:31]
	v_mfma_f32_16x16x32_bf16 v[24:27], v[162:165], v[216:219], v[24:27]
	v_mfma_f32_16x16x32_bf16 v[12:15], v[132:135], v[224:227], v[12:15]
	v_mfma_f32_16x16x32_bf16 v[8:11], v[162:165], v[224:227], v[8:11]
	v_mfma_f32_16x16x32_bf16 v[60:63], v[158:161], v[204:207], v[60:63]
	v_mfma_f32_16x16x32_bf16 v[56:59], v[166:169], v[204:207], v[56:59]
	v_mfma_f32_16x16x32_bf16 v[44:47], v[158:161], v[212:215], v[44:47]
	v_mfma_f32_16x16x32_bf16 v[40:43], v[166:169], v[212:215], v[40:43]
	v_mfma_f32_16x16x32_bf16 v[28:31], v[158:161], v[220:223], v[28:31]
	v_mfma_f32_16x16x32_bf16 v[24:27], v[166:169], v[220:223], v[24:27]
	v_mfma_f32_16x16x32_bf16 v[12:15], v[158:161], v[228:231], v[12:15]
	v_mfma_f32_16x16x32_bf16 v[8:11], v[166:169], v[228:231], v[8:11]
	s_setprio 0
	s_setprio 1
	v_mfma_f32_16x16x32_bf16 v[52:55], v[184:187], v[200:203], v[52:55]
	v_mfma_f32_16x16x32_bf16 v[48:51], v[192:195], v[200:203], v[48:51]
	v_mfma_f32_16x16x32_bf16 v[36:39], v[184:187], v[208:211], v[36:39]
	v_mfma_f32_16x16x32_bf16 v[32:35], v[192:195], v[208:211], v[32:35]
	v_mfma_f32_16x16x32_bf16 v[20:23], v[184:187], v[216:219], v[20:23]
	v_mfma_f32_16x16x32_bf16 v[16:19], v[192:195], v[216:219], v[16:19]
	v_mfma_f32_16x16x32_bf16 v[4:7], v[184:187], v[224:227], v[4:7]
	v_mfma_f32_16x16x32_bf16 v[0:3], v[192:195], v[224:227], v[0:3]
	v_mfma_f32_16x16x32_bf16 v[52:55], v[188:191], v[204:207], v[52:55]
	v_mfma_f32_16x16x32_bf16 v[48:51], v[196:199], v[204:207], v[48:51]
	v_mfma_f32_16x16x32_bf16 v[36:39], v[188:191], v[212:215], v[36:39]
	v_mfma_f32_16x16x32_bf16 v[32:35], v[196:199], v[212:215], v[32:35]
	v_mfma_f32_16x16x32_bf16 v[20:23], v[188:191], v[220:223], v[20:23]
	v_mfma_f32_16x16x32_bf16 v[16:19], v[196:199], v[220:223], v[16:19]
	v_mfma_f32_16x16x32_bf16 v[4:7], v[188:191], v[228:231], v[4:7]
	v_mfma_f32_16x16x32_bf16 v[0:3], v[196:199], v[228:231], v[0:3]
	s_barrier
	s_setprio 0
	s_add_i32 s10, 0, 0x18000
	s_add_i32 s93, 0, 0x1c000
	ds_read_b128 v[132:135], v232 offset:32768
	ds_read_b128 v[158:161], v232 offset:33792
	ds_read_b128 v[162:165], v232 offset:34816
	ds_read_b128 v[166:169], v232 offset:35840
	ds_read_b128 v[184:187], v232 offset:49152
	ds_read_b128 v[188:191], v232 offset:50176
	ds_read_b128 v[192:195], v232 offset:51200
	ds_read_b128 v[196:199], v232 offset:52224
	s_add_u32 s62, s64, 0x40000
	s_addc_u32 s63, s65, 0
	s_mov_b32 m0, s67
	ds_read_b128 v[200:203], v181 offset:32768
	ds_read_b128 v[204:207], v181 offset:33792
	ds_read_b128 v[208:211], v181 offset:34816
	ds_read_b128 v[212:215], v181 offset:35840
	ds_read_b128 v[216:219], v181 offset:36864
	ds_read_b128 v[220:223], v181 offset:37888
	ds_read_b128 v[224:227], v181 offset:38912
	global_load_lds_dwordx4 v136, s[62:63]
	s_mov_b32 m0, s68
	ds_read_b128 v[228:231], v181 offset:39936
	global_load_lds_dwordx4 v140, s[62:63]
	s_waitcnt vmcnt(8)
	s_waitcnt lgkmcnt(0)
	s_setprio 1
	s_barrier
	v_mfma_f32_16x16x32_bf16 v[124:127], v[132:135], v[200:203], v[124:127]
	v_mfma_f32_16x16x32_bf16 v[120:123], v[162:165], v[200:203], v[120:123]
	v_mfma_f32_16x16x32_bf16 v[108:111], v[132:135], v[208:211], v[108:111]
	v_mfma_f32_16x16x32_bf16 v[104:107], v[162:165], v[208:211], v[104:107]
	v_mfma_f32_16x16x32_bf16 v[92:95], v[132:135], v[216:219], v[92:95]
	v_mfma_f32_16x16x32_bf16 v[88:91], v[162:165], v[216:219], v[88:91]
	v_mfma_f32_16x16x32_bf16 v[76:79], v[132:135], v[224:227], v[76:79]
	v_mfma_f32_16x16x32_bf16 v[72:75], v[162:165], v[224:227], v[72:75]
	v_mfma_f32_16x16x32_bf16 v[124:127], v[158:161], v[204:207], v[124:127]
	v_mfma_f32_16x16x32_bf16 v[120:123], v[166:169], v[204:207], v[120:123]
	v_mfma_f32_16x16x32_bf16 v[108:111], v[158:161], v[212:215], v[108:111]
	v_mfma_f32_16x16x32_bf16 v[104:107], v[166:169], v[212:215], v[104:107]
	v_mfma_f32_16x16x32_bf16 v[92:95], v[158:161], v[220:223], v[92:95]
	v_mfma_f32_16x16x32_bf16 v[88:91], v[166:169], v[220:223], v[88:91]
	v_mfma_f32_16x16x32_bf16 v[76:79], v[158:161], v[228:231], v[76:79]
	v_mfma_f32_16x16x32_bf16 v[72:75], v[166:169], v[228:231], v[72:75]
	s_setprio 0
	s_setprio 1
	v_mfma_f32_16x16x32_bf16 v[116:119], v[184:187], v[200:203], v[116:119]
	v_mfma_f32_16x16x32_bf16 v[112:115], v[192:195], v[200:203], v[112:115]
	v_mfma_f32_16x16x32_bf16 v[100:103], v[184:187], v[208:211], v[100:103]
	v_mfma_f32_16x16x32_bf16 v[96:99], v[192:195], v[208:211], v[96:99]
	v_mfma_f32_16x16x32_bf16 v[84:87], v[184:187], v[216:219], v[84:87]
	v_mfma_f32_16x16x32_bf16 v[80:83], v[192:195], v[216:219], v[80:83]
	v_mfma_f32_16x16x32_bf16 v[68:71], v[184:187], v[224:227], v[68:71]
	v_mfma_f32_16x16x32_bf16 v[64:67], v[192:195], v[224:227], v[64:67]
	v_mfma_f32_16x16x32_bf16 v[116:119], v[188:191], v[204:207], v[116:119]
	v_mfma_f32_16x16x32_bf16 v[112:115], v[196:199], v[204:207], v[112:115]
	v_mfma_f32_16x16x32_bf16 v[100:103], v[188:191], v[212:215], v[100:103]
	v_mfma_f32_16x16x32_bf16 v[96:99], v[196:199], v[212:215], v[96:99]
	v_mfma_f32_16x16x32_bf16 v[84:87], v[188:191], v[220:223], v[84:87]
	v_mfma_f32_16x16x32_bf16 v[80:83], v[196:199], v[220:223], v[80:83]
	v_mfma_f32_16x16x32_bf16 v[68:71], v[188:191], v[228:231], v[68:71]
	v_mfma_f32_16x16x32_bf16 v[64:67], v[196:199], v[228:231], v[64:67]
	s_barrier
	s_setprio 0
	s_add_i32 s10, s10, s66
	s_mov_b32 m0, s10
	ds_read_b128 v[200:203], v181 offset:49152
	ds_read_b128 v[204:207], v181 offset:50176
	ds_read_b128 v[208:211], v181 offset:51200
	global_load_lds_dwordx4 v138, s[60:61]
	s_add_i32 m0, s10, 0x2000
	ds_read_b128 v[212:215], v181 offset:52224
	global_load_lds_dwordx4 v142, s[60:61]
	s_add_u32 s60, s60, 0x40000
	s_addc_u32 s61, s61, 0
	s_add_i32 s10, s93, s66
	s_mov_b32 m0, s10
	ds_read_b128 v[216:219], v181 offset:53248
	global_load_lds_dwordx4 v138, s[60:61]
	s_add_i32 m0, s10, 0x2000
	ds_read_b128 v[220:223], v181 offset:54272
	global_load_lds_dwordx4 v142, s[60:61]
	s_mov_b32 m0, s73
	ds_read_b128 v[224:227], v181 offset:55296
	global_load_lds_dwordx4 v136, s[58:59]
	s_mov_b32 m0, s78
	ds_read_b128 v[228:231], v181 offset:56320
	global_load_lds_dwordx4 v140, s[58:59]
	s_waitcnt vmcnt(8)
	s_waitcnt lgkmcnt(0)
	s_setprio 1
	s_barrier
	v_mfma_f32_16x16x32_bf16 v[60:63], v[132:135], v[200:203], v[60:63]
	v_mfma_f32_16x16x32_bf16 v[56:59], v[162:165], v[200:203], v[56:59]
	v_mfma_f32_16x16x32_bf16 v[44:47], v[132:135], v[208:211], v[44:47]
	v_mfma_f32_16x16x32_bf16 v[40:43], v[162:165], v[208:211], v[40:43]
	v_mfma_f32_16x16x32_bf16 v[28:31], v[132:135], v[216:219], v[28:31]
	v_mfma_f32_16x16x32_bf16 v[24:27], v[162:165], v[216:219], v[24:27]
	v_mfma_f32_16x16x32_bf16 v[12:15], v[132:135], v[224:227], v[12:15]
	v_mfma_f32_16x16x32_bf16 v[8:11], v[162:165], v[224:227], v[8:11]
	v_mfma_f32_16x16x32_bf16 v[60:63], v[158:161], v[204:207], v[60:63]
	v_mfma_f32_16x16x32_bf16 v[56:59], v[166:169], v[204:207], v[56:59]
	v_mfma_f32_16x16x32_bf16 v[44:47], v[158:161], v[212:215], v[44:47]
	v_mfma_f32_16x16x32_bf16 v[40:43], v[166:169], v[212:215], v[40:43]
	v_mfma_f32_16x16x32_bf16 v[28:31], v[158:161], v[220:223], v[28:31]
	v_mfma_f32_16x16x32_bf16 v[24:27], v[166:169], v[220:223], v[24:27]
	v_mfma_f32_16x16x32_bf16 v[12:15], v[158:161], v[228:231], v[12:15]
	v_mfma_f32_16x16x32_bf16 v[8:11], v[166:169], v[228:231], v[8:11]
	s_setprio 0
	s_setprio 1
	v_mfma_f32_16x16x32_bf16 v[52:55], v[184:187], v[200:203], v[52:55]
	v_mfma_f32_16x16x32_bf16 v[48:51], v[192:195], v[200:203], v[48:51]
	v_mfma_f32_16x16x32_bf16 v[36:39], v[184:187], v[208:211], v[36:39]
	v_mfma_f32_16x16x32_bf16 v[32:35], v[192:195], v[208:211], v[32:35]
	v_mfma_f32_16x16x32_bf16 v[20:23], v[184:187], v[216:219], v[20:23]
	v_mfma_f32_16x16x32_bf16 v[16:19], v[192:195], v[216:219], v[16:19]
	v_mfma_f32_16x16x32_bf16 v[4:7], v[184:187], v[224:227], v[4:7]
	v_mfma_f32_16x16x32_bf16 v[0:3], v[192:195], v[224:227], v[0:3]
	v_mfma_f32_16x16x32_bf16 v[52:55], v[188:191], v[204:207], v[52:55]
	v_mfma_f32_16x16x32_bf16 v[48:51], v[196:199], v[204:207], v[48:51]
	v_mfma_f32_16x16x32_bf16 v[36:39], v[188:191], v[212:215], v[36:39]
	v_mfma_f32_16x16x32_bf16 v[32:35], v[196:199], v[212:215], v[32:35]
	v_mfma_f32_16x16x32_bf16 v[20:23], v[188:191], v[220:223], v[20:23]
	v_mfma_f32_16x16x32_bf16 v[16:19], v[196:199], v[220:223], v[16:19]
	v_mfma_f32_16x16x32_bf16 v[4:7], v[188:191], v[228:231], v[4:7]
	v_mfma_f32_16x16x32_bf16 v[0:3], v[196:199], v[228:231], v[0:3]
	s_barrier
	s_setprio 0
	s_add_i32 s10, s92, 2
	s_add_u32 s56, s56, 0x100
	s_addc_u32 s57, s57, 0
	s_cmp_gt_u32 s92, 13
	s_mov_b32 s92, s10
	s_cbranch_scc1 .LBB0_169

.LBB0_713:
	s_add_u32 s19, s63, s6
	s_addc_u32 s29, s64, s7
	s_add_u32 s31, s65, s8
	s_addc_u32 s79, s66, s9
	s_ashr_i32 s23, s22, 31
	s_lshl_b64 s[6:7], s[22:23], 19
	s_add_u32 s24, s34, s6
	s_addc_u32 s25, s35, s7
	s_and_b64 s[8:9], s[4:5], exec
	s_cselect_b32 s23, s25, s45
	s_cselect_b32 s80, s24, s44
	s_ashr_i32 s21, s20, 31
	s_lshl_b64 s[8:9], s[20:21], 19
	s_add_u32 s26, s42, s8
	s_addc_u32 s27, s43, s9
	s_and_b64 s[36:37], s[4:5], exec
	s_cselect_b32 s21, s27, s39
	s_cselect_b32 s81, s26, s38
	s_add_u32 s36, s80, 0x80
	s_addc_u32 s37, s23, 0
	s_add_u32 s46, s81, 0x80
	s_addc_u32 s47, s21, 0
	v_lshl_add_u64 v[128:129], s[44:45], 0, v[156:157]
	v_lshl_add_u64 v[130:131], s[44:45], 0, v[158:159]
	s_mov_b32 s82, 0
	s_mov_b64 s[48:49], 0
	v_add_u32_e32 v168, 0x10000, v171
	s_add_u32 s56, s44, s48
	s_addc_u32 s57, s45, s49
	s_mov_b64 s[100:101], s[56:57]
	s_add_u32 s84, s38, s48
	s_addc_u32 s83, s39, s49
	s_add_u32 s50, s56, 0x180
	s_addc_u32 s51, s57, 0
	s_add_u32 s52, s84, 0x180
	s_addc_u32 s53, s83, 0
	s_add_u32 s56, s56, 0x100
	s_addc_u32 s57, s57, 0
	s_add_u32 s54, s84, 0x100
	s_addc_u32 s55, s83, 0
	s_cmpk_eq_i32 s48, 0x700
	s_cselect_b32 s50, s36, s50
	s_cselect_b32 s51, s37, s51
	s_cselect_b32 s52, s46, s52
	s_cselect_b32 s53, s47, s53
	s_cselect_b32 s56, s80, s56
	s_cselect_b32 s57, s23, s57
	s_cselect_b32 s54, s81, s54
	s_cselect_b32 s55, s21, s55
	ds_read_b128 v[132:135], v168
	ds_read_b128 v[136:139], v168 offset:1024
	ds_read_b128 v[140:143], v168 offset:2048
	ds_read_b128 v[164:167], v168 offset:3072
	ds_read_b128 v[174:177], v168 offset:16384
	ds_read_b128 v[178:181], v168 offset:17408
	ds_read_b128 v[182:185], v168 offset:18432
	ds_read_b128 v[186:189], v168 offset:19456
	s_add_i32 m0, s59, 0xc000
	ds_read_b128 v[190:193], v172
	ds_read_b128 v[194:197], v172 offset:1024
	ds_read_b128 v[198:201], v172 offset:2048
	ds_read_b128 v[202:205], v172 offset:3072
	ds_read_b128 v[206:209], v172 offset:4096
	ds_read_b128 v[210:213], v172 offset:5120
	ds_read_b128 v[214:217], v172 offset:6144
	global_load_lds_dwordx4 v156, s[100:101]
	s_add_i32 m0, s59, 0xe000
	ds_read_b128 v[218:221], v172 offset:7168
	global_load_lds_dwordx4 v158, s[100:101]
	s_waitcnt vmcnt(8)
	s_waitcnt lgkmcnt(0)
	s_setprio 1
	s_barrier
	v_mfma_f32_16x16x32_bf16 v[124:127], v[132:135], v[190:193], 0
	v_mfma_f32_16x16x32_bf16 v[120:123], v[140:143], v[190:193], 0
	v_mfma_f32_16x16x32_bf16 v[108:111], v[132:135], v[198:201], 0
	v_mfma_f32_16x16x32_bf16 v[104:107], v[140:143], v[198:201], 0
	v_mfma_f32_16x16x32_bf16 v[92:95], v[132:135], v[206:209], 0
	v_mfma_f32_16x16x32_bf16 v[88:91], v[140:143], v[206:209], 0
	v_mfma_f32_16x16x32_bf16 v[76:79], v[132:135], v[214:217], 0
	v_mfma_f32_16x16x32_bf16 v[72:75], v[140:143], v[214:217], 0
	v_mfma_f32_16x16x32_bf16 v[124:127], v[136:139], v[194:197], v[124:127]
	v_mfma_f32_16x16x32_bf16 v[120:123], v[164:167], v[194:197], v[120:123]
	v_mfma_f32_16x16x32_bf16 v[108:111], v[136:139], v[202:205], v[108:111]
	v_mfma_f32_16x16x32_bf16 v[104:107], v[164:167], v[202:205], v[104:107]
	v_mfma_f32_16x16x32_bf16 v[92:95], v[136:139], v[210:213], v[92:95]
	v_mfma_f32_16x16x32_bf16 v[88:91], v[164:167], v[210:213], v[88:91]
	v_mfma_f32_16x16x32_bf16 v[76:79], v[136:139], v[218:221], v[76:79]
	v_mfma_f32_16x16x32_bf16 v[72:75], v[164:167], v[218:221], v[72:75]
	s_setprio 0
	s_setprio 1
	v_mfma_f32_16x16x32_bf16 v[116:119], v[174:177], v[190:193], 0
	v_mfma_f32_16x16x32_bf16 v[112:115], v[182:185], v[190:193], 0
	v_mfma_f32_16x16x32_bf16 v[100:103], v[174:177], v[198:201], 0
	v_mfma_f32_16x16x32_bf16 v[96:99], v[182:185], v[198:201], 0
	v_mfma_f32_16x16x32_bf16 v[84:87], v[174:177], v[206:209], 0
	v_mfma_f32_16x16x32_bf16 v[80:83], v[182:185], v[206:209], 0
	v_mfma_f32_16x16x32_bf16 v[68:71], v[174:177], v[214:217], 0
	v_mfma_f32_16x16x32_bf16 v[64:67], v[182:185], v[214:217], 0
	v_mfma_f32_16x16x32_bf16 v[116:119], v[178:181], v[194:197], v[116:119]
	v_mfma_f32_16x16x32_bf16 v[112:115], v[186:189], v[194:197], v[112:115]
	v_mfma_f32_16x16x32_bf16 v[100:103], v[178:181], v[202:205], v[100:103]
	v_mfma_f32_16x16x32_bf16 v[96:99], v[186:189], v[202:205], v[96:99]
	v_mfma_f32_16x16x32_bf16 v[84:87], v[178:181], v[210:213], v[84:87]
	v_mfma_f32_16x16x32_bf16 v[80:83], v[186:189], v[210:213], v[80:83]
	v_mfma_f32_16x16x32_bf16 v[68:71], v[178:181], v[218:221], v[68:71]
	v_mfma_f32_16x16x32_bf16 v[64:67], v[186:189], v[218:221], v[64:67]
	s_barrier
	s_setprio 0
	s_add_i32 s10, s72, s58
	s_mov_b32 m0, s10
	ds_read_b128 v[190:193], v172 offset:16384
	ds_read_b128 v[194:197], v172 offset:17408
	ds_read_b128 v[198:201], v172 offset:18432
	global_load_lds_dwordx4 v146, s[54:55]
	s_add_i32 m0, s10, 0x2000
	ds_read_b128 v[202:205], v172 offset:19456
	global_load_lds_dwordx4 v150, s[54:55]
	s_add_u32 s54, s54, 0x40000
	s_addc_u32 s55, s55, 0
	s_add_i32 s10, s73, s58
	s_mov_b32 m0, s10
	ds_read_b128 v[206:209], v172 offset:20480
	global_load_lds_dwordx4 v146, s[54:55]
	s_add_i32 m0, s10, 0x2000
	ds_read_b128 v[210:213], v172 offset:21504
	global_load_lds_dwordx4 v150, s[54:55]
	s_mov_b32 m0, s59
	ds_read_b128 v[214:217], v172 offset:22528
	global_load_lds_dwordx4 v144, s[56:57]
	s_mov_b32 m0, s60
	ds_read_b128 v[218:221], v172 offset:23552
	global_load_lds_dwordx4 v148, s[56:57]
	s_waitcnt vmcnt(8)
	s_waitcnt lgkmcnt(0)
	s_setprio 1
	s_barrier
	v_mfma_f32_16x16x32_bf16 v[60:63], v[132:135], v[190:193], 0
	v_mfma_f32_16x16x32_bf16 v[56:59], v[140:143], v[190:193], 0
	v_mfma_f32_16x16x32_bf16 v[44:47], v[132:135], v[198:201], 0
	v_mfma_f32_16x16x32_bf16 v[40:43], v[140:143], v[198:201], 0
	v_mfma_f32_16x16x32_bf16 v[28:31], v[132:135], v[206:209], 0
	v_mfma_f32_16x16x32_bf16 v[24:27], v[140:143], v[206:209], 0
	v_mfma_f32_16x16x32_bf16 v[12:15], v[132:135], v[214:217], 0
	v_mfma_f32_16x16x32_bf16 v[8:11], v[140:143], v[214:217], 0
	v_mfma_f32_16x16x32_bf16 v[60:63], v[136:139], v[194:197], v[60:63]
	v_mfma_f32_16x16x32_bf16 v[56:59], v[164:167], v[194:197], v[56:59]
	v_mfma_f32_16x16x32_bf16 v[44:47], v[136:139], v[202:205], v[44:47]
	v_mfma_f32_16x16x32_bf16 v[40:43], v[164:167], v[202:205], v[40:43]
	v_mfma_f32_16x16x32_bf16 v[28:31], v[136:139], v[210:213], v[28:31]
	v_mfma_f32_16x16x32_bf16 v[24:27], v[164:167], v[210:213], v[24:27]
	v_mfma_f32_16x16x32_bf16 v[12:15], v[136:139], v[218:221], v[12:15]
	v_mfma_f32_16x16x32_bf16 v[8:11], v[164:167], v[218:221], v[8:11]
	s_setprio 0
	s_setprio 1
	v_mfma_f32_16x16x32_bf16 v[52:55], v[174:177], v[190:193], 0
	v_mfma_f32_16x16x32_bf16 v[48:51], v[182:185], v[190:193], 0
	v_mfma_f32_16x16x32_bf16 v[36:39], v[174:177], v[198:201], 0
	v_mfma_f32_16x16x32_bf16 v[32:35], v[182:185], v[198:201], 0
	v_mfma_f32_16x16x32_bf16 v[20:23], v[174:177], v[206:209], 0
	v_mfma_f32_16x16x32_bf16 v[16:19], v[182:185], v[206:209], 0
	v_mfma_f32_16x16x32_bf16 v[4:7], v[174:177], v[214:217], 0
	v_mfma_f32_16x16x32_bf16 v[0:3], v[182:185], v[214:217], 0
	v_mfma_f32_16x16x32_bf16 v[52:55], v[178:181], v[194:197], v[52:55]
	v_mfma_f32_16x16x32_bf16 v[48:51], v[186:189], v[194:197], v[48:51]
	v_mfma_f32_16x16x32_bf16 v[36:39], v[178:181], v[202:205], v[36:39]
	v_mfma_f32_16x16x32_bf16 v[32:35], v[186:189], v[202:205], v[32:35]
	v_mfma_f32_16x16x32_bf16 v[20:23], v[178:181], v[210:213], v[20:23]
	v_mfma_f32_16x16x32_bf16 v[16:19], v[186:189], v[210:213], v[16:19]
	v_mfma_f32_16x16x32_bf16 v[4:7], v[178:181], v[218:221], v[4:7]
	v_mfma_f32_16x16x32_bf16 v[0:3], v[186:189], v[218:221], v[0:3]
	s_barrier
	s_setprio 0
	s_add_i32 s10, 0, 0x18000
	s_add_i32 s83, 0, 0x1c000
	ds_read_b128 v[132:135], v168 offset:32768
	ds_read_b128 v[136:139], v168 offset:33792
	ds_read_b128 v[140:143], v168 offset:34816
	ds_read_b128 v[164:167], v168 offset:35840
	ds_read_b128 v[174:177], v168 offset:49152
	ds_read_b128 v[178:181], v168 offset:50176
	ds_read_b128 v[182:185], v168 offset:51200
	ds_read_b128 v[186:189], v168 offset:52224
	s_add_u32 s54, s56, 0x40000
	s_addc_u32 s55, s57, 0
	s_mov_b32 m0, s61
	ds_read_b128 v[190:193], v172 offset:32768
	ds_read_b128 v[194:197], v172 offset:33792
	ds_read_b128 v[198:201], v172 offset:34816
	ds_read_b128 v[202:205], v172 offset:35840
	ds_read_b128 v[206:209], v172 offset:36864
	ds_read_b128 v[210:213], v172 offset:37888
	ds_read_b128 v[214:217], v172 offset:38912
	global_load_lds_dwordx4 v144, s[54:55]
	s_mov_b32 m0, s62
	ds_read_b128 v[218:221], v172 offset:39936
	global_load_lds_dwordx4 v148, s[54:55]
	s_waitcnt vmcnt(8)
	s_waitcnt lgkmcnt(0)
	s_setprio 1
	s_barrier
	v_mfma_f32_16x16x32_bf16 v[124:127], v[132:135], v[190:193], v[124:127]
	v_mfma_f32_16x16x32_bf16 v[120:123], v[140:143], v[190:193], v[120:123]
	v_mfma_f32_16x16x32_bf16 v[108:111], v[132:135], v[198:201], v[108:111]
	v_mfma_f32_16x16x32_bf16 v[104:107], v[140:143], v[198:201], v[104:107]
	v_mfma_f32_16x16x32_bf16 v[92:95], v[132:135], v[206:209], v[92:95]
	v_mfma_f32_16x16x32_bf16 v[88:91], v[140:143], v[206:209], v[88:91]
	v_mfma_f32_16x16x32_bf16 v[76:79], v[132:135], v[214:217], v[76:79]
	v_mfma_f32_16x16x32_bf16 v[72:75], v[140:143], v[214:217], v[72:75]
	v_mfma_f32_16x16x32_bf16 v[124:127], v[136:139], v[194:197], v[124:127]
	v_mfma_f32_16x16x32_bf16 v[120:123], v[164:167], v[194:197], v[120:123]
	v_mfma_f32_16x16x32_bf16 v[108:111], v[136:139], v[202:205], v[108:111]
	v_mfma_f32_16x16x32_bf16 v[104:107], v[164:167], v[202:205], v[104:107]
	v_mfma_f32_16x16x32_bf16 v[92:95], v[136:139], v[210:213], v[92:95]
	v_mfma_f32_16x16x32_bf16 v[88:91], v[164:167], v[210:213], v[88:91]
	v_mfma_f32_16x16x32_bf16 v[76:79], v[136:139], v[218:221], v[76:79]
	v_mfma_f32_16x16x32_bf16 v[72:75], v[164:167], v[218:221], v[72:75]
	s_setprio 0
	s_setprio 1
	v_mfma_f32_16x16x32_bf16 v[116:119], v[174:177], v[190:193], v[116:119]
	v_mfma_f32_16x16x32_bf16 v[112:115], v[182:185], v[190:193], v[112:115]
	v_mfma_f32_16x16x32_bf16 v[100:103], v[174:177], v[198:201], v[100:103]
	v_mfma_f32_16x16x32_bf16 v[96:99], v[182:185], v[198:201], v[96:99]
	v_mfma_f32_16x16x32_bf16 v[84:87], v[174:177], v[206:209], v[84:87]
	v_mfma_f32_16x16x32_bf16 v[80:83], v[182:185], v[206:209], v[80:83]
	v_mfma_f32_16x16x32_bf16 v[68:71], v[174:177], v[214:217], v[68:71]
	v_mfma_f32_16x16x32_bf16 v[64:67], v[182:185], v[214:217], v[64:67]
	v_mfma_f32_16x16x32_bf16 v[116:119], v[178:181], v[194:197], v[116:119]
	v_mfma_f32_16x16x32_bf16 v[112:115], v[186:189], v[194:197], v[112:115]
	v_mfma_f32_16x16x32_bf16 v[100:103], v[178:181], v[202:205], v[100:103]
	v_mfma_f32_16x16x32_bf16 v[96:99], v[186:189], v[202:205], v[96:99]
	v_mfma_f32_16x16x32_bf16 v[84:87], v[178:181], v[210:213], v[84:87]
	v_mfma_f32_16x16x32_bf16 v[80:83], v[186:189], v[210:213], v[80:83]
	v_mfma_f32_16x16x32_bf16 v[68:71], v[178:181], v[218:221], v[68:71]
	v_mfma_f32_16x16x32_bf16 v[64:67], v[186:189], v[218:221], v[64:67]
	s_barrier
	s_setprio 0
	s_add_i32 s10, s10, s58
	s_mov_b32 m0, s10
	ds_read_b128 v[190:193], v172 offset:49152
	ds_read_b128 v[194:197], v172 offset:50176
	ds_read_b128 v[198:201], v172 offset:51200
	global_load_lds_dwordx4 v146, s[52:53]
	s_add_i32 m0, s10, 0x2000
	ds_read_b128 v[202:205], v172 offset:52224
	global_load_lds_dwordx4 v150, s[52:53]
	s_add_u32 s52, s52, 0x40000
	s_addc_u32 s53, s53, 0
	s_add_i32 s10, s83, s58
	s_mov_b32 m0, s10
	ds_read_b128 v[206:209], v172 offset:53248
	global_load_lds_dwordx4 v146, s[52:53]
	s_add_i32 m0, s10, 0x2000
	ds_read_b128 v[210:213], v172 offset:54272
	global_load_lds_dwordx4 v150, s[52:53]
	s_mov_b32 m0, s68
	ds_read_b128 v[214:217], v172 offset:55296
	global_load_lds_dwordx4 v144, s[50:51]
	s_mov_b32 m0, s69
	ds_read_b128 v[218:221], v172 offset:56320
	global_load_lds_dwordx4 v148, s[50:51]
	s_waitcnt vmcnt(8)
	s_waitcnt lgkmcnt(0)
	s_setprio 1
	s_barrier
	v_mfma_f32_16x16x32_bf16 v[60:63], v[132:135], v[190:193], v[60:63]
	v_mfma_f32_16x16x32_bf16 v[56:59], v[140:143], v[190:193], v[56:59]
	v_mfma_f32_16x16x32_bf16 v[44:47], v[132:135], v[198:201], v[44:47]
	v_mfma_f32_16x16x32_bf16 v[40:43], v[140:143], v[198:201], v[40:43]
	v_mfma_f32_16x16x32_bf16 v[28:31], v[132:135], v[206:209], v[28:31]
	v_mfma_f32_16x16x32_bf16 v[24:27], v[140:143], v[206:209], v[24:27]
	v_mfma_f32_16x16x32_bf16 v[12:15], v[132:135], v[214:217], v[12:15]
	v_mfma_f32_16x16x32_bf16 v[8:11], v[140:143], v[214:217], v[8:11]
	v_mfma_f32_16x16x32_bf16 v[60:63], v[136:139], v[194:197], v[60:63]
	v_mfma_f32_16x16x32_bf16 v[56:59], v[164:167], v[194:197], v[56:59]
	v_mfma_f32_16x16x32_bf16 v[44:47], v[136:139], v[202:205], v[44:47]
	v_mfma_f32_16x16x32_bf16 v[40:43], v[164:167], v[202:205], v[40:43]
	v_mfma_f32_16x16x32_bf16 v[28:31], v[136:139], v[210:213], v[28:31]
	v_mfma_f32_16x16x32_bf16 v[24:27], v[164:167], v[210:213], v[24:27]
	v_mfma_f32_16x16x32_bf16 v[12:15], v[136:139], v[218:221], v[12:15]
	v_mfma_f32_16x16x32_bf16 v[8:11], v[164:167], v[218:221], v[8:11]
	s_setprio 0
	s_setprio 1
	v_mfma_f32_16x16x32_bf16 v[52:55], v[174:177], v[190:193], v[52:55]
	v_mfma_f32_16x16x32_bf16 v[48:51], v[182:185], v[190:193], v[48:51]
	v_mfma_f32_16x16x32_bf16 v[36:39], v[174:177], v[198:201], v[36:39]
	v_mfma_f32_16x16x32_bf16 v[32:35], v[182:185], v[198:201], v[32:35]
	v_mfma_f32_16x16x32_bf16 v[20:23], v[174:177], v[206:209], v[20:23]
	v_mfma_f32_16x16x32_bf16 v[16:19], v[182:185], v[206:209], v[16:19]
	v_mfma_f32_16x16x32_bf16 v[4:7], v[174:177], v[214:217], v[4:7]
	v_mfma_f32_16x16x32_bf16 v[0:3], v[182:185], v[214:217], v[0:3]
	v_mfma_f32_16x16x32_bf16 v[52:55], v[178:181], v[194:197], v[52:55]
	v_mfma_f32_16x16x32_bf16 v[48:51], v[186:189], v[194:197], v[48:51]
	v_mfma_f32_16x16x32_bf16 v[36:39], v[178:181], v[202:205], v[36:39]
	v_mfma_f32_16x16x32_bf16 v[32:35], v[186:189], v[202:205], v[32:35]
	v_mfma_f32_16x16x32_bf16 v[20:23], v[178:181], v[210:213], v[20:23]
	v_mfma_f32_16x16x32_bf16 v[16:19], v[186:189], v[210:213], v[16:19]
	v_mfma_f32_16x16x32_bf16 v[4:7], v[178:181], v[218:221], v[4:7]
	v_mfma_f32_16x16x32_bf16 v[0:3], v[186:189], v[218:221], v[0:3]
	s_barrier
	s_setprio 0
	s_add_i32 s10, s82, 2
	s_add_u32 s48, s48, 0x100
	s_addc_u32 s49, s49, 0
	s_cmp_gt_u32 s82, 13
	s_mov_b32 s82, s10
	s_cbranch_scc1 .LBB0_721
	s_branch .LBB0_715
.LBB0_714:
	ds_read_b128 v[132:135], v168
	ds_read_b128 v[136:139], v168 offset:1024
	ds_read_b128 v[140:143], v168 offset:2048
	ds_read_b128 v[164:167], v168 offset:3072
	ds_read_b128 v[174:177], v168 offset:16384
	ds_read_b128 v[178:181], v168 offset:17408
	ds_read_b128 v[182:185], v168 offset:18432
	ds_read_b128 v[186:189], v168 offset:19456
	s_add_i32 m0, s59, 0xc000
	ds_read_b128 v[190:193], v172
	ds_read_b128 v[194:197], v172 offset:1024
	ds_read_b128 v[198:201], v172 offset:2048
	ds_read_b128 v[202:205], v172 offset:3072
	ds_read_b128 v[206:209], v172 offset:4096
	ds_read_b128 v[210:213], v172 offset:5120
	ds_read_b128 v[214:217], v172 offset:6144
	global_load_lds_dwordx4 v156, s[100:101]
	s_add_i32 m0, s59, 0xe000
	ds_read_b128 v[218:221], v172 offset:7168
	global_load_lds_dwordx4 v158, s[100:101]
	s_waitcnt vmcnt(8)
	s_waitcnt lgkmcnt(0)
	s_setprio 1
	s_barrier
	v_mfma_f32_16x16x32_bf16 v[124:127], v[132:135], v[190:193], v[124:127]
	v_mfma_f32_16x16x32_bf16 v[120:123], v[140:143], v[190:193], v[120:123]
	v_mfma_f32_16x16x32_bf16 v[108:111], v[132:135], v[198:201], v[108:111]
	v_mfma_f32_16x16x32_bf16 v[104:107], v[140:143], v[198:201], v[104:107]
	v_mfma_f32_16x16x32_bf16 v[92:95], v[132:135], v[206:209], v[92:95]
	v_mfma_f32_16x16x32_bf16 v[88:91], v[140:143], v[206:209], v[88:91]
	v_mfma_f32_16x16x32_bf16 v[76:79], v[132:135], v[214:217], v[76:79]
	v_mfma_f32_16x16x32_bf16 v[72:75], v[140:143], v[214:217], v[72:75]
	v_mfma_f32_16x16x32_bf16 v[124:127], v[136:139], v[194:197], v[124:127]
	v_mfma_f32_16x16x32_bf16 v[120:123], v[164:167], v[194:197], v[120:123]
	v_mfma_f32_16x16x32_bf16 v[108:111], v[136:139], v[202:205], v[108:111]
	v_mfma_f32_16x16x32_bf16 v[104:107], v[164:167], v[202:205], v[104:107]
	v_mfma_f32_16x16x32_bf16 v[92:95], v[136:139], v[210:213], v[92:95]
	v_mfma_f32_16x16x32_bf16 v[88:91], v[164:167], v[210:213], v[88:91]
	v_mfma_f32_16x16x32_bf16 v[76:79], v[136:139], v[218:221], v[76:79]
	v_mfma_f32_16x16x32_bf16 v[72:75], v[164:167], v[218:221], v[72:75]
	s_setprio 0
	s_setprio 1
	v_mfma_f32_16x16x32_bf16 v[116:119], v[174:177], v[190:193], v[116:119]
	v_mfma_f32_16x16x32_bf16 v[112:115], v[182:185], v[190:193], v[112:115]
	v_mfma_f32_16x16x32_bf16 v[100:103], v[174:177], v[198:201], v[100:103]
	v_mfma_f32_16x16x32_bf16 v[96:99], v[182:185], v[198:201], v[96:99]
	v_mfma_f32_16x16x32_bf16 v[84:87], v[174:177], v[206:209], v[84:87]
	v_mfma_f32_16x16x32_bf16 v[80:83], v[182:185], v[206:209], v[80:83]
	v_mfma_f32_16x16x32_bf16 v[68:71], v[174:177], v[214:217], v[68:71]
	v_mfma_f32_16x16x32_bf16 v[64:67], v[182:185], v[214:217], v[64:67]
	v_mfma_f32_16x16x32_bf16 v[116:119], v[178:181], v[194:197], v[116:119]
	v_mfma_f32_16x16x32_bf16 v[112:115], v[186:189], v[194:197], v[112:115]
	v_mfma_f32_16x16x32_bf16 v[100:103], v[178:181], v[202:205], v[100:103]
	v_mfma_f32_16x16x32_bf16 v[96:99], v[186:189], v[202:205], v[96:99]
	v_mfma_f32_16x16x32_bf16 v[84:87], v[178:181], v[210:213], v[84:87]
	v_mfma_f32_16x16x32_bf16 v[80:83], v[186:189], v[210:213], v[80:83]
	v_mfma_f32_16x16x32_bf16 v[68:71], v[178:181], v[218:221], v[68:71]
	v_mfma_f32_16x16x32_bf16 v[64:67], v[186:189], v[218:221], v[64:67]
	s_barrier
	s_setprio 0
	s_add_i32 s10, s72, s58
	s_mov_b32 m0, s10
	ds_read_b128 v[190:193], v172 offset:16384
	ds_read_b128 v[194:197], v172 offset:17408
	ds_read_b128 v[198:201], v172 offset:18432
	global_load_lds_dwordx4 v146, s[54:55]
	s_add_i32 m0, s10, 0x2000
	ds_read_b128 v[202:205], v172 offset:19456
	global_load_lds_dwordx4 v150, s[54:55]
	s_add_u32 s54, s54, 0x40000
	s_addc_u32 s55, s55, 0
	s_add_i32 s10, s73, s58
	s_mov_b32 m0, s10
	ds_read_b128 v[206:209], v172 offset:20480
	global_load_lds_dwordx4 v146, s[54:55]
	s_add_i32 m0, s10, 0x2000
	ds_read_b128 v[210:213], v172 offset:21504
	global_load_lds_dwordx4 v150, s[54:55]
	s_mov_b32 m0, s59
	ds_read_b128 v[214:217], v172 offset:22528
	global_load_lds_dwordx4 v144, s[56:57]
	s_mov_b32 m0, s60
	ds_read_b128 v[218:221], v172 offset:23552
	global_load_lds_dwordx4 v148, s[56:57]
	s_waitcnt vmcnt(8)
	s_waitcnt lgkmcnt(0)
	s_setprio 1
	s_barrier
	v_mfma_f32_16x16x32_bf16 v[60:63], v[132:135], v[190:193], v[60:63]
	v_mfma_f32_16x16x32_bf16 v[56:59], v[140:143], v[190:193], v[56:59]
	v_mfma_f32_16x16x32_bf16 v[44:47], v[132:135], v[198:201], v[44:47]
	v_mfma_f32_16x16x32_bf16 v[40:43], v[140:143], v[198:201], v[40:43]
	v_mfma_f32_16x16x32_bf16 v[28:31], v[132:135], v[206:209], v[28:31]
	v_mfma_f32_16x16x32_bf16 v[24:27], v[140:143], v[206:209], v[24:27]
	v_mfma_f32_16x16x32_bf16 v[12:15], v[132:135], v[214:217], v[12:15]
	v_mfma_f32_16x16x32_bf16 v[8:11], v[140:143], v[214:217], v[8:11]
	v_mfma_f32_16x16x32_bf16 v[60:63], v[136:139], v[194:197], v[60:63]
	v_mfma_f32_16x16x32_bf16 v[56:59], v[164:167], v[194:197], v[56:59]
	v_mfma_f32_16x16x32_bf16 v[44:47], v[136:139], v[202:205], v[44:47]
	v_mfma_f32_16x16x32_bf16 v[40:43], v[164:167], v[202:205], v[40:43]
	v_mfma_f32_16x16x32_bf16 v[28:31], v[136:139], v[210:213], v[28:31]
	v_mfma_f32_16x16x32_bf16 v[24:27], v[164:167], v[210:213], v[24:27]
	v_mfma_f32_16x16x32_bf16 v[12:15], v[136:139], v[218:221], v[12:15]
	v_mfma_f32_16x16x32_bf16 v[8:11], v[164:167], v[218:221], v[8:11]
	s_setprio 0
	s_setprio 1
	v_mfma_f32_16x16x32_bf16 v[52:55], v[174:177], v[190:193], v[52:55]
	v_mfma_f32_16x16x32_bf16 v[48:51], v[182:185], v[190:193], v[48:51]
	v_mfma_f32_16x16x32_bf16 v[36:39], v[174:177], v[198:201], v[36:39]
	v_mfma_f32_16x16x32_bf16 v[32:35], v[182:185], v[198:201], v[32:35]
	v_mfma_f32_16x16x32_bf16 v[20:23], v[174:177], v[206:209], v[20:23]
	v_mfma_f32_16x16x32_bf16 v[16:19], v[182:185], v[206:209], v[16:19]
	v_mfma_f32_16x16x32_bf16 v[4:7], v[174:177], v[214:217], v[4:7]
	v_mfma_f32_16x16x32_bf16 v[0:3], v[182:185], v[214:217], v[0:3]
	v_mfma_f32_16x16x32_bf16 v[52:55], v[178:181], v[194:197], v[52:55]
	v_mfma_f32_16x16x32_bf16 v[48:51], v[186:189], v[194:197], v[48:51]
	v_mfma_f32_16x16x32_bf16 v[36:39], v[178:181], v[202:205], v[36:39]
	v_mfma_f32_16x16x32_bf16 v[32:35], v[186:189], v[202:205], v[32:35]
	v_mfma_f32_16x16x32_bf16 v[20:23], v[178:181], v[210:213], v[20:23]
	v_mfma_f32_16x16x32_bf16 v[16:19], v[186:189], v[210:213], v[16:19]
	v_mfma_f32_16x16x32_bf16 v[4:7], v[178:181], v[218:221], v[4:7]
	v_mfma_f32_16x16x32_bf16 v[0:3], v[186:189], v[218:221], v[0:3]
	s_barrier
	s_setprio 0
	s_add_i32 s10, 0, 0x18000
	s_add_i32 s83, 0, 0x1c000
	ds_read_b128 v[132:135], v168 offset:32768
	ds_read_b128 v[136:139], v168 offset:33792
	ds_read_b128 v[140:143], v168 offset:34816
	ds_read_b128 v[164:167], v168 offset:35840
	ds_read_b128 v[174:177], v168 offset:49152
	ds_read_b128 v[178:181], v168 offset:50176
	ds_read_b128 v[182:185], v168 offset:51200
	ds_read_b128 v[186:189], v168 offset:52224
	s_add_u32 s54, s56, 0x40000
	s_addc_u32 s55, s57, 0
	s_mov_b32 m0, s61
	ds_read_b128 v[190:193], v172 offset:32768
	ds_read_b128 v[194:197], v172 offset:33792
	ds_read_b128 v[198:201], v172 offset:34816
	ds_read_b128 v[202:205], v172 offset:35840
	ds_read_b128 v[206:209], v172 offset:36864
	ds_read_b128 v[210:213], v172 offset:37888
	ds_read_b128 v[214:217], v172 offset:38912
	global_load_lds_dwordx4 v144, s[54:55]
	s_mov_b32 m0, s62
	ds_read_b128 v[218:221], v172 offset:39936
	global_load_lds_dwordx4 v148, s[54:55]
	s_waitcnt vmcnt(8)
	s_waitcnt lgkmcnt(0)
	s_setprio 1
	s_barrier
	v_mfma_f32_16x16x32_bf16 v[124:127], v[132:135], v[190:193], v[124:127]
	v_mfma_f32_16x16x32_bf16 v[120:123], v[140:143], v[190:193], v[120:123]
	v_mfma_f32_16x16x32_bf16 v[108:111], v[132:135], v[198:201], v[108:111]
	v_mfma_f32_16x16x32_bf16 v[104:107], v[140:143], v[198:201], v[104:107]
	v_mfma_f32_16x16x32_bf16 v[92:95], v[132:135], v[206:209], v[92:95]
	v_mfma_f32_16x16x32_bf16 v[88:91], v[140:143], v[206:209], v[88:91]
	v_mfma_f32_16x16x32_bf16 v[76:79], v[132:135], v[214:217], v[76:79]
	v_mfma_f32_16x16x32_bf16 v[72:75], v[140:143], v[214:217], v[72:75]
	v_mfma_f32_16x16x32_bf16 v[124:127], v[136:139], v[194:197], v[124:127]
	v_mfma_f32_16x16x32_bf16 v[120:123], v[164:167], v[194:197], v[120:123]
	v_mfma_f32_16x16x32_bf16 v[108:111], v[136:139], v[202:205], v[108:111]
	v_mfma_f32_16x16x32_bf16 v[104:107], v[164:167], v[202:205], v[104:107]
	v_mfma_f32_16x16x32_bf16 v[92:95], v[136:139], v[210:213], v[92:95]
	v_mfma_f32_16x16x32_bf16 v[88:91], v[164:167], v[210:213], v[88:91]
	v_mfma_f32_16x16x32_bf16 v[76:79], v[136:139], v[218:221], v[76:79]
	v_mfma_f32_16x16x32_bf16 v[72:75], v[164:167], v[218:221], v[72:75]
	s_setprio 0
	s_setprio 1
	v_mfma_f32_16x16x32_bf16 v[116:119], v[174:177], v[190:193], v[116:119]
	v_mfma_f32_16x16x32_bf16 v[112:115], v[182:185], v[190:193], v[112:115]
	v_mfma_f32_16x16x32_bf16 v[100:103], v[174:177], v[198:201], v[100:103]
	v_mfma_f32_16x16x32_bf16 v[96:99], v[182:185], v[198:201], v[96:99]
	v_mfma_f32_16x16x32_bf16 v[84:87], v[174:177], v[206:209], v[84:87]
	v_mfma_f32_16x16x32_bf16 v[80:83], v[182:185], v[206:209], v[80:83]
	v_mfma_f32_16x16x32_bf16 v[68:71], v[174:177], v[214:217], v[68:71]
	v_mfma_f32_16x16x32_bf16 v[64:67], v[182:185], v[214:217], v[64:67]
	v_mfma_f32_16x16x32_bf16 v[116:119], v[178:181], v[194:197], v[116:119]
	v_mfma_f32_16x16x32_bf16 v[112:115], v[186:189], v[194:197], v[112:115]
	v_mfma_f32_16x16x32_bf16 v[100:103], v[178:181], v[202:205], v[100:103]
	v_mfma_f32_16x16x32_bf16 v[96:99], v[186:189], v[202:205], v[96:99]
	v_mfma_f32_16x16x32_bf16 v[84:87], v[178:181], v[210:213], v[84:87]
	v_mfma_f32_16x16x32_bf16 v[80:83], v[186:189], v[210:213], v[80:83]
	v_mfma_f32_16x16x32_bf16 v[68:71], v[178:181], v[218:221], v[68:71]
	v_mfma_f32_16x16x32_bf16 v[64:67], v[186:189], v[218:221], v[64:67]
	s_barrier
	s_setprio 0
	s_add_i32 s10, s10, s58
	s_mov_b32 m0, s10
	ds_read_b128 v[190:193], v172 offset:49152
	ds_read_b128 v[194:197], v172 offset:50176
	ds_read_b128 v[198:201], v172 offset:51200
	global_load_lds_dwordx4 v146, s[52:53]
	s_add_i32 m0, s10, 0x2000
	ds_read_b128 v[202:205], v172 offset:52224
	global_load_lds_dwordx4 v150, s[52:53]
	s_add_u32 s52, s52, 0x40000
	s_addc_u32 s53, s53, 0
	s_add_i32 s10, s83, s58
	s_mov_b32 m0, s10
	ds_read_b128 v[206:209], v172 offset:53248
	global_load_lds_dwordx4 v146, s[52:53]
	s_add_i32 m0, s10, 0x2000
	ds_read_b128 v[210:213], v172 offset:54272
	global_load_lds_dwordx4 v150, s[52:53]
	s_mov_b32 m0, s68
	ds_read_b128 v[214:217], v172 offset:55296
	global_load_lds_dwordx4 v144, s[50:51]
	s_mov_b32 m0, s69
	ds_read_b128 v[218:221], v172 offset:56320
	global_load_lds_dwordx4 v148, s[50:51]
	s_waitcnt vmcnt(8)
	s_waitcnt lgkmcnt(0)
	s_setprio 1
	s_barrier
	v_mfma_f32_16x16x32_bf16 v[60:63], v[132:135], v[190:193], v[60:63]
	v_mfma_f32_16x16x32_bf16 v[56:59], v[140:143], v[190:193], v[56:59]
	v_mfma_f32_16x16x32_bf16 v[44:47], v[132:135], v[198:201], v[44:47]
	v_mfma_f32_16x16x32_bf16 v[40:43], v[140:143], v[198:201], v[40:43]
	v_mfma_f32_16x16x32_bf16 v[28:31], v[132:135], v[206:209], v[28:31]
	v_mfma_f32_16x16x32_bf16 v[24:27], v[140:143], v[206:209], v[24:27]
	v_mfma_f32_16x16x32_bf16 v[12:15], v[132:135], v[214:217], v[12:15]
	v_mfma_f32_16x16x32_bf16 v[8:11], v[140:143], v[214:217], v[8:11]
	v_mfma_f32_16x16x32_bf16 v[60:63], v[136:139], v[194:197], v[60:63]
	v_mfma_f32_16x16x32_bf16 v[56:59], v[164:167], v[194:197], v[56:59]
	v_mfma_f32_16x16x32_bf16 v[44:47], v[136:139], v[202:205], v[44:47]
	v_mfma_f32_16x16x32_bf16 v[40:43], v[164:167], v[202:205], v[40:43]
	v_mfma_f32_16x16x32_bf16 v[28:31], v[136:139], v[210:213], v[28:31]
	v_mfma_f32_16x16x32_bf16 v[24:27], v[164:167], v[210:213], v[24:27]
	v_mfma_f32_16x16x32_bf16 v[12:15], v[136:139], v[218:221], v[12:15]
	v_mfma_f32_16x16x32_bf16 v[8:11], v[164:167], v[218:221], v[8:11]
	s_setprio 0
	s_setprio 1
	v_mfma_f32_16x16x32_bf16 v[52:55], v[174:177], v[190:193], v[52:55]
	v_mfma_f32_16x16x32_bf16 v[48:51], v[182:185], v[190:193], v[48:51]
	v_mfma_f32_16x16x32_bf16 v[36:39], v[174:177], v[198:201], v[36:39]
	v_mfma_f32_16x16x32_bf16 v[32:35], v[182:185], v[198:201], v[32:35]
	v_mfma_f32_16x16x32_bf16 v[20:23], v[174:177], v[206:209], v[20:23]
	v_mfma_f32_16x16x32_bf16 v[16:19], v[182:185], v[206:209], v[16:19]
	v_mfma_f32_16x16x32_bf16 v[4:7], v[174:177], v[214:217], v[4:7]
	v_mfma_f32_16x16x32_bf16 v[0:3], v[182:185], v[214:217], v[0:3]
	v_mfma_f32_16x16x32_bf16 v[52:55], v[178:181], v[194:197], v[52:55]
	v_mfma_f32_16x16x32_bf16 v[48:51], v[186:189], v[194:197], v[48:51]
	v_mfma_f32_16x16x32_bf16 v[36:39], v[178:181], v[202:205], v[36:39]
	v_mfma_f32_16x16x32_bf16 v[32:35], v[186:189], v[202:205], v[32:35]
	v_mfma_f32_16x16x32_bf16 v[20:23], v[178:181], v[210:213], v[20:23]
	v_mfma_f32_16x16x32_bf16 v[16:19], v[186:189], v[210:213], v[16:19]
	v_mfma_f32_16x16x32_bf16 v[4:7], v[178:181], v[218:221], v[4:7]
	v_mfma_f32_16x16x32_bf16 v[0:3], v[186:189], v[218:221], v[0:3]
	s_barrier
	s_setprio 0
	s_add_i32 s10, s82, 2
	s_add_u32 s48, s48, 0x100
	s_addc_u32 s49, s49, 0
	s_cmp_gt_u32 s82, 13
	s_mov_b32 s82, s10
	s_cbranch_scc1 .LBB0_721

.LBB0_805:
	s_add_u32 s27, s61, s4
	s_addc_u32 s72, s62, s5
	s_add_u32 s73, s63, s6
	s_addc_u32 s78, s64, s7
	s_ashr_i32 s21, s20, 31
	s_lshl_b64 s[4:5], s[20:21], 19
	s_add_u32 s22, s40, s4
	s_addc_u32 s23, s41, s5
	s_and_b64 s[6:7], s[0:1], exec
	s_cselect_b32 s21, s23, s31
	s_cselect_b32 s79, s22, s30
	s_ashr_i32 s19, s18, 31
	s_lshl_b64 s[6:7], s[18:19], 19
	s_add_u32 s24, s42, s6
	s_addc_u32 s25, s43, s7
	s_and_b64 s[36:37], s[0:1], exec
	s_cselect_b32 s19, s25, s29
	s_cselect_b32 s80, s24, s28
	s_add_u32 s36, s79, 0x80
	s_addc_u32 s37, s21, 0
	s_add_u32 s38, s80, 0x80
	s_addc_u32 s39, s19, 0
	v_lshl_add_u64 v[148:149], s[30:31], 0, v[140:141]
	v_lshl_add_u64 v[150:151], s[30:31], 0, v[142:143]
	s_mov_b32 s81, 0
	s_mov_b64 s[44:45], 0
	v_add_u32_e32 v154, 0x10000, v157
	s_add_u32 s52, s30, s44
	s_addc_u32 s53, s31, s45
	s_mov_b64 s[100:101], s[52:53]
	s_add_u32 s83, s28, s44
	s_addc_u32 s82, s29, s45
	s_add_u32 s46, s52, 0x180
	s_addc_u32 s47, s53, 0
	s_add_u32 s48, s83, 0x180
	s_addc_u32 s49, s82, 0
	s_add_u32 s52, s52, 0x100
	s_addc_u32 s53, s53, 0
	s_add_u32 s50, s83, 0x100
	s_addc_u32 s51, s82, 0
	s_cmpk_eq_i32 s44, 0x700
	s_cselect_b32 s46, s36, s46
	s_cselect_b32 s47, s37, s47
	s_cselect_b32 s48, s38, s48
	s_cselect_b32 s49, s39, s49
	s_cselect_b32 s52, s79, s52
	s_cselect_b32 s53, s21, s53
	s_cselect_b32 s50, s80, s50
	s_cselect_b32 s51, s19, s51
	ds_read_b128 v[166:169], v154
	ds_read_b128 v[170:173], v154 offset:1024
	ds_read_b128 v[174:177], v154 offset:2048
	ds_read_b128 v[178:181], v154 offset:3072
	ds_read_b128 v[182:185], v154 offset:16384
	ds_read_b128 v[186:189], v154 offset:17408
	ds_read_b128 v[190:193], v154 offset:18432
	ds_read_b128 v[194:197], v154 offset:19456
	s_add_i32 m0, s57, 0xc000
	ds_read_b128 v[198:201], v161
	ds_read_b128 v[202:205], v161 offset:1024
	ds_read_b128 v[206:209], v161 offset:2048
	ds_read_b128 v[210:213], v161 offset:3072
	ds_read_b128 v[214:217], v161 offset:4096
	ds_read_b128 v[218:221], v161 offset:5120
	ds_read_b128 v[222:225], v161 offset:6144
	global_load_lds_dwordx4 v140, s[100:101]
	s_add_i32 m0, s57, 0xe000
	ds_read_b128 v[226:229], v161 offset:7168
	global_load_lds_dwordx4 v142, s[100:101]
	s_waitcnt vmcnt(8)
	s_waitcnt lgkmcnt(0)
	s_setprio 1
	s_barrier
	v_mfma_f32_16x16x32_bf16 v[124:127], v[166:169], v[198:201], 0
	v_mfma_f32_16x16x32_bf16 v[120:123], v[174:177], v[198:201], 0
	v_mfma_f32_16x16x32_bf16 v[108:111], v[166:169], v[206:209], 0
	v_mfma_f32_16x16x32_bf16 v[104:107], v[174:177], v[206:209], 0
	v_mfma_f32_16x16x32_bf16 v[92:95], v[166:169], v[214:217], 0
	v_mfma_f32_16x16x32_bf16 v[88:91], v[174:177], v[214:217], 0
	v_mfma_f32_16x16x32_bf16 v[76:79], v[166:169], v[222:225], 0
	v_mfma_f32_16x16x32_bf16 v[72:75], v[174:177], v[222:225], 0
	v_mfma_f32_16x16x32_bf16 v[124:127], v[170:173], v[202:205], v[124:127]
	v_mfma_f32_16x16x32_bf16 v[120:123], v[178:181], v[202:205], v[120:123]
	v_mfma_f32_16x16x32_bf16 v[108:111], v[170:173], v[210:213], v[108:111]
	v_mfma_f32_16x16x32_bf16 v[104:107], v[178:181], v[210:213], v[104:107]
	v_mfma_f32_16x16x32_bf16 v[92:95], v[170:173], v[218:221], v[92:95]
	v_mfma_f32_16x16x32_bf16 v[88:91], v[178:181], v[218:221], v[88:91]
	v_mfma_f32_16x16x32_bf16 v[76:79], v[170:173], v[226:229], v[76:79]
	v_mfma_f32_16x16x32_bf16 v[72:75], v[178:181], v[226:229], v[72:75]
	s_setprio 0
	s_setprio 1
	v_mfma_f32_16x16x32_bf16 v[116:119], v[182:185], v[198:201], 0
	v_mfma_f32_16x16x32_bf16 v[112:115], v[190:193], v[198:201], 0
	v_mfma_f32_16x16x32_bf16 v[100:103], v[182:185], v[206:209], 0
	v_mfma_f32_16x16x32_bf16 v[96:99], v[190:193], v[206:209], 0
	v_mfma_f32_16x16x32_bf16 v[84:87], v[182:185], v[214:217], 0
	v_mfma_f32_16x16x32_bf16 v[80:83], v[190:193], v[214:217], 0
	v_mfma_f32_16x16x32_bf16 v[68:71], v[182:185], v[222:225], 0
	v_mfma_f32_16x16x32_bf16 v[64:67], v[190:193], v[222:225], 0
	v_mfma_f32_16x16x32_bf16 v[116:119], v[186:189], v[202:205], v[116:119]
	v_mfma_f32_16x16x32_bf16 v[112:115], v[194:197], v[202:205], v[112:115]
	v_mfma_f32_16x16x32_bf16 v[100:103], v[186:189], v[210:213], v[100:103]
	v_mfma_f32_16x16x32_bf16 v[96:99], v[194:197], v[210:213], v[96:99]
	v_mfma_f32_16x16x32_bf16 v[84:87], v[186:189], v[218:221], v[84:87]
	v_mfma_f32_16x16x32_bf16 v[80:83], v[194:197], v[218:221], v[80:83]
	v_mfma_f32_16x16x32_bf16 v[68:71], v[186:189], v[226:229], v[68:71]
	v_mfma_f32_16x16x32_bf16 v[64:67], v[194:197], v[226:229], v[64:67]
	s_barrier
	s_setprio 0
	s_add_i32 s8, s68, s54
	s_mov_b32 m0, s8
	ds_read_b128 v[198:201], v161 offset:16384
	ds_read_b128 v[202:205], v161 offset:17408
	ds_read_b128 v[206:209], v161 offset:18432
	global_load_lds_dwordx4 v128, s[50:51]
	s_add_i32 m0, s8, 0x2000
	ds_read_b128 v[210:213], v161 offset:19456
	global_load_lds_dwordx4 v130, s[50:51]
	s_add_u32 s50, s50, 0x40000
	s_addc_u32 s51, s51, 0
	s_add_i32 s8, s69, s54
	s_mov_b32 m0, s8
	ds_read_b128 v[214:217], v161 offset:20480
	global_load_lds_dwordx4 v128, s[50:51]
	s_add_i32 m0, s8, 0x2000
	ds_read_b128 v[218:221], v161 offset:21504
	global_load_lds_dwordx4 v130, s[50:51]
	s_mov_b32 m0, s57
	ds_read_b128 v[222:225], v161 offset:22528
	global_load_lds_dwordx4 v134, s[52:53]
	s_mov_b32 m0, s58
	ds_read_b128 v[226:229], v161 offset:23552
	global_load_lds_dwordx4 v132, s[52:53]
	s_waitcnt vmcnt(8)
	s_waitcnt lgkmcnt(0)
	s_setprio 1
	s_barrier
	v_mfma_f32_16x16x32_bf16 v[60:63], v[166:169], v[198:201], 0
	v_mfma_f32_16x16x32_bf16 v[56:59], v[174:177], v[198:201], 0
	v_mfma_f32_16x16x32_bf16 v[44:47], v[166:169], v[206:209], 0
	v_mfma_f32_16x16x32_bf16 v[40:43], v[174:177], v[206:209], 0
	v_mfma_f32_16x16x32_bf16 v[28:31], v[166:169], v[214:217], 0
	v_mfma_f32_16x16x32_bf16 v[24:27], v[174:177], v[214:217], 0
	v_mfma_f32_16x16x32_bf16 v[12:15], v[166:169], v[222:225], 0
	v_mfma_f32_16x16x32_bf16 v[8:11], v[174:177], v[222:225], 0
	v_mfma_f32_16x16x32_bf16 v[60:63], v[170:173], v[202:205], v[60:63]
	v_mfma_f32_16x16x32_bf16 v[56:59], v[178:181], v[202:205], v[56:59]
	v_mfma_f32_16x16x32_bf16 v[44:47], v[170:173], v[210:213], v[44:47]
	v_mfma_f32_16x16x32_bf16 v[40:43], v[178:181], v[210:213], v[40:43]
	v_mfma_f32_16x16x32_bf16 v[28:31], v[170:173], v[218:221], v[28:31]
	v_mfma_f32_16x16x32_bf16 v[24:27], v[178:181], v[218:221], v[24:27]
	v_mfma_f32_16x16x32_bf16 v[12:15], v[170:173], v[226:229], v[12:15]
	v_mfma_f32_16x16x32_bf16 v[8:11], v[178:181], v[226:229], v[8:11]
	s_setprio 0
	s_setprio 1
	v_mfma_f32_16x16x32_bf16 v[52:55], v[182:185], v[198:201], 0
	v_mfma_f32_16x16x32_bf16 v[48:51], v[190:193], v[198:201], 0
	v_mfma_f32_16x16x32_bf16 v[36:39], v[182:185], v[206:209], 0
	v_mfma_f32_16x16x32_bf16 v[32:35], v[190:193], v[206:209], 0
	v_mfma_f32_16x16x32_bf16 v[20:23], v[182:185], v[214:217], 0
	v_mfma_f32_16x16x32_bf16 v[16:19], v[190:193], v[214:217], 0
	v_mfma_f32_16x16x32_bf16 v[4:7], v[182:185], v[222:225], 0
	v_mfma_f32_16x16x32_bf16 v[0:3], v[190:193], v[222:225], 0
	v_mfma_f32_16x16x32_bf16 v[52:55], v[186:189], v[202:205], v[52:55]
	v_mfma_f32_16x16x32_bf16 v[48:51], v[194:197], v[202:205], v[48:51]
	v_mfma_f32_16x16x32_bf16 v[36:39], v[186:189], v[210:213], v[36:39]
	v_mfma_f32_16x16x32_bf16 v[32:35], v[194:197], v[210:213], v[32:35]
	v_mfma_f32_16x16x32_bf16 v[20:23], v[186:189], v[218:221], v[20:23]
	v_mfma_f32_16x16x32_bf16 v[16:19], v[194:197], v[218:221], v[16:19]
	v_mfma_f32_16x16x32_bf16 v[4:7], v[186:189], v[226:229], v[4:7]
	v_mfma_f32_16x16x32_bf16 v[0:3], v[194:197], v[226:229], v[0:3]
	s_barrier
	s_setprio 0
	s_add_i32 s8, 0, 0x18000
	s_add_i32 s82, 0, 0x1c000
	ds_read_b128 v[166:169], v154 offset:32768
	ds_read_b128 v[170:173], v154 offset:33792
	ds_read_b128 v[174:177], v154 offset:34816
	ds_read_b128 v[178:181], v154 offset:35840
	ds_read_b128 v[182:185], v154 offset:49152
	ds_read_b128 v[186:189], v154 offset:50176
	ds_read_b128 v[190:193], v154 offset:51200
	ds_read_b128 v[194:197], v154 offset:52224
	s_add_u32 s50, s52, 0x40000
	s_addc_u32 s51, s53, 0
	s_mov_b32 m0, s59
	ds_read_b128 v[198:201], v161 offset:32768
	ds_read_b128 v[202:205], v161 offset:33792
	ds_read_b128 v[206:209], v161 offset:34816
	ds_read_b128 v[210:213], v161 offset:35840
	ds_read_b128 v[214:217], v161 offset:36864
	ds_read_b128 v[218:221], v161 offset:37888
	ds_read_b128 v[222:225], v161 offset:38912
	global_load_lds_dwordx4 v134, s[50:51]
	s_mov_b32 m0, s60
	ds_read_b128 v[226:229], v161 offset:39936
	global_load_lds_dwordx4 v132, s[50:51]
	s_waitcnt vmcnt(8)
	s_waitcnt lgkmcnt(0)
	s_setprio 1
	s_barrier
	v_mfma_f32_16x16x32_bf16 v[124:127], v[166:169], v[198:201], v[124:127]
	v_mfma_f32_16x16x32_bf16 v[120:123], v[174:177], v[198:201], v[120:123]
	v_mfma_f32_16x16x32_bf16 v[108:111], v[166:169], v[206:209], v[108:111]
	v_mfma_f32_16x16x32_bf16 v[104:107], v[174:177], v[206:209], v[104:107]
	v_mfma_f32_16x16x32_bf16 v[92:95], v[166:169], v[214:217], v[92:95]
	v_mfma_f32_16x16x32_bf16 v[88:91], v[174:177], v[214:217], v[88:91]
	v_mfma_f32_16x16x32_bf16 v[76:79], v[166:169], v[222:225], v[76:79]
	v_mfma_f32_16x16x32_bf16 v[72:75], v[174:177], v[222:225], v[72:75]
	v_mfma_f32_16x16x32_bf16 v[124:127], v[170:173], v[202:205], v[124:127]
	v_mfma_f32_16x16x32_bf16 v[120:123], v[178:181], v[202:205], v[120:123]
	v_mfma_f32_16x16x32_bf16 v[108:111], v[170:173], v[210:213], v[108:111]
	v_mfma_f32_16x16x32_bf16 v[104:107], v[178:181], v[210:213], v[104:107]
	v_mfma_f32_16x16x32_bf16 v[92:95], v[170:173], v[218:221], v[92:95]
	v_mfma_f32_16x16x32_bf16 v[88:91], v[178:181], v[218:221], v[88:91]
	v_mfma_f32_16x16x32_bf16 v[76:79], v[170:173], v[226:229], v[76:79]
	v_mfma_f32_16x16x32_bf16 v[72:75], v[178:181], v[226:229], v[72:75]
	s_setprio 0
	s_setprio 1
	v_mfma_f32_16x16x32_bf16 v[116:119], v[182:185], v[198:201], v[116:119]
	v_mfma_f32_16x16x32_bf16 v[112:115], v[190:193], v[198:201], v[112:115]
	v_mfma_f32_16x16x32_bf16 v[100:103], v[182:185], v[206:209], v[100:103]
	v_mfma_f32_16x16x32_bf16 v[96:99], v[190:193], v[206:209], v[96:99]
	v_mfma_f32_16x16x32_bf16 v[84:87], v[182:185], v[214:217], v[84:87]
	v_mfma_f32_16x16x32_bf16 v[80:83], v[190:193], v[214:217], v[80:83]
	v_mfma_f32_16x16x32_bf16 v[68:71], v[182:185], v[222:225], v[68:71]
	v_mfma_f32_16x16x32_bf16 v[64:67], v[190:193], v[222:225], v[64:67]
	v_mfma_f32_16x16x32_bf16 v[116:119], v[186:189], v[202:205], v[116:119]
	v_mfma_f32_16x16x32_bf16 v[112:115], v[194:197], v[202:205], v[112:115]
	v_mfma_f32_16x16x32_bf16 v[100:103], v[186:189], v[210:213], v[100:103]
	v_mfma_f32_16x16x32_bf16 v[96:99], v[194:197], v[210:213], v[96:99]
	v_mfma_f32_16x16x32_bf16 v[84:87], v[186:189], v[218:221], v[84:87]
	v_mfma_f32_16x16x32_bf16 v[80:83], v[194:197], v[218:221], v[80:83]
	v_mfma_f32_16x16x32_bf16 v[68:71], v[186:189], v[226:229], v[68:71]
	v_mfma_f32_16x16x32_bf16 v[64:67], v[194:197], v[226:229], v[64:67]
	s_barrier
	s_setprio 0
	s_add_i32 s8, s8, s54
	s_mov_b32 m0, s8
	ds_read_b128 v[198:201], v161 offset:49152
	ds_read_b128 v[202:205], v161 offset:50176
	ds_read_b128 v[206:209], v161 offset:51200
	global_load_lds_dwordx4 v128, s[48:49]
	s_add_i32 m0, s8, 0x2000
	ds_read_b128 v[210:213], v161 offset:52224
	global_load_lds_dwordx4 v130, s[48:49]
	s_add_u32 s48, s48, 0x40000
	s_addc_u32 s49, s49, 0
	s_add_i32 s8, s82, s54
	s_mov_b32 m0, s8
	ds_read_b128 v[214:217], v161 offset:53248
	global_load_lds_dwordx4 v128, s[48:49]
	s_add_i32 m0, s8, 0x2000
	ds_read_b128 v[218:221], v161 offset:54272
	global_load_lds_dwordx4 v130, s[48:49]
	s_mov_b32 m0, s65
	ds_read_b128 v[222:225], v161 offset:55296
	global_load_lds_dwordx4 v134, s[46:47]
	s_mov_b32 m0, s66
	ds_read_b128 v[226:229], v161 offset:56320
	global_load_lds_dwordx4 v132, s[46:47]
	s_waitcnt vmcnt(8)
	s_waitcnt lgkmcnt(0)
	s_setprio 1
	s_barrier
	v_mfma_f32_16x16x32_bf16 v[60:63], v[166:169], v[198:201], v[60:63]
	v_mfma_f32_16x16x32_bf16 v[56:59], v[174:177], v[198:201], v[56:59]
	v_mfma_f32_16x16x32_bf16 v[44:47], v[166:169], v[206:209], v[44:47]
	v_mfma_f32_16x16x32_bf16 v[40:43], v[174:177], v[206:209], v[40:43]
	v_mfma_f32_16x16x32_bf16 v[28:31], v[166:169], v[214:217], v[28:31]
	v_mfma_f32_16x16x32_bf16 v[24:27], v[174:177], v[214:217], v[24:27]
	v_mfma_f32_16x16x32_bf16 v[12:15], v[166:169], v[222:225], v[12:15]
	v_mfma_f32_16x16x32_bf16 v[8:11], v[174:177], v[222:225], v[8:11]
	v_mfma_f32_16x16x32_bf16 v[60:63], v[170:173], v[202:205], v[60:63]
	v_mfma_f32_16x16x32_bf16 v[56:59], v[178:181], v[202:205], v[56:59]
	v_mfma_f32_16x16x32_bf16 v[44:47], v[170:173], v[210:213], v[44:47]
	v_mfma_f32_16x16x32_bf16 v[40:43], v[178:181], v[210:213], v[40:43]
	v_mfma_f32_16x16x32_bf16 v[28:31], v[170:173], v[218:221], v[28:31]
	v_mfma_f32_16x16x32_bf16 v[24:27], v[178:181], v[218:221], v[24:27]
	v_mfma_f32_16x16x32_bf16 v[12:15], v[170:173], v[226:229], v[12:15]
	v_mfma_f32_16x16x32_bf16 v[8:11], v[178:181], v[226:229], v[8:11]
	s_setprio 0
	s_setprio 1
	v_mfma_f32_16x16x32_bf16 v[52:55], v[182:185], v[198:201], v[52:55]
	v_mfma_f32_16x16x32_bf16 v[48:51], v[190:193], v[198:201], v[48:51]
	v_mfma_f32_16x16x32_bf16 v[36:39], v[182:185], v[206:209], v[36:39]
	v_mfma_f32_16x16x32_bf16 v[32:35], v[190:193], v[206:209], v[32:35]
	v_mfma_f32_16x16x32_bf16 v[20:23], v[182:185], v[214:217], v[20:23]
	v_mfma_f32_16x16x32_bf16 v[16:19], v[190:193], v[214:217], v[16:19]
	v_mfma_f32_16x16x32_bf16 v[4:7], v[182:185], v[222:225], v[4:7]
	v_mfma_f32_16x16x32_bf16 v[0:3], v[190:193], v[222:225], v[0:3]
	v_mfma_f32_16x16x32_bf16 v[52:55], v[186:189], v[202:205], v[52:55]
	v_mfma_f32_16x16x32_bf16 v[48:51], v[194:197], v[202:205], v[48:51]
	v_mfma_f32_16x16x32_bf16 v[36:39], v[186:189], v[210:213], v[36:39]
	v_mfma_f32_16x16x32_bf16 v[32:35], v[194:197], v[210:213], v[32:35]
	v_mfma_f32_16x16x32_bf16 v[20:23], v[186:189], v[218:221], v[20:23]
	v_mfma_f32_16x16x32_bf16 v[16:19], v[194:197], v[218:221], v[16:19]
	v_mfma_f32_16x16x32_bf16 v[4:7], v[186:189], v[226:229], v[4:7]
	v_mfma_f32_16x16x32_bf16 v[0:3], v[194:197], v[226:229], v[0:3]
	s_barrier
	s_setprio 0
	s_add_i32 s8, s81, 2
	s_add_u32 s44, s44, 0x100
	s_addc_u32 s45, s45, 0
	s_cmp_gt_u32 s81, 13
	s_mov_b32 s81, s8
	s_cbranch_scc1 .LBB0_813
	s_branch .LBB0_807
.LBB0_806:
	ds_read_b128 v[166:169], v154
	ds_read_b128 v[170:173], v154 offset:1024
	ds_read_b128 v[174:177], v154 offset:2048
	ds_read_b128 v[178:181], v154 offset:3072
	ds_read_b128 v[182:185], v154 offset:16384
	ds_read_b128 v[186:189], v154 offset:17408
	ds_read_b128 v[190:193], v154 offset:18432
	ds_read_b128 v[194:197], v154 offset:19456
	s_add_i32 m0, s57, 0xc000
	ds_read_b128 v[198:201], v161
	ds_read_b128 v[202:205], v161 offset:1024
	ds_read_b128 v[206:209], v161 offset:2048
	ds_read_b128 v[210:213], v161 offset:3072
	ds_read_b128 v[214:217], v161 offset:4096
	ds_read_b128 v[218:221], v161 offset:5120
	ds_read_b128 v[222:225], v161 offset:6144
	global_load_lds_dwordx4 v140, s[100:101]
	s_add_i32 m0, s57, 0xe000
	ds_read_b128 v[226:229], v161 offset:7168
	global_load_lds_dwordx4 v142, s[100:101]
	s_waitcnt vmcnt(8)
	s_waitcnt lgkmcnt(0)
	s_setprio 1
	s_barrier
	v_mfma_f32_16x16x32_bf16 v[124:127], v[166:169], v[198:201], v[124:127]
	v_mfma_f32_16x16x32_bf16 v[120:123], v[174:177], v[198:201], v[120:123]
	v_mfma_f32_16x16x32_bf16 v[108:111], v[166:169], v[206:209], v[108:111]
	v_mfma_f32_16x16x32_bf16 v[104:107], v[174:177], v[206:209], v[104:107]
	v_mfma_f32_16x16x32_bf16 v[92:95], v[166:169], v[214:217], v[92:95]
	v_mfma_f32_16x16x32_bf16 v[88:91], v[174:177], v[214:217], v[88:91]
	v_mfma_f32_16x16x32_bf16 v[76:79], v[166:169], v[222:225], v[76:79]
	v_mfma_f32_16x16x32_bf16 v[72:75], v[174:177], v[222:225], v[72:75]
	v_mfma_f32_16x16x32_bf16 v[124:127], v[170:173], v[202:205], v[124:127]
	v_mfma_f32_16x16x32_bf16 v[120:123], v[178:181], v[202:205], v[120:123]
	v_mfma_f32_16x16x32_bf16 v[108:111], v[170:173], v[210:213], v[108:111]
	v_mfma_f32_16x16x32_bf16 v[104:107], v[178:181], v[210:213], v[104:107]
	v_mfma_f32_16x16x32_bf16 v[92:95], v[170:173], v[218:221], v[92:95]
	v_mfma_f32_16x16x32_bf16 v[88:91], v[178:181], v[218:221], v[88:91]
	v_mfma_f32_16x16x32_bf16 v[76:79], v[170:173], v[226:229], v[76:79]
	v_mfma_f32_16x16x32_bf16 v[72:75], v[178:181], v[226:229], v[72:75]
	s_setprio 0
	s_setprio 1
	v_mfma_f32_16x16x32_bf16 v[116:119], v[182:185], v[198:201], v[116:119]
	v_mfma_f32_16x16x32_bf16 v[112:115], v[190:193], v[198:201], v[112:115]
	v_mfma_f32_16x16x32_bf16 v[100:103], v[182:185], v[206:209], v[100:103]
	v_mfma_f32_16x16x32_bf16 v[96:99], v[190:193], v[206:209], v[96:99]
	v_mfma_f32_16x16x32_bf16 v[84:87], v[182:185], v[214:217], v[84:87]
	v_mfma_f32_16x16x32_bf16 v[80:83], v[190:193], v[214:217], v[80:83]
	v_mfma_f32_16x16x32_bf16 v[68:71], v[182:185], v[222:225], v[68:71]
	v_mfma_f32_16x16x32_bf16 v[64:67], v[190:193], v[222:225], v[64:67]
	v_mfma_f32_16x16x32_bf16 v[116:119], v[186:189], v[202:205], v[116:119]
	v_mfma_f32_16x16x32_bf16 v[112:115], v[194:197], v[202:205], v[112:115]
	v_mfma_f32_16x16x32_bf16 v[100:103], v[186:189], v[210:213], v[100:103]
	v_mfma_f32_16x16x32_bf16 v[96:99], v[194:197], v[210:213], v[96:99]
	v_mfma_f32_16x16x32_bf16 v[84:87], v[186:189], v[218:221], v[84:87]
	v_mfma_f32_16x16x32_bf16 v[80:83], v[194:197], v[218:221], v[80:83]
	v_mfma_f32_16x16x32_bf16 v[68:71], v[186:189], v[226:229], v[68:71]
	v_mfma_f32_16x16x32_bf16 v[64:67], v[194:197], v[226:229], v[64:67]
	s_barrier
	s_setprio 0
	s_add_i32 s8, s68, s54
	s_mov_b32 m0, s8
	ds_read_b128 v[198:201], v161 offset:16384
	ds_read_b128 v[202:205], v161 offset:17408
	ds_read_b128 v[206:209], v161 offset:18432
	global_load_lds_dwordx4 v128, s[50:51]
	s_add_i32 m0, s8, 0x2000
	ds_read_b128 v[210:213], v161 offset:19456
	global_load_lds_dwordx4 v130, s[50:51]
	s_add_u32 s50, s50, 0x40000
	s_addc_u32 s51, s51, 0
	s_add_i32 s8, s69, s54
	s_mov_b32 m0, s8
	ds_read_b128 v[214:217], v161 offset:20480
	global_load_lds_dwordx4 v128, s[50:51]
	s_add_i32 m0, s8, 0x2000
	ds_read_b128 v[218:221], v161 offset:21504
	global_load_lds_dwordx4 v130, s[50:51]
	s_mov_b32 m0, s57
	ds_read_b128 v[222:225], v161 offset:22528
	global_load_lds_dwordx4 v134, s[52:53]
	s_mov_b32 m0, s58
	ds_read_b128 v[226:229], v161 offset:23552
	global_load_lds_dwordx4 v132, s[52:53]
	s_waitcnt vmcnt(8)
	s_waitcnt lgkmcnt(0)
	s_setprio 1
	s_barrier
	v_mfma_f32_16x16x32_bf16 v[60:63], v[166:169], v[198:201], v[60:63]
	v_mfma_f32_16x16x32_bf16 v[56:59], v[174:177], v[198:201], v[56:59]
	v_mfma_f32_16x16x32_bf16 v[44:47], v[166:169], v[206:209], v[44:47]
	v_mfma_f32_16x16x32_bf16 v[40:43], v[174:177], v[206:209], v[40:43]
	v_mfma_f32_16x16x32_bf16 v[28:31], v[166:169], v[214:217], v[28:31]
	v_mfma_f32_16x16x32_bf16 v[24:27], v[174:177], v[214:217], v[24:27]
	v_mfma_f32_16x16x32_bf16 v[12:15], v[166:169], v[222:225], v[12:15]
	v_mfma_f32_16x16x32_bf16 v[8:11], v[174:177], v[222:225], v[8:11]
	v_mfma_f32_16x16x32_bf16 v[60:63], v[170:173], v[202:205], v[60:63]
	v_mfma_f32_16x16x32_bf16 v[56:59], v[178:181], v[202:205], v[56:59]
	v_mfma_f32_16x16x32_bf16 v[44:47], v[170:173], v[210:213], v[44:47]
	v_mfma_f32_16x16x32_bf16 v[40:43], v[178:181], v[210:213], v[40:43]
	v_mfma_f32_16x16x32_bf16 v[28:31], v[170:173], v[218:221], v[28:31]
	v_mfma_f32_16x16x32_bf16 v[24:27], v[178:181], v[218:221], v[24:27]
	v_mfma_f32_16x16x32_bf16 v[12:15], v[170:173], v[226:229], v[12:15]
	v_mfma_f32_16x16x32_bf16 v[8:11], v[178:181], v[226:229], v[8:11]
	s_setprio 0
	s_setprio 1
	v_mfma_f32_16x16x32_bf16 v[52:55], v[182:185], v[198:201], v[52:55]
	v_mfma_f32_16x16x32_bf16 v[48:51], v[190:193], v[198:201], v[48:51]
	v_mfma_f32_16x16x32_bf16 v[36:39], v[182:185], v[206:209], v[36:39]
	v_mfma_f32_16x16x32_bf16 v[32:35], v[190:193], v[206:209], v[32:35]
	v_mfma_f32_16x16x32_bf16 v[20:23], v[182:185], v[214:217], v[20:23]
	v_mfma_f32_16x16x32_bf16 v[16:19], v[190:193], v[214:217], v[16:19]
	v_mfma_f32_16x16x32_bf16 v[4:7], v[182:185], v[222:225], v[4:7]
	v_mfma_f32_16x16x32_bf16 v[0:3], v[190:193], v[222:225], v[0:3]
	v_mfma_f32_16x16x32_bf16 v[52:55], v[186:189], v[202:205], v[52:55]
	v_mfma_f32_16x16x32_bf16 v[48:51], v[194:197], v[202:205], v[48:51]
	v_mfma_f32_16x16x32_bf16 v[36:39], v[186:189], v[210:213], v[36:39]
	v_mfma_f32_16x16x32_bf16 v[32:35], v[194:197], v[210:213], v[32:35]
	v_mfma_f32_16x16x32_bf16 v[20:23], v[186:189], v[218:221], v[20:23]
	v_mfma_f32_16x16x32_bf16 v[16:19], v[194:197], v[218:221], v[16:19]
	v_mfma_f32_16x16x32_bf16 v[4:7], v[186:189], v[226:229], v[4:7]
	v_mfma_f32_16x16x32_bf16 v[0:3], v[194:197], v[226:229], v[0:3]
	s_barrier
	s_setprio 0
	s_add_i32 s8, 0, 0x18000
	s_add_i32 s82, 0, 0x1c000
	ds_read_b128 v[166:169], v154 offset:32768
	ds_read_b128 v[170:173], v154 offset:33792
	ds_read_b128 v[174:177], v154 offset:34816
	ds_read_b128 v[178:181], v154 offset:35840
	ds_read_b128 v[182:185], v154 offset:49152
	ds_read_b128 v[186:189], v154 offset:50176
	ds_read_b128 v[190:193], v154 offset:51200
	ds_read_b128 v[194:197], v154 offset:52224
	s_add_u32 s50, s52, 0x40000
	s_addc_u32 s51, s53, 0
	s_mov_b32 m0, s59
	ds_read_b128 v[198:201], v161 offset:32768
	ds_read_b128 v[202:205], v161 offset:33792
	ds_read_b128 v[206:209], v161 offset:34816
	ds_read_b128 v[210:213], v161 offset:35840
	ds_read_b128 v[214:217], v161 offset:36864
	ds_read_b128 v[218:221], v161 offset:37888
	ds_read_b128 v[222:225], v161 offset:38912
	global_load_lds_dwordx4 v134, s[50:51]
	s_mov_b32 m0, s60
	ds_read_b128 v[226:229], v161 offset:39936
	global_load_lds_dwordx4 v132, s[50:51]
	s_waitcnt vmcnt(8)
	s_waitcnt lgkmcnt(0)
	s_setprio 1
	s_barrier
	v_mfma_f32_16x16x32_bf16 v[124:127], v[166:169], v[198:201], v[124:127]
	v_mfma_f32_16x16x32_bf16 v[120:123], v[174:177], v[198:201], v[120:123]
	v_mfma_f32_16x16x32_bf16 v[108:111], v[166:169], v[206:209], v[108:111]
	v_mfma_f32_16x16x32_bf16 v[104:107], v[174:177], v[206:209], v[104:107]
	v_mfma_f32_16x16x32_bf16 v[92:95], v[166:169], v[214:217], v[92:95]
	v_mfma_f32_16x16x32_bf16 v[88:91], v[174:177], v[214:217], v[88:91]
	v_mfma_f32_16x16x32_bf16 v[76:79], v[166:169], v[222:225], v[76:79]
	v_mfma_f32_16x16x32_bf16 v[72:75], v[174:177], v[222:225], v[72:75]
	v_mfma_f32_16x16x32_bf16 v[124:127], v[170:173], v[202:205], v[124:127]
	v_mfma_f32_16x16x32_bf16 v[120:123], v[178:181], v[202:205], v[120:123]
	v_mfma_f32_16x16x32_bf16 v[108:111], v[170:173], v[210:213], v[108:111]
	v_mfma_f32_16x16x32_bf16 v[104:107], v[178:181], v[210:213], v[104:107]
	v_mfma_f32_16x16x32_bf16 v[92:95], v[170:173], v[218:221], v[92:95]
	v_mfma_f32_16x16x32_bf16 v[88:91], v[178:181], v[218:221], v[88:91]
	v_mfma_f32_16x16x32_bf16 v[76:79], v[170:173], v[226:229], v[76:79]
	v_mfma_f32_16x16x32_bf16 v[72:75], v[178:181], v[226:229], v[72:75]
	s_setprio 0
	s_setprio 1
	v_mfma_f32_16x16x32_bf16 v[116:119], v[182:185], v[198:201], v[116:119]
	v_mfma_f32_16x16x32_bf16 v[112:115], v[190:193], v[198:201], v[112:115]
	v_mfma_f32_16x16x32_bf16 v[100:103], v[182:185], v[206:209], v[100:103]
	v_mfma_f32_16x16x32_bf16 v[96:99], v[190:193], v[206:209], v[96:99]
	v_mfma_f32_16x16x32_bf16 v[84:87], v[182:185], v[214:217], v[84:87]
	v_mfma_f32_16x16x32_bf16 v[80:83], v[190:193], v[214:217], v[80:83]
	v_mfma_f32_16x16x32_bf16 v[68:71], v[182:185], v[222:225], v[68:71]
	v_mfma_f32_16x16x32_bf16 v[64:67], v[190:193], v[222:225], v[64:67]
	v_mfma_f32_16x16x32_bf16 v[116:119], v[186:189], v[202:205], v[116:119]
	v_mfma_f32_16x16x32_bf16 v[112:115], v[194:197], v[202:205], v[112:115]
	v_mfma_f32_16x16x32_bf16 v[100:103], v[186:189], v[210:213], v[100:103]
	v_mfma_f32_16x16x32_bf16 v[96:99], v[194:197], v[210:213], v[96:99]
	v_mfma_f32_16x16x32_bf16 v[84:87], v[186:189], v[218:221], v[84:87]
	v_mfma_f32_16x16x32_bf16 v[80:83], v[194:197], v[218:221], v[80:83]
	v_mfma_f32_16x16x32_bf16 v[68:71], v[186:189], v[226:229], v[68:71]
	v_mfma_f32_16x16x32_bf16 v[64:67], v[194:197], v[226:229], v[64:67]
	s_barrier
	s_setprio 0
	s_add_i32 s8, s8, s54
	s_mov_b32 m0, s8
	ds_read_b128 v[198:201], v161 offset:49152
	ds_read_b128 v[202:205], v161 offset:50176
	ds_read_b128 v[206:209], v161 offset:51200
	global_load_lds_dwordx4 v128, s[48:49]
	s_add_i32 m0, s8, 0x2000
	ds_read_b128 v[210:213], v161 offset:52224
	global_load_lds_dwordx4 v130, s[48:49]
	s_add_u32 s48, s48, 0x40000
	s_addc_u32 s49, s49, 0
	s_add_i32 s8, s82, s54
	s_mov_b32 m0, s8
	ds_read_b128 v[214:217], v161 offset:53248
	global_load_lds_dwordx4 v128, s[48:49]
	s_add_i32 m0, s8, 0x2000
	ds_read_b128 v[218:221], v161 offset:54272
	global_load_lds_dwordx4 v130, s[48:49]
	s_mov_b32 m0, s65
	ds_read_b128 v[222:225], v161 offset:55296
	global_load_lds_dwordx4 v134, s[46:47]
	s_mov_b32 m0, s66
	ds_read_b128 v[226:229], v161 offset:56320
	global_load_lds_dwordx4 v132, s[46:47]
	s_waitcnt vmcnt(8)
	s_waitcnt lgkmcnt(0)
	s_setprio 1
	s_barrier
	v_mfma_f32_16x16x32_bf16 v[60:63], v[166:169], v[198:201], v[60:63]
	v_mfma_f32_16x16x32_bf16 v[56:59], v[174:177], v[198:201], v[56:59]
	v_mfma_f32_16x16x32_bf16 v[44:47], v[166:169], v[206:209], v[44:47]
	v_mfma_f32_16x16x32_bf16 v[40:43], v[174:177], v[206:209], v[40:43]
	v_mfma_f32_16x16x32_bf16 v[28:31], v[166:169], v[214:217], v[28:31]
	v_mfma_f32_16x16x32_bf16 v[24:27], v[174:177], v[214:217], v[24:27]
	v_mfma_f32_16x16x32_bf16 v[12:15], v[166:169], v[222:225], v[12:15]
	v_mfma_f32_16x16x32_bf16 v[8:11], v[174:177], v[222:225], v[8:11]
	v_mfma_f32_16x16x32_bf16 v[60:63], v[170:173], v[202:205], v[60:63]
	v_mfma_f32_16x16x32_bf16 v[56:59], v[178:181], v[202:205], v[56:59]
	v_mfma_f32_16x16x32_bf16 v[44:47], v[170:173], v[210:213], v[44:47]
	v_mfma_f32_16x16x32_bf16 v[40:43], v[178:181], v[210:213], v[40:43]
	v_mfma_f32_16x16x32_bf16 v[28:31], v[170:173], v[218:221], v[28:31]
	v_mfma_f32_16x16x32_bf16 v[24:27], v[178:181], v[218:221], v[24:27]
	v_mfma_f32_16x16x32_bf16 v[12:15], v[170:173], v[226:229], v[12:15]
	v_mfma_f32_16x16x32_bf16 v[8:11], v[178:181], v[226:229], v[8:11]
	s_setprio 0
	s_setprio 1
	v_mfma_f32_16x16x32_bf16 v[52:55], v[182:185], v[198:201], v[52:55]
	v_mfma_f32_16x16x32_bf16 v[48:51], v[190:193], v[198:201], v[48:51]
	v_mfma_f32_16x16x32_bf16 v[36:39], v[182:185], v[206:209], v[36:39]
	v_mfma_f32_16x16x32_bf16 v[32:35], v[190:193], v[206:209], v[32:35]
	v_mfma_f32_16x16x32_bf16 v[20:23], v[182:185], v[214:217], v[20:23]
	v_mfma_f32_16x16x32_bf16 v[16:19], v[190:193], v[214:217], v[16:19]
	v_mfma_f32_16x16x32_bf16 v[4:7], v[182:185], v[222:225], v[4:7]
	v_mfma_f32_16x16x32_bf16 v[0:3], v[190:193], v[222:225], v[0:3]
	v_mfma_f32_16x16x32_bf16 v[52:55], v[186:189], v[202:205], v[52:55]
	v_mfma_f32_16x16x32_bf16 v[48:51], v[194:197], v[202:205], v[48:51]
	v_mfma_f32_16x16x32_bf16 v[36:39], v[186:189], v[210:213], v[36:39]
	v_mfma_f32_16x16x32_bf16 v[32:35], v[194:197], v[210:213], v[32:35]
	v_mfma_f32_16x16x32_bf16 v[20:23], v[186:189], v[218:221], v[20:23]
	v_mfma_f32_16x16x32_bf16 v[16:19], v[194:197], v[218:221], v[16:19]
	v_mfma_f32_16x16x32_bf16 v[4:7], v[186:189], v[226:229], v[4:7]
	v_mfma_f32_16x16x32_bf16 v[0:3], v[194:197], v[226:229], v[0:3]
	s_barrier
	s_setprio 0
	s_add_i32 s8, s81, 2
	s_add_u32 s44, s44, 0x100
	s_addc_u32 s45, s45, 0
	s_cmp_gt_u32 s81, 13
	s_mov_b32 s81, s8
	s_cbranch_scc1 .LBB0_813

.LBB0_895:
	s_add_u32 s70, s55, s28
	s_addc_u32 s71, s56, s29
	s_add_u32 s72, s57, s30
	s_addc_u32 s73, s58, s31
	s_add_u32 s28, s4, 0x80
	s_addc_u32 s29, s5, 0
	s_add_u32 s30, s20, 0x80
	s_addc_u32 s31, s21, 0
	v_lshl_add_u64 v[128:129], s[26:27], 0, v[148:149]
	v_lshl_add_u64 v[130:131], s[26:27], 0, v[150:151]
	s_mov_b32 s78, 0
	s_mov_b64 s[36:37], 0
	v_add_u32_e32 v220, 0x10000, v165
	s_add_u32 s46, s26, s36
	s_addc_u32 s47, s27, s37
	s_mov_b64 s[100:101], s[46:47]
	s_add_u32 s80, s24, s36
	s_addc_u32 s79, s25, s37
	s_add_u32 s38, s46, 0x180
	s_addc_u32 s39, s47, 0
	s_add_u32 s40, s80, 0x180
	s_addc_u32 s41, s79, 0
	s_add_u32 s46, s46, 0x100
	s_addc_u32 s47, s47, 0
	s_add_u32 s44, s80, 0x100
	s_addc_u32 s45, s79, 0
	s_cmpk_eq_i32 s36, 0x1500
	s_cselect_b32 s38, s28, s38
	s_cselect_b32 s39, s29, s39
	s_cselect_b32 s40, s30, s40
	s_cselect_b32 s41, s31, s41
	s_cselect_b32 s46, s4, s46
	s_cselect_b32 s47, s5, s47
	s_cselect_b32 s44, s20, s44
	s_cselect_b32 s45, s21, s45
	ds_read_b128 v[132:135], v220
	ds_read_b128 v[156:159], v220 offset:1024
	ds_read_b128 v[160:163], v220 offset:2048
	ds_read_b128 v[168:171], v220 offset:3072
	ds_read_b128 v[172:175], v220 offset:16384
	ds_read_b128 v[176:179], v220 offset:17408
	ds_read_b128 v[180:183], v220 offset:18432
	ds_read_b128 v[184:187], v220 offset:19456
	s_add_i32 m0, s51, 0xc000
	ds_read_b128 v[188:191], v166
	ds_read_b128 v[192:195], v166 offset:1024
	ds_read_b128 v[196:199], v166 offset:2048
	ds_read_b128 v[200:203], v166 offset:3072
	ds_read_b128 v[204:207], v166 offset:4096
	ds_read_b128 v[208:211], v166 offset:5120
	ds_read_b128 v[212:215], v166 offset:6144
	global_load_lds_dwordx4 v148, s[100:101]
	s_add_i32 m0, s51, 0xe000
	ds_read_b128 v[216:219], v166 offset:7168
	global_load_lds_dwordx4 v150, s[100:101]
	s_waitcnt vmcnt(8)
	s_waitcnt lgkmcnt(0)
	s_setprio 1
	s_barrier
	v_mfma_f32_16x16x32_bf16 v[124:127], v[132:135], v[188:191], 0
	v_mfma_f32_16x16x32_bf16 v[120:123], v[160:163], v[188:191], 0
	v_mfma_f32_16x16x32_bf16 v[108:111], v[132:135], v[196:199], 0
	v_mfma_f32_16x16x32_bf16 v[104:107], v[160:163], v[196:199], 0
	v_mfma_f32_16x16x32_bf16 v[92:95], v[132:135], v[204:207], 0
	v_mfma_f32_16x16x32_bf16 v[88:91], v[160:163], v[204:207], 0
	v_mfma_f32_16x16x32_bf16 v[76:79], v[132:135], v[212:215], 0
	v_mfma_f32_16x16x32_bf16 v[72:75], v[160:163], v[212:215], 0
	v_mfma_f32_16x16x32_bf16 v[124:127], v[156:159], v[192:195], v[124:127]
	v_mfma_f32_16x16x32_bf16 v[120:123], v[168:171], v[192:195], v[120:123]
	v_mfma_f32_16x16x32_bf16 v[108:111], v[156:159], v[200:203], v[108:111]
	v_mfma_f32_16x16x32_bf16 v[104:107], v[168:171], v[200:203], v[104:107]
	v_mfma_f32_16x16x32_bf16 v[92:95], v[156:159], v[208:211], v[92:95]
	v_mfma_f32_16x16x32_bf16 v[88:91], v[168:171], v[208:211], v[88:91]
	v_mfma_f32_16x16x32_bf16 v[76:79], v[156:159], v[216:219], v[76:79]
	v_mfma_f32_16x16x32_bf16 v[72:75], v[168:171], v[216:219], v[72:75]
	s_setprio 0
	s_setprio 1
	v_mfma_f32_16x16x32_bf16 v[116:119], v[172:175], v[188:191], 0
	v_mfma_f32_16x16x32_bf16 v[112:115], v[180:183], v[188:191], 0
	v_mfma_f32_16x16x32_bf16 v[100:103], v[172:175], v[196:199], 0
	v_mfma_f32_16x16x32_bf16 v[96:99], v[180:183], v[196:199], 0
	v_mfma_f32_16x16x32_bf16 v[84:87], v[172:175], v[204:207], 0
	v_mfma_f32_16x16x32_bf16 v[80:83], v[180:183], v[204:207], 0
	v_mfma_f32_16x16x32_bf16 v[68:71], v[172:175], v[212:215], 0
	v_mfma_f32_16x16x32_bf16 v[64:67], v[180:183], v[212:215], 0
	v_mfma_f32_16x16x32_bf16 v[116:119], v[176:179], v[192:195], v[116:119]
	v_mfma_f32_16x16x32_bf16 v[112:115], v[184:187], v[192:195], v[112:115]
	v_mfma_f32_16x16x32_bf16 v[100:103], v[176:179], v[200:203], v[100:103]
	v_mfma_f32_16x16x32_bf16 v[96:99], v[184:187], v[200:203], v[96:99]
	v_mfma_f32_16x16x32_bf16 v[84:87], v[176:179], v[208:211], v[84:87]
	v_mfma_f32_16x16x32_bf16 v[80:83], v[184:187], v[208:211], v[80:83]
	v_mfma_f32_16x16x32_bf16 v[68:71], v[176:179], v[216:219], v[68:71]
	v_mfma_f32_16x16x32_bf16 v[64:67], v[184:187], v[216:219], v[64:67]
	s_barrier
	s_setprio 0
	s_add_i32 s8, s64, s50
	s_mov_b32 m0, s8
	ds_read_b128 v[188:191], v166 offset:16384
	ds_read_b128 v[192:195], v166 offset:17408
	ds_read_b128 v[196:199], v166 offset:18432
	global_load_lds_dwordx4 v138, s[44:45]
	s_add_i32 m0, s8, 0x2000
	ds_read_b128 v[200:203], v166 offset:19456
	global_load_lds_dwordx4 v142, s[44:45]
	s_add_u32 s44, s44, 0xb0000
	s_addc_u32 s45, s45, 0
	s_add_i32 s8, s65, s50
	s_mov_b32 m0, s8
	ds_read_b128 v[204:207], v166 offset:20480
	global_load_lds_dwordx4 v138, s[44:45]
	s_add_i32 m0, s8, 0x2000
	ds_read_b128 v[208:211], v166 offset:21504
	global_load_lds_dwordx4 v142, s[44:45]
	s_mov_b32 m0, s51
	ds_read_b128 v[212:215], v166 offset:22528
	global_load_lds_dwordx4 v136, s[46:47]
	s_mov_b32 m0, s52
	ds_read_b128 v[216:219], v166 offset:23552
	global_load_lds_dwordx4 v140, s[46:47]
	s_waitcnt vmcnt(8)
	s_waitcnt lgkmcnt(0)
	s_setprio 1
	s_barrier
	v_mfma_f32_16x16x32_bf16 v[60:63], v[132:135], v[188:191], 0
	v_mfma_f32_16x16x32_bf16 v[56:59], v[160:163], v[188:191], 0
	v_mfma_f32_16x16x32_bf16 v[44:47], v[132:135], v[196:199], 0
	v_mfma_f32_16x16x32_bf16 v[40:43], v[160:163], v[196:199], 0
	v_mfma_f32_16x16x32_bf16 v[28:31], v[132:135], v[204:207], 0
	v_mfma_f32_16x16x32_bf16 v[24:27], v[160:163], v[204:207], 0
	v_mfma_f32_16x16x32_bf16 v[12:15], v[132:135], v[212:215], 0
	v_mfma_f32_16x16x32_bf16 v[8:11], v[160:163], v[212:215], 0
	v_mfma_f32_16x16x32_bf16 v[60:63], v[156:159], v[192:195], v[60:63]
	v_mfma_f32_16x16x32_bf16 v[56:59], v[168:171], v[192:195], v[56:59]
	v_mfma_f32_16x16x32_bf16 v[44:47], v[156:159], v[200:203], v[44:47]
	v_mfma_f32_16x16x32_bf16 v[40:43], v[168:171], v[200:203], v[40:43]
	v_mfma_f32_16x16x32_bf16 v[28:31], v[156:159], v[208:211], v[28:31]
	v_mfma_f32_16x16x32_bf16 v[24:27], v[168:171], v[208:211], v[24:27]
	v_mfma_f32_16x16x32_bf16 v[12:15], v[156:159], v[216:219], v[12:15]
	v_mfma_f32_16x16x32_bf16 v[8:11], v[168:171], v[216:219], v[8:11]
	s_setprio 0
	s_setprio 1
	v_mfma_f32_16x16x32_bf16 v[52:55], v[172:175], v[188:191], 0
	v_mfma_f32_16x16x32_bf16 v[48:51], v[180:183], v[188:191], 0
	v_mfma_f32_16x16x32_bf16 v[36:39], v[172:175], v[196:199], 0
	v_mfma_f32_16x16x32_bf16 v[32:35], v[180:183], v[196:199], 0
	v_mfma_f32_16x16x32_bf16 v[20:23], v[172:175], v[204:207], 0
	v_mfma_f32_16x16x32_bf16 v[16:19], v[180:183], v[204:207], 0
	v_mfma_f32_16x16x32_bf16 v[4:7], v[172:175], v[212:215], 0
	v_mfma_f32_16x16x32_bf16 v[0:3], v[180:183], v[212:215], 0
	v_mfma_f32_16x16x32_bf16 v[52:55], v[176:179], v[192:195], v[52:55]
	v_mfma_f32_16x16x32_bf16 v[48:51], v[184:187], v[192:195], v[48:51]
	v_mfma_f32_16x16x32_bf16 v[36:39], v[176:179], v[200:203], v[36:39]
	v_mfma_f32_16x16x32_bf16 v[32:35], v[184:187], v[200:203], v[32:35]
	v_mfma_f32_16x16x32_bf16 v[20:23], v[176:179], v[208:211], v[20:23]
	v_mfma_f32_16x16x32_bf16 v[16:19], v[184:187], v[208:211], v[16:19]
	v_mfma_f32_16x16x32_bf16 v[4:7], v[176:179], v[216:219], v[4:7]
	v_mfma_f32_16x16x32_bf16 v[0:3], v[184:187], v[216:219], v[0:3]
	s_barrier
	s_setprio 0
	s_add_i32 s8, 0, 0x18000
	s_add_i32 s79, 0, 0x1c000
	ds_read_b128 v[132:135], v220 offset:32768
	ds_read_b128 v[156:159], v220 offset:33792
	ds_read_b128 v[160:163], v220 offset:34816
	ds_read_b128 v[168:171], v220 offset:35840
	ds_read_b128 v[172:175], v220 offset:49152
	ds_read_b128 v[176:179], v220 offset:50176
	ds_read_b128 v[180:183], v220 offset:51200
	ds_read_b128 v[184:187], v220 offset:52224
	s_add_u32 s44, s46, 0xb0000
	s_addc_u32 s45, s47, 0
	s_mov_b32 m0, s53
	ds_read_b128 v[188:191], v166 offset:32768
	ds_read_b128 v[192:195], v166 offset:33792
	ds_read_b128 v[196:199], v166 offset:34816
	ds_read_b128 v[200:203], v166 offset:35840
	ds_read_b128 v[204:207], v166 offset:36864
	ds_read_b128 v[208:211], v166 offset:37888
	ds_read_b128 v[212:215], v166 offset:38912
	global_load_lds_dwordx4 v136, s[44:45]
	s_mov_b32 m0, s54
	ds_read_b128 v[216:219], v166 offset:39936
	global_load_lds_dwordx4 v140, s[44:45]
	s_waitcnt vmcnt(8)
	s_waitcnt lgkmcnt(0)
	s_setprio 1
	s_barrier
	v_mfma_f32_16x16x32_bf16 v[124:127], v[132:135], v[188:191], v[124:127]
	v_mfma_f32_16x16x32_bf16 v[120:123], v[160:163], v[188:191], v[120:123]
	v_mfma_f32_16x16x32_bf16 v[108:111], v[132:135], v[196:199], v[108:111]
	v_mfma_f32_16x16x32_bf16 v[104:107], v[160:163], v[196:199], v[104:107]
	v_mfma_f32_16x16x32_bf16 v[92:95], v[132:135], v[204:207], v[92:95]
	v_mfma_f32_16x16x32_bf16 v[88:91], v[160:163], v[204:207], v[88:91]
	v_mfma_f32_16x16x32_bf16 v[76:79], v[132:135], v[212:215], v[76:79]
	v_mfma_f32_16x16x32_bf16 v[72:75], v[160:163], v[212:215], v[72:75]
	v_mfma_f32_16x16x32_bf16 v[124:127], v[156:159], v[192:195], v[124:127]
	v_mfma_f32_16x16x32_bf16 v[120:123], v[168:171], v[192:195], v[120:123]
	v_mfma_f32_16x16x32_bf16 v[108:111], v[156:159], v[200:203], v[108:111]
	v_mfma_f32_16x16x32_bf16 v[104:107], v[168:171], v[200:203], v[104:107]
	v_mfma_f32_16x16x32_bf16 v[92:95], v[156:159], v[208:211], v[92:95]
	v_mfma_f32_16x16x32_bf16 v[88:91], v[168:171], v[208:211], v[88:91]
	v_mfma_f32_16x16x32_bf16 v[76:79], v[156:159], v[216:219], v[76:79]
	v_mfma_f32_16x16x32_bf16 v[72:75], v[168:171], v[216:219], v[72:75]
	s_setprio 0
	s_setprio 1
	v_mfma_f32_16x16x32_bf16 v[116:119], v[172:175], v[188:191], v[116:119]
	v_mfma_f32_16x16x32_bf16 v[112:115], v[180:183], v[188:191], v[112:115]
	v_mfma_f32_16x16x32_bf16 v[100:103], v[172:175], v[196:199], v[100:103]
	v_mfma_f32_16x16x32_bf16 v[96:99], v[180:183], v[196:199], v[96:99]
	v_mfma_f32_16x16x32_bf16 v[84:87], v[172:175], v[204:207], v[84:87]
	v_mfma_f32_16x16x32_bf16 v[80:83], v[180:183], v[204:207], v[80:83]
	v_mfma_f32_16x16x32_bf16 v[68:71], v[172:175], v[212:215], v[68:71]
	v_mfma_f32_16x16x32_bf16 v[64:67], v[180:183], v[212:215], v[64:67]
	v_mfma_f32_16x16x32_bf16 v[116:119], v[176:179], v[192:195], v[116:119]
	v_mfma_f32_16x16x32_bf16 v[112:115], v[184:187], v[192:195], v[112:115]
	v_mfma_f32_16x16x32_bf16 v[100:103], v[176:179], v[200:203], v[100:103]
	v_mfma_f32_16x16x32_bf16 v[96:99], v[184:187], v[200:203], v[96:99]
	v_mfma_f32_16x16x32_bf16 v[84:87], v[176:179], v[208:211], v[84:87]
	v_mfma_f32_16x16x32_bf16 v[80:83], v[184:187], v[208:211], v[80:83]
	v_mfma_f32_16x16x32_bf16 v[68:71], v[176:179], v[216:219], v[68:71]
	v_mfma_f32_16x16x32_bf16 v[64:67], v[184:187], v[216:219], v[64:67]
	s_barrier
	s_setprio 0
	s_add_i32 s8, s8, s50
	s_mov_b32 m0, s8
	ds_read_b128 v[188:191], v166 offset:49152
	ds_read_b128 v[192:195], v166 offset:50176
	ds_read_b128 v[196:199], v166 offset:51200
	global_load_lds_dwordx4 v138, s[40:41]
	s_add_i32 m0, s8, 0x2000
	ds_read_b128 v[200:203], v166 offset:52224
	global_load_lds_dwordx4 v142, s[40:41]
	s_add_u32 s40, s40, 0xb0000
	s_addc_u32 s41, s41, 0
	s_add_i32 s8, s79, s50
	s_mov_b32 m0, s8
	ds_read_b128 v[204:207], v166 offset:53248
	global_load_lds_dwordx4 v138, s[40:41]
	s_add_i32 m0, s8, 0x2000
	ds_read_b128 v[208:211], v166 offset:54272
	global_load_lds_dwordx4 v142, s[40:41]
	s_mov_b32 m0, s60
	ds_read_b128 v[212:215], v166 offset:55296
	global_load_lds_dwordx4 v136, s[38:39]
	s_mov_b32 m0, s61
	ds_read_b128 v[216:219], v166 offset:56320
	global_load_lds_dwordx4 v140, s[38:39]
	s_waitcnt vmcnt(8)
	s_waitcnt lgkmcnt(0)
	s_setprio 1
	s_barrier
	v_mfma_f32_16x16x32_bf16 v[60:63], v[132:135], v[188:191], v[60:63]
	v_mfma_f32_16x16x32_bf16 v[56:59], v[160:163], v[188:191], v[56:59]
	v_mfma_f32_16x16x32_bf16 v[44:47], v[132:135], v[196:199], v[44:47]
	v_mfma_f32_16x16x32_bf16 v[40:43], v[160:163], v[196:199], v[40:43]
	v_mfma_f32_16x16x32_bf16 v[28:31], v[132:135], v[204:207], v[28:31]
	v_mfma_f32_16x16x32_bf16 v[24:27], v[160:163], v[204:207], v[24:27]
	v_mfma_f32_16x16x32_bf16 v[12:15], v[132:135], v[212:215], v[12:15]
	v_mfma_f32_16x16x32_bf16 v[8:11], v[160:163], v[212:215], v[8:11]
	v_mfma_f32_16x16x32_bf16 v[60:63], v[156:159], v[192:195], v[60:63]
	v_mfma_f32_16x16x32_bf16 v[56:59], v[168:171], v[192:195], v[56:59]
	v_mfma_f32_16x16x32_bf16 v[44:47], v[156:159], v[200:203], v[44:47]
	v_mfma_f32_16x16x32_bf16 v[40:43], v[168:171], v[200:203], v[40:43]
	v_mfma_f32_16x16x32_bf16 v[28:31], v[156:159], v[208:211], v[28:31]
	v_mfma_f32_16x16x32_bf16 v[24:27], v[168:171], v[208:211], v[24:27]
	v_mfma_f32_16x16x32_bf16 v[12:15], v[156:159], v[216:219], v[12:15]
	v_mfma_f32_16x16x32_bf16 v[8:11], v[168:171], v[216:219], v[8:11]
	s_setprio 0
	s_setprio 1
	v_mfma_f32_16x16x32_bf16 v[52:55], v[172:175], v[188:191], v[52:55]
	v_mfma_f32_16x16x32_bf16 v[48:51], v[180:183], v[188:191], v[48:51]
	v_mfma_f32_16x16x32_bf16 v[36:39], v[172:175], v[196:199], v[36:39]
	v_mfma_f32_16x16x32_bf16 v[32:35], v[180:183], v[196:199], v[32:35]
	v_mfma_f32_16x16x32_bf16 v[20:23], v[172:175], v[204:207], v[20:23]
	v_mfma_f32_16x16x32_bf16 v[16:19], v[180:183], v[204:207], v[16:19]
	v_mfma_f32_16x16x32_bf16 v[4:7], v[172:175], v[212:215], v[4:7]
	v_mfma_f32_16x16x32_bf16 v[0:3], v[180:183], v[212:215], v[0:3]
	v_mfma_f32_16x16x32_bf16 v[52:55], v[176:179], v[192:195], v[52:55]
	v_mfma_f32_16x16x32_bf16 v[48:51], v[184:187], v[192:195], v[48:51]
	v_mfma_f32_16x16x32_bf16 v[36:39], v[176:179], v[200:203], v[36:39]
	v_mfma_f32_16x16x32_bf16 v[32:35], v[184:187], v[200:203], v[32:35]
	v_mfma_f32_16x16x32_bf16 v[20:23], v[176:179], v[208:211], v[20:23]
	v_mfma_f32_16x16x32_bf16 v[16:19], v[184:187], v[208:211], v[16:19]
	v_mfma_f32_16x16x32_bf16 v[4:7], v[176:179], v[216:219], v[4:7]
	v_mfma_f32_16x16x32_bf16 v[0:3], v[184:187], v[216:219], v[0:3]
	s_barrier
	s_setprio 0
	s_add_i32 s8, s78, 2
	s_add_u32 s36, s36, 0x100
	s_addc_u32 s37, s37, 0
	s_cmp_gt_u32 s78, 41
	s_mov_b32 s78, s8
	s_cbranch_scc1 .LBB0_903
	s_branch .LBB0_897
.LBB0_896:
	ds_read_b128 v[132:135], v220
	ds_read_b128 v[156:159], v220 offset:1024
	ds_read_b128 v[160:163], v220 offset:2048
	ds_read_b128 v[168:171], v220 offset:3072
	ds_read_b128 v[172:175], v220 offset:16384
	ds_read_b128 v[176:179], v220 offset:17408
	ds_read_b128 v[180:183], v220 offset:18432
	ds_read_b128 v[184:187], v220 offset:19456
	s_add_i32 m0, s51, 0xc000
	ds_read_b128 v[188:191], v166
	ds_read_b128 v[192:195], v166 offset:1024
	ds_read_b128 v[196:199], v166 offset:2048
	ds_read_b128 v[200:203], v166 offset:3072
	ds_read_b128 v[204:207], v166 offset:4096
	ds_read_b128 v[208:211], v166 offset:5120
	ds_read_b128 v[212:215], v166 offset:6144
	global_load_lds_dwordx4 v148, s[100:101]
	s_add_i32 m0, s51, 0xe000
	ds_read_b128 v[216:219], v166 offset:7168
	global_load_lds_dwordx4 v150, s[100:101]
	s_waitcnt vmcnt(8)
	s_waitcnt lgkmcnt(0)
	s_setprio 1
	s_barrier
	v_mfma_f32_16x16x32_bf16 v[124:127], v[132:135], v[188:191], v[124:127]
	v_mfma_f32_16x16x32_bf16 v[120:123], v[160:163], v[188:191], v[120:123]
	v_mfma_f32_16x16x32_bf16 v[108:111], v[132:135], v[196:199], v[108:111]
	v_mfma_f32_16x16x32_bf16 v[104:107], v[160:163], v[196:199], v[104:107]
	v_mfma_f32_16x16x32_bf16 v[92:95], v[132:135], v[204:207], v[92:95]
	v_mfma_f32_16x16x32_bf16 v[88:91], v[160:163], v[204:207], v[88:91]
	v_mfma_f32_16x16x32_bf16 v[76:79], v[132:135], v[212:215], v[76:79]
	v_mfma_f32_16x16x32_bf16 v[72:75], v[160:163], v[212:215], v[72:75]
	v_mfma_f32_16x16x32_bf16 v[124:127], v[156:159], v[192:195], v[124:127]
	v_mfma_f32_16x16x32_bf16 v[120:123], v[168:171], v[192:195], v[120:123]
	v_mfma_f32_16x16x32_bf16 v[108:111], v[156:159], v[200:203], v[108:111]
	v_mfma_f32_16x16x32_bf16 v[104:107], v[168:171], v[200:203], v[104:107]
	v_mfma_f32_16x16x32_bf16 v[92:95], v[156:159], v[208:211], v[92:95]
	v_mfma_f32_16x16x32_bf16 v[88:91], v[168:171], v[208:211], v[88:91]
	v_mfma_f32_16x16x32_bf16 v[76:79], v[156:159], v[216:219], v[76:79]
	v_mfma_f32_16x16x32_bf16 v[72:75], v[168:171], v[216:219], v[72:75]
	s_setprio 0
	s_setprio 1
	v_mfma_f32_16x16x32_bf16 v[116:119], v[172:175], v[188:191], v[116:119]
	v_mfma_f32_16x16x32_bf16 v[112:115], v[180:183], v[188:191], v[112:115]
	v_mfma_f32_16x16x32_bf16 v[100:103], v[172:175], v[196:199], v[100:103]
	v_mfma_f32_16x16x32_bf16 v[96:99], v[180:183], v[196:199], v[96:99]
	v_mfma_f32_16x16x32_bf16 v[84:87], v[172:175], v[204:207], v[84:87]
	v_mfma_f32_16x16x32_bf16 v[80:83], v[180:183], v[204:207], v[80:83]
	v_mfma_f32_16x16x32_bf16 v[68:71], v[172:175], v[212:215], v[68:71]
	v_mfma_f32_16x16x32_bf16 v[64:67], v[180:183], v[212:215], v[64:67]
	v_mfma_f32_16x16x32_bf16 v[116:119], v[176:179], v[192:195], v[116:119]
	v_mfma_f32_16x16x32_bf16 v[112:115], v[184:187], v[192:195], v[112:115]
	v_mfma_f32_16x16x32_bf16 v[100:103], v[176:179], v[200:203], v[100:103]
	v_mfma_f32_16x16x32_bf16 v[96:99], v[184:187], v[200:203], v[96:99]
	v_mfma_f32_16x16x32_bf16 v[84:87], v[176:179], v[208:211], v[84:87]
	v_mfma_f32_16x16x32_bf16 v[80:83], v[184:187], v[208:211], v[80:83]
	v_mfma_f32_16x16x32_bf16 v[68:71], v[176:179], v[216:219], v[68:71]
	v_mfma_f32_16x16x32_bf16 v[64:67], v[184:187], v[216:219], v[64:67]
	s_barrier
	s_setprio 0
	s_add_i32 s8, s64, s50
	s_mov_b32 m0, s8
	ds_read_b128 v[188:191], v166 offset:16384
	ds_read_b128 v[192:195], v166 offset:17408
	ds_read_b128 v[196:199], v166 offset:18432
	global_load_lds_dwordx4 v138, s[44:45]
	s_add_i32 m0, s8, 0x2000
	ds_read_b128 v[200:203], v166 offset:19456
	global_load_lds_dwordx4 v142, s[44:45]
	s_add_u32 s44, s44, 0xb0000
	s_addc_u32 s45, s45, 0
	s_add_i32 s8, s65, s50
	s_mov_b32 m0, s8
	ds_read_b128 v[204:207], v166 offset:20480
	global_load_lds_dwordx4 v138, s[44:45]
	s_add_i32 m0, s8, 0x2000
	ds_read_b128 v[208:211], v166 offset:21504
	global_load_lds_dwordx4 v142, s[44:45]
	s_mov_b32 m0, s51
	ds_read_b128 v[212:215], v166 offset:22528
	global_load_lds_dwordx4 v136, s[46:47]
	s_mov_b32 m0, s52
	ds_read_b128 v[216:219], v166 offset:23552
	global_load_lds_dwordx4 v140, s[46:47]
	s_waitcnt vmcnt(8)
	s_waitcnt lgkmcnt(0)
	s_setprio 1
	s_barrier
	v_mfma_f32_16x16x32_bf16 v[60:63], v[132:135], v[188:191], v[60:63]
	v_mfma_f32_16x16x32_bf16 v[56:59], v[160:163], v[188:191], v[56:59]
	v_mfma_f32_16x16x32_bf16 v[44:47], v[132:135], v[196:199], v[44:47]
	v_mfma_f32_16x16x32_bf16 v[40:43], v[160:163], v[196:199], v[40:43]
	v_mfma_f32_16x16x32_bf16 v[28:31], v[132:135], v[204:207], v[28:31]
	v_mfma_f32_16x16x32_bf16 v[24:27], v[160:163], v[204:207], v[24:27]
	v_mfma_f32_16x16x32_bf16 v[12:15], v[132:135], v[212:215], v[12:15]
	v_mfma_f32_16x16x32_bf16 v[8:11], v[160:163], v[212:215], v[8:11]
	v_mfma_f32_16x16x32_bf16 v[60:63], v[156:159], v[192:195], v[60:63]
	v_mfma_f32_16x16x32_bf16 v[56:59], v[168:171], v[192:195], v[56:59]
	v_mfma_f32_16x16x32_bf16 v[44:47], v[156:159], v[200:203], v[44:47]
	v_mfma_f32_16x16x32_bf16 v[40:43], v[168:171], v[200:203], v[40:43]
	v_mfma_f32_16x16x32_bf16 v[28:31], v[156:159], v[208:211], v[28:31]
	v_mfma_f32_16x16x32_bf16 v[24:27], v[168:171], v[208:211], v[24:27]
	v_mfma_f32_16x16x32_bf16 v[12:15], v[156:159], v[216:219], v[12:15]
	v_mfma_f32_16x16x32_bf16 v[8:11], v[168:171], v[216:219], v[8:11]
	s_setprio 0
	s_setprio 1
	v_mfma_f32_16x16x32_bf16 v[52:55], v[172:175], v[188:191], v[52:55]
	v_mfma_f32_16x16x32_bf16 v[48:51], v[180:183], v[188:191], v[48:51]
	v_mfma_f32_16x16x32_bf16 v[36:39], v[172:175], v[196:199], v[36:39]
	v_mfma_f32_16x16x32_bf16 v[32:35], v[180:183], v[196:199], v[32:35]
	v_mfma_f32_16x16x32_bf16 v[20:23], v[172:175], v[204:207], v[20:23]
	v_mfma_f32_16x16x32_bf16 v[16:19], v[180:183], v[204:207], v[16:19]
	v_mfma_f32_16x16x32_bf16 v[4:7], v[172:175], v[212:215], v[4:7]
	v_mfma_f32_16x16x32_bf16 v[0:3], v[180:183], v[212:215], v[0:3]
	v_mfma_f32_16x16x32_bf16 v[52:55], v[176:179], v[192:195], v[52:55]
	v_mfma_f32_16x16x32_bf16 v[48:51], v[184:187], v[192:195], v[48:51]
	v_mfma_f32_16x16x32_bf16 v[36:39], v[176:179], v[200:203], v[36:39]
	v_mfma_f32_16x16x32_bf16 v[32:35], v[184:187], v[200:203], v[32:35]
	v_mfma_f32_16x16x32_bf16 v[20:23], v[176:179], v[208:211], v[20:23]
	v_mfma_f32_16x16x32_bf16 v[16:19], v[184:187], v[208:211], v[16:19]
	v_mfma_f32_16x16x32_bf16 v[4:7], v[176:179], v[216:219], v[4:7]
	v_mfma_f32_16x16x32_bf16 v[0:3], v[184:187], v[216:219], v[0:3]
	s_barrier
	s_setprio 0
	s_add_i32 s8, 0, 0x18000
	s_add_i32 s79, 0, 0x1c000
	ds_read_b128 v[132:135], v220 offset:32768
	ds_read_b128 v[156:159], v220 offset:33792
	ds_read_b128 v[160:163], v220 offset:34816
	ds_read_b128 v[168:171], v220 offset:35840
	ds_read_b128 v[172:175], v220 offset:49152
	ds_read_b128 v[176:179], v220 offset:50176
	ds_read_b128 v[180:183], v220 offset:51200
	ds_read_b128 v[184:187], v220 offset:52224
	s_add_u32 s44, s46, 0xb0000
	s_addc_u32 s45, s47, 0
	s_mov_b32 m0, s53
	ds_read_b128 v[188:191], v166 offset:32768
	ds_read_b128 v[192:195], v166 offset:33792
	ds_read_b128 v[196:199], v166 offset:34816
	ds_read_b128 v[200:203], v166 offset:35840
	ds_read_b128 v[204:207], v166 offset:36864
	ds_read_b128 v[208:211], v166 offset:37888
	ds_read_b128 v[212:215], v166 offset:38912
	global_load_lds_dwordx4 v136, s[44:45]
	s_mov_b32 m0, s54
	ds_read_b128 v[216:219], v166 offset:39936
	global_load_lds_dwordx4 v140, s[44:45]
	s_waitcnt vmcnt(8)
	s_waitcnt lgkmcnt(0)
	s_setprio 1
	s_barrier
	v_mfma_f32_16x16x32_bf16 v[124:127], v[132:135], v[188:191], v[124:127]
	v_mfma_f32_16x16x32_bf16 v[120:123], v[160:163], v[188:191], v[120:123]
	v_mfma_f32_16x16x32_bf16 v[108:111], v[132:135], v[196:199], v[108:111]
	v_mfma_f32_16x16x32_bf16 v[104:107], v[160:163], v[196:199], v[104:107]
	v_mfma_f32_16x16x32_bf16 v[92:95], v[132:135], v[204:207], v[92:95]
	v_mfma_f32_16x16x32_bf16 v[88:91], v[160:163], v[204:207], v[88:91]
	v_mfma_f32_16x16x32_bf16 v[76:79], v[132:135], v[212:215], v[76:79]
	v_mfma_f32_16x16x32_bf16 v[72:75], v[160:163], v[212:215], v[72:75]
	v_mfma_f32_16x16x32_bf16 v[124:127], v[156:159], v[192:195], v[124:127]
	v_mfma_f32_16x16x32_bf16 v[120:123], v[168:171], v[192:195], v[120:123]
	v_mfma_f32_16x16x32_bf16 v[108:111], v[156:159], v[200:203], v[108:111]
	v_mfma_f32_16x16x32_bf16 v[104:107], v[168:171], v[200:203], v[104:107]
	v_mfma_f32_16x16x32_bf16 v[92:95], v[156:159], v[208:211], v[92:95]
	v_mfma_f32_16x16x32_bf16 v[88:91], v[168:171], v[208:211], v[88:91]
	v_mfma_f32_16x16x32_bf16 v[76:79], v[156:159], v[216:219], v[76:79]
	v_mfma_f32_16x16x32_bf16 v[72:75], v[168:171], v[216:219], v[72:75]
	s_setprio 0
	s_setprio 1
	v_mfma_f32_16x16x32_bf16 v[116:119], v[172:175], v[188:191], v[116:119]
	v_mfma_f32_16x16x32_bf16 v[112:115], v[180:183], v[188:191], v[112:115]
	v_mfma_f32_16x16x32_bf16 v[100:103], v[172:175], v[196:199], v[100:103]
	v_mfma_f32_16x16x32_bf16 v[96:99], v[180:183], v[196:199], v[96:99]
	v_mfma_f32_16x16x32_bf16 v[84:87], v[172:175], v[204:207], v[84:87]
	v_mfma_f32_16x16x32_bf16 v[80:83], v[180:183], v[204:207], v[80:83]
	v_mfma_f32_16x16x32_bf16 v[68:71], v[172:175], v[212:215], v[68:71]
	v_mfma_f32_16x16x32_bf16 v[64:67], v[180:183], v[212:215], v[64:67]
	v_mfma_f32_16x16x32_bf16 v[116:119], v[176:179], v[192:195], v[116:119]
	v_mfma_f32_16x16x32_bf16 v[112:115], v[184:187], v[192:195], v[112:115]
	v_mfma_f32_16x16x32_bf16 v[100:103], v[176:179], v[200:203], v[100:103]
	v_mfma_f32_16x16x32_bf16 v[96:99], v[184:187], v[200:203], v[96:99]
	v_mfma_f32_16x16x32_bf16 v[84:87], v[176:179], v[208:211], v[84:87]
	v_mfma_f32_16x16x32_bf16 v[80:83], v[184:187], v[208:211], v[80:83]
	v_mfma_f32_16x16x32_bf16 v[68:71], v[176:179], v[216:219], v[68:71]
	v_mfma_f32_16x16x32_bf16 v[64:67], v[184:187], v[216:219], v[64:67]
	s_barrier
	s_setprio 0
	s_add_i32 s8, s8, s50
	s_mov_b32 m0, s8
	ds_read_b128 v[188:191], v166 offset:49152
	ds_read_b128 v[192:195], v166 offset:50176
	ds_read_b128 v[196:199], v166 offset:51200
	global_load_lds_dwordx4 v138, s[40:41]
	s_add_i32 m0, s8, 0x2000
	ds_read_b128 v[200:203], v166 offset:52224
	global_load_lds_dwordx4 v142, s[40:41]
	s_add_u32 s40, s40, 0xb0000
	s_addc_u32 s41, s41, 0
	s_add_i32 s8, s79, s50
	s_mov_b32 m0, s8
	ds_read_b128 v[204:207], v166 offset:53248
	global_load_lds_dwordx4 v138, s[40:41]
	s_add_i32 m0, s8, 0x2000
	ds_read_b128 v[208:211], v166 offset:54272
	global_load_lds_dwordx4 v142, s[40:41]
	s_mov_b32 m0, s60
	ds_read_b128 v[212:215], v166 offset:55296
	global_load_lds_dwordx4 v136, s[38:39]
	s_mov_b32 m0, s61
	ds_read_b128 v[216:219], v166 offset:56320
	global_load_lds_dwordx4 v140, s[38:39]
	s_waitcnt vmcnt(8)
	s_waitcnt lgkmcnt(0)
	s_setprio 1
	s_barrier
	v_mfma_f32_16x16x32_bf16 v[60:63], v[132:135], v[188:191], v[60:63]
	v_mfma_f32_16x16x32_bf16 v[56:59], v[160:163], v[188:191], v[56:59]
	v_mfma_f32_16x16x32_bf16 v[44:47], v[132:135], v[196:199], v[44:47]
	v_mfma_f32_16x16x32_bf16 v[40:43], v[160:163], v[196:199], v[40:43]
	v_mfma_f32_16x16x32_bf16 v[28:31], v[132:135], v[204:207], v[28:31]
	v_mfma_f32_16x16x32_bf16 v[24:27], v[160:163], v[204:207], v[24:27]
	v_mfma_f32_16x16x32_bf16 v[12:15], v[132:135], v[212:215], v[12:15]
	v_mfma_f32_16x16x32_bf16 v[8:11], v[160:163], v[212:215], v[8:11]
	v_mfma_f32_16x16x32_bf16 v[60:63], v[156:159], v[192:195], v[60:63]
	v_mfma_f32_16x16x32_bf16 v[56:59], v[168:171], v[192:195], v[56:59]
	v_mfma_f32_16x16x32_bf16 v[44:47], v[156:159], v[200:203], v[44:47]
	v_mfma_f32_16x16x32_bf16 v[40:43], v[168:171], v[200:203], v[40:43]
	v_mfma_f32_16x16x32_bf16 v[28:31], v[156:159], v[208:211], v[28:31]
	v_mfma_f32_16x16x32_bf16 v[24:27], v[168:171], v[208:211], v[24:27]
	v_mfma_f32_16x16x32_bf16 v[12:15], v[156:159], v[216:219], v[12:15]
	v_mfma_f32_16x16x32_bf16 v[8:11], v[168:171], v[216:219], v[8:11]
	s_setprio 0
	s_setprio 1
	v_mfma_f32_16x16x32_bf16 v[52:55], v[172:175], v[188:191], v[52:55]
	v_mfma_f32_16x16x32_bf16 v[48:51], v[180:183], v[188:191], v[48:51]
	v_mfma_f32_16x16x32_bf16 v[36:39], v[172:175], v[196:199], v[36:39]
	v_mfma_f32_16x16x32_bf16 v[32:35], v[180:183], v[196:199], v[32:35]
	v_mfma_f32_16x16x32_bf16 v[20:23], v[172:175], v[204:207], v[20:23]
	v_mfma_f32_16x16x32_bf16 v[16:19], v[180:183], v[204:207], v[16:19]
	v_mfma_f32_16x16x32_bf16 v[4:7], v[172:175], v[212:215], v[4:7]
	v_mfma_f32_16x16x32_bf16 v[0:3], v[180:183], v[212:215], v[0:3]
	v_mfma_f32_16x16x32_bf16 v[52:55], v[176:179], v[192:195], v[52:55]
	v_mfma_f32_16x16x32_bf16 v[48:51], v[184:187], v[192:195], v[48:51]
	v_mfma_f32_16x16x32_bf16 v[36:39], v[176:179], v[200:203], v[36:39]
	v_mfma_f32_16x16x32_bf16 v[32:35], v[184:187], v[200:203], v[32:35]
	v_mfma_f32_16x16x32_bf16 v[20:23], v[176:179], v[208:211], v[20:23]
	v_mfma_f32_16x16x32_bf16 v[16:19], v[184:187], v[208:211], v[16:19]
	v_mfma_f32_16x16x32_bf16 v[4:7], v[176:179], v[216:219], v[4:7]
	v_mfma_f32_16x16x32_bf16 v[0:3], v[184:187], v[216:219], v[0:3]
	s_barrier
	s_setprio 0
	s_add_i32 s8, s78, 2
	s_add_u32 s36, s36, 0x100
	s_addc_u32 s37, s37, 0
	s_cmp_gt_u32 s78, 41
	s_mov_b32 s78, s8
	s_cbranch_scc1 .LBB0_903

.LBB0_1017:
	s_add_u32 s65, s54, s6
	s_addc_u32 s66, s55, s7
	s_add_u32 s67, s56, s8
	s_addc_u32 s68, s57, s9
	s_ashr_i32 s19, s18, 31
	s_lshl_b64 s[6:7], s[18:19], 19
	s_add_u32 s20, s34, s6
	s_addc_u32 s21, s35, s7
	s_and_b64 s[8:9], s[0:1], exec
	s_cselect_b32 s19, s21, s29
	s_cselect_b32 s69, s20, s28
	s_ashr_i32 s17, s16, 31
	s_lshl_b64 s[8:9], s[16:17], 19
	s_add_u32 s22, s48, s8
	s_addc_u32 s23, s49, s9
	s_and_b64 s[30:31], s[0:1], exec
	s_cselect_b32 s17, s23, s27
	s_cselect_b32 s70, s22, s26
	s_add_u32 s30, s69, 0x80
	s_addc_u32 s31, s19, 0
	s_add_u32 s36, s70, 0x80
	s_addc_u32 s37, s17, 0
	v_lshl_add_u64 v[128:129], s[28:29], 0, v[196:197]
	v_lshl_add_u64 v[130:131], s[28:29], 0, v[198:199]
	s_mov_b32 s71, 0
	s_mov_b64 s[38:39], 0
	v_add_u32_e32 v216, 0x10000, v220
	s_add_u32 s46, s28, s38
	s_addc_u32 s47, s29, s39
	s_mov_b64 s[100:101], s[46:47]
	s_add_u32 s73, s26, s38
	s_addc_u32 s72, s27, s39
	s_add_u32 s40, s46, 0x180
	s_addc_u32 s41, s47, 0
	s_add_u32 s42, s73, 0x180
	s_addc_u32 s43, s72, 0
	s_add_u32 s46, s46, 0x100
	s_addc_u32 s47, s47, 0
	s_add_u32 s44, s73, 0x100
	s_addc_u32 s45, s72, 0
	s_cmpk_eq_i32 s38, 0x700
	s_cselect_b32 s40, s30, s40
	s_cselect_b32 s41, s31, s41
	s_cselect_b32 s42, s36, s42
	s_cselect_b32 s43, s37, s43
	s_cselect_b32 s46, s69, s46
	s_cselect_b32 s47, s19, s47
	s_cselect_b32 s44, s70, s44
	s_cselect_b32 s45, s17, s45
	ds_read_b128 v[132:135], v216
	ds_read_b128 v[136:139], v216 offset:1024
	ds_read_b128 v[140:143], v216 offset:2048
	ds_read_b128 v[144:147], v216 offset:3072
	ds_read_b128 v[148:151], v216 offset:16384
	ds_read_b128 v[152:155], v216 offset:17408
	ds_read_b128 v[156:159], v216 offset:18432
	ds_read_b128 v[160:163], v216 offset:19456
	s_add_i32 m0, s25, 0xc000
	ds_read_b128 v[164:167], v221
	ds_read_b128 v[168:171], v221 offset:1024
	ds_read_b128 v[172:175], v221 offset:2048
	ds_read_b128 v[176:179], v221 offset:3072
	ds_read_b128 v[180:183], v221 offset:4096
	ds_read_b128 v[204:207], v221 offset:5120
	ds_read_b128 v[208:211], v221 offset:6144
	global_load_lds_dwordx4 v196, s[100:101]
	s_add_i32 m0, s25, 0xe000
	ds_read_b128 v[212:215], v221 offset:7168
	global_load_lds_dwordx4 v198, s[100:101]
	s_waitcnt vmcnt(8)
	s_waitcnt lgkmcnt(0)
	s_setprio 1
	s_barrier
	v_mfma_f32_16x16x32_bf16 v[124:127], v[132:135], v[164:167], 0
	v_mfma_f32_16x16x32_bf16 v[120:123], v[140:143], v[164:167], 0
	v_mfma_f32_16x16x32_bf16 v[108:111], v[132:135], v[172:175], 0
	v_mfma_f32_16x16x32_bf16 v[104:107], v[140:143], v[172:175], 0
	v_mfma_f32_16x16x32_bf16 v[92:95], v[132:135], v[180:183], 0
	v_mfma_f32_16x16x32_bf16 v[88:91], v[140:143], v[180:183], 0
	v_mfma_f32_16x16x32_bf16 v[76:79], v[132:135], v[208:211], 0
	v_mfma_f32_16x16x32_bf16 v[72:75], v[140:143], v[208:211], 0
	v_mfma_f32_16x16x32_bf16 v[124:127], v[136:139], v[168:171], v[124:127]
	v_mfma_f32_16x16x32_bf16 v[120:123], v[144:147], v[168:171], v[120:123]
	v_mfma_f32_16x16x32_bf16 v[108:111], v[136:139], v[176:179], v[108:111]
	v_mfma_f32_16x16x32_bf16 v[104:107], v[144:147], v[176:179], v[104:107]
	v_mfma_f32_16x16x32_bf16 v[92:95], v[136:139], v[204:207], v[92:95]
	v_mfma_f32_16x16x32_bf16 v[88:91], v[144:147], v[204:207], v[88:91]
	v_mfma_f32_16x16x32_bf16 v[76:79], v[136:139], v[212:215], v[76:79]
	v_mfma_f32_16x16x32_bf16 v[72:75], v[144:147], v[212:215], v[72:75]
	s_setprio 0
	s_setprio 1
	v_mfma_f32_16x16x32_bf16 v[116:119], v[148:151], v[164:167], 0
	v_mfma_f32_16x16x32_bf16 v[112:115], v[156:159], v[164:167], 0
	v_mfma_f32_16x16x32_bf16 v[100:103], v[148:151], v[172:175], 0
	v_mfma_f32_16x16x32_bf16 v[96:99], v[156:159], v[172:175], 0
	v_mfma_f32_16x16x32_bf16 v[84:87], v[148:151], v[180:183], 0
	v_mfma_f32_16x16x32_bf16 v[80:83], v[156:159], v[180:183], 0
	v_mfma_f32_16x16x32_bf16 v[68:71], v[148:151], v[208:211], 0
	v_mfma_f32_16x16x32_bf16 v[64:67], v[156:159], v[208:211], 0
	v_mfma_f32_16x16x32_bf16 v[116:119], v[152:155], v[168:171], v[116:119]
	v_mfma_f32_16x16x32_bf16 v[112:115], v[160:163], v[168:171], v[112:115]
	v_mfma_f32_16x16x32_bf16 v[100:103], v[152:155], v[176:179], v[100:103]
	v_mfma_f32_16x16x32_bf16 v[96:99], v[160:163], v[176:179], v[96:99]
	v_mfma_f32_16x16x32_bf16 v[84:87], v[152:155], v[204:207], v[84:87]
	v_mfma_f32_16x16x32_bf16 v[80:83], v[160:163], v[204:207], v[80:83]
	v_mfma_f32_16x16x32_bf16 v[68:71], v[152:155], v[212:215], v[68:71]
	v_mfma_f32_16x16x32_bf16 v[64:67], v[160:163], v[212:215], v[64:67]
	s_barrier
	s_setprio 0
	s_add_i32 s10, s61, s50
	s_mov_b32 m0, s10
	ds_read_b128 v[164:167], v221 offset:16384
	ds_read_b128 v[168:171], v221 offset:17408
	ds_read_b128 v[172:175], v221 offset:18432
	global_load_lds_dwordx4 v186, s[44:45]
	s_add_i32 m0, s10, 0x2000
	ds_read_b128 v[176:179], v221 offset:19456
	global_load_lds_dwordx4 v190, s[44:45]
	s_add_u32 s44, s44, 0x40000
	s_addc_u32 s45, s45, 0
	s_add_i32 s10, s62, s50
	s_mov_b32 m0, s10
	ds_read_b128 v[180:183], v221 offset:20480
	global_load_lds_dwordx4 v186, s[44:45]
	s_add_i32 m0, s10, 0x2000
	ds_read_b128 v[204:207], v221 offset:21504
	global_load_lds_dwordx4 v190, s[44:45]
	s_mov_b32 m0, s25
	ds_read_b128 v[208:211], v221 offset:22528
	global_load_lds_dwordx4 v184, s[46:47]
	s_mov_b32 m0, s51
	ds_read_b128 v[212:215], v221 offset:23552
	global_load_lds_dwordx4 v188, s[46:47]
	s_waitcnt vmcnt(8)
	s_waitcnt lgkmcnt(0)
	s_setprio 1
	s_barrier
	v_mfma_f32_16x16x32_bf16 v[60:63], v[132:135], v[164:167], 0
	v_mfma_f32_16x16x32_bf16 v[56:59], v[140:143], v[164:167], 0
	v_mfma_f32_16x16x32_bf16 v[44:47], v[132:135], v[172:175], 0
	v_mfma_f32_16x16x32_bf16 v[40:43], v[140:143], v[172:175], 0
	v_mfma_f32_16x16x32_bf16 v[28:31], v[132:135], v[180:183], 0
	v_mfma_f32_16x16x32_bf16 v[24:27], v[140:143], v[180:183], 0
	v_mfma_f32_16x16x32_bf16 v[12:15], v[132:135], v[208:211], 0
	v_mfma_f32_16x16x32_bf16 v[8:11], v[140:143], v[208:211], 0
	v_mfma_f32_16x16x32_bf16 v[60:63], v[136:139], v[168:171], v[60:63]
	v_mfma_f32_16x16x32_bf16 v[56:59], v[144:147], v[168:171], v[56:59]
	v_mfma_f32_16x16x32_bf16 v[44:47], v[136:139], v[176:179], v[44:47]
	v_mfma_f32_16x16x32_bf16 v[40:43], v[144:147], v[176:179], v[40:43]
	v_mfma_f32_16x16x32_bf16 v[28:31], v[136:139], v[204:207], v[28:31]
	v_mfma_f32_16x16x32_bf16 v[24:27], v[144:147], v[204:207], v[24:27]
	v_mfma_f32_16x16x32_bf16 v[12:15], v[136:139], v[212:215], v[12:15]
	v_mfma_f32_16x16x32_bf16 v[8:11], v[144:147], v[212:215], v[8:11]
	s_setprio 0
	s_setprio 1
	v_mfma_f32_16x16x32_bf16 v[52:55], v[148:151], v[164:167], 0
	v_mfma_f32_16x16x32_bf16 v[48:51], v[156:159], v[164:167], 0
	v_mfma_f32_16x16x32_bf16 v[36:39], v[148:151], v[172:175], 0
	v_mfma_f32_16x16x32_bf16 v[32:35], v[156:159], v[172:175], 0
	v_mfma_f32_16x16x32_bf16 v[20:23], v[148:151], v[180:183], 0
	v_mfma_f32_16x16x32_bf16 v[16:19], v[156:159], v[180:183], 0
	v_mfma_f32_16x16x32_bf16 v[4:7], v[148:151], v[208:211], 0
	v_mfma_f32_16x16x32_bf16 v[0:3], v[156:159], v[208:211], 0
	v_mfma_f32_16x16x32_bf16 v[52:55], v[152:155], v[168:171], v[52:55]
	v_mfma_f32_16x16x32_bf16 v[48:51], v[160:163], v[168:171], v[48:51]
	v_mfma_f32_16x16x32_bf16 v[36:39], v[152:155], v[176:179], v[36:39]
	v_mfma_f32_16x16x32_bf16 v[32:35], v[160:163], v[176:179], v[32:35]
	v_mfma_f32_16x16x32_bf16 v[20:23], v[152:155], v[204:207], v[20:23]
	v_mfma_f32_16x16x32_bf16 v[16:19], v[160:163], v[204:207], v[16:19]
	v_mfma_f32_16x16x32_bf16 v[4:7], v[152:155], v[212:215], v[4:7]
	v_mfma_f32_16x16x32_bf16 v[0:3], v[160:163], v[212:215], v[0:3]
	s_barrier
	s_setprio 0
	s_add_i32 s10, 0, 0x18000
	s_add_i32 s72, 0, 0x1c000
	ds_read_b128 v[132:135], v216 offset:32768
	ds_read_b128 v[136:139], v216 offset:33792
	ds_read_b128 v[140:143], v216 offset:34816
	ds_read_b128 v[144:147], v216 offset:35840
	ds_read_b128 v[148:151], v216 offset:49152
	ds_read_b128 v[152:155], v216 offset:50176
	ds_read_b128 v[156:159], v216 offset:51200
	ds_read_b128 v[160:163], v216 offset:52224
	s_add_u32 s44, s46, 0x40000
	s_addc_u32 s45, s47, 0
	s_mov_b32 m0, s52
	ds_read_b128 v[164:167], v221 offset:32768
	ds_read_b128 v[168:171], v221 offset:33792
	ds_read_b128 v[172:175], v221 offset:34816
	ds_read_b128 v[176:179], v221 offset:35840
	ds_read_b128 v[180:183], v221 offset:36864
	ds_read_b128 v[204:207], v221 offset:37888
	ds_read_b128 v[208:211], v221 offset:38912
	global_load_lds_dwordx4 v184, s[44:45]
	s_mov_b32 m0, s53
	ds_read_b128 v[212:215], v221 offset:39936
	global_load_lds_dwordx4 v188, s[44:45]
	s_waitcnt vmcnt(8)
	s_waitcnt lgkmcnt(0)
	s_setprio 1
	s_barrier
	v_mfma_f32_16x16x32_bf16 v[124:127], v[132:135], v[164:167], v[124:127]
	v_mfma_f32_16x16x32_bf16 v[120:123], v[140:143], v[164:167], v[120:123]
	v_mfma_f32_16x16x32_bf16 v[108:111], v[132:135], v[172:175], v[108:111]
	v_mfma_f32_16x16x32_bf16 v[104:107], v[140:143], v[172:175], v[104:107]
	v_mfma_f32_16x16x32_bf16 v[92:95], v[132:135], v[180:183], v[92:95]
	v_mfma_f32_16x16x32_bf16 v[88:91], v[140:143], v[180:183], v[88:91]
	v_mfma_f32_16x16x32_bf16 v[76:79], v[132:135], v[208:211], v[76:79]
	v_mfma_f32_16x16x32_bf16 v[72:75], v[140:143], v[208:211], v[72:75]
	v_mfma_f32_16x16x32_bf16 v[124:127], v[136:139], v[168:171], v[124:127]
	v_mfma_f32_16x16x32_bf16 v[120:123], v[144:147], v[168:171], v[120:123]
	v_mfma_f32_16x16x32_bf16 v[108:111], v[136:139], v[176:179], v[108:111]
	v_mfma_f32_16x16x32_bf16 v[104:107], v[144:147], v[176:179], v[104:107]
	v_mfma_f32_16x16x32_bf16 v[92:95], v[136:139], v[204:207], v[92:95]
	v_mfma_f32_16x16x32_bf16 v[88:91], v[144:147], v[204:207], v[88:91]
	v_mfma_f32_16x16x32_bf16 v[76:79], v[136:139], v[212:215], v[76:79]
	v_mfma_f32_16x16x32_bf16 v[72:75], v[144:147], v[212:215], v[72:75]
	s_setprio 0
	s_setprio 1
	v_mfma_f32_16x16x32_bf16 v[116:119], v[148:151], v[164:167], v[116:119]
	v_mfma_f32_16x16x32_bf16 v[112:115], v[156:159], v[164:167], v[112:115]
	v_mfma_f32_16x16x32_bf16 v[100:103], v[148:151], v[172:175], v[100:103]
	v_mfma_f32_16x16x32_bf16 v[96:99], v[156:159], v[172:175], v[96:99]
	v_mfma_f32_16x16x32_bf16 v[84:87], v[148:151], v[180:183], v[84:87]
	v_mfma_f32_16x16x32_bf16 v[80:83], v[156:159], v[180:183], v[80:83]
	v_mfma_f32_16x16x32_bf16 v[68:71], v[148:151], v[208:211], v[68:71]
	v_mfma_f32_16x16x32_bf16 v[64:67], v[156:159], v[208:211], v[64:67]
	v_mfma_f32_16x16x32_bf16 v[116:119], v[152:155], v[168:171], v[116:119]
	v_mfma_f32_16x16x32_bf16 v[112:115], v[160:163], v[168:171], v[112:115]
	v_mfma_f32_16x16x32_bf16 v[100:103], v[152:155], v[176:179], v[100:103]
	v_mfma_f32_16x16x32_bf16 v[96:99], v[160:163], v[176:179], v[96:99]
	v_mfma_f32_16x16x32_bf16 v[84:87], v[152:155], v[204:207], v[84:87]
	v_mfma_f32_16x16x32_bf16 v[80:83], v[160:163], v[204:207], v[80:83]
	v_mfma_f32_16x16x32_bf16 v[68:71], v[152:155], v[212:215], v[68:71]
	v_mfma_f32_16x16x32_bf16 v[64:67], v[160:163], v[212:215], v[64:67]
	s_barrier
	s_setprio 0
	s_add_i32 s10, s10, s50
	s_mov_b32 m0, s10
	ds_read_b128 v[164:167], v221 offset:49152
	ds_read_b128 v[168:171], v221 offset:50176
	ds_read_b128 v[172:175], v221 offset:51200
	global_load_lds_dwordx4 v186, s[42:43]
	s_add_i32 m0, s10, 0x2000
	ds_read_b128 v[176:179], v221 offset:52224
	global_load_lds_dwordx4 v190, s[42:43]
	s_add_u32 s42, s42, 0x40000
	s_addc_u32 s43, s43, 0
	s_add_i32 s10, s72, s50
	s_mov_b32 m0, s10
	ds_read_b128 v[180:183], v221 offset:53248
	global_load_lds_dwordx4 v186, s[42:43]
	s_add_i32 m0, s10, 0x2000
	ds_read_b128 v[204:207], v221 offset:54272
	global_load_lds_dwordx4 v190, s[42:43]
	s_mov_b32 m0, s58
	ds_read_b128 v[208:211], v221 offset:55296
	global_load_lds_dwordx4 v184, s[40:41]
	s_mov_b32 m0, s59
	ds_read_b128 v[212:215], v221 offset:56320
	global_load_lds_dwordx4 v188, s[40:41]
	s_waitcnt vmcnt(8)
	s_waitcnt lgkmcnt(0)
	s_setprio 1
	s_barrier
	v_mfma_f32_16x16x32_bf16 v[60:63], v[132:135], v[164:167], v[60:63]
	v_mfma_f32_16x16x32_bf16 v[56:59], v[140:143], v[164:167], v[56:59]
	v_mfma_f32_16x16x32_bf16 v[44:47], v[132:135], v[172:175], v[44:47]
	v_mfma_f32_16x16x32_bf16 v[40:43], v[140:143], v[172:175], v[40:43]
	v_mfma_f32_16x16x32_bf16 v[28:31], v[132:135], v[180:183], v[28:31]
	v_mfma_f32_16x16x32_bf16 v[24:27], v[140:143], v[180:183], v[24:27]
	v_mfma_f32_16x16x32_bf16 v[12:15], v[132:135], v[208:211], v[12:15]
	v_mfma_f32_16x16x32_bf16 v[8:11], v[140:143], v[208:211], v[8:11]
	v_mfma_f32_16x16x32_bf16 v[60:63], v[136:139], v[168:171], v[60:63]
	v_mfma_f32_16x16x32_bf16 v[56:59], v[144:147], v[168:171], v[56:59]
	v_mfma_f32_16x16x32_bf16 v[44:47], v[136:139], v[176:179], v[44:47]
	v_mfma_f32_16x16x32_bf16 v[40:43], v[144:147], v[176:179], v[40:43]
	v_mfma_f32_16x16x32_bf16 v[28:31], v[136:139], v[204:207], v[28:31]
	v_mfma_f32_16x16x32_bf16 v[24:27], v[144:147], v[204:207], v[24:27]
	v_mfma_f32_16x16x32_bf16 v[12:15], v[136:139], v[212:215], v[12:15]
	v_mfma_f32_16x16x32_bf16 v[8:11], v[144:147], v[212:215], v[8:11]
	s_setprio 0
	s_setprio 1
	v_mfma_f32_16x16x32_bf16 v[52:55], v[148:151], v[164:167], v[52:55]
	v_mfma_f32_16x16x32_bf16 v[48:51], v[156:159], v[164:167], v[48:51]
	v_mfma_f32_16x16x32_bf16 v[36:39], v[148:151], v[172:175], v[36:39]
	v_mfma_f32_16x16x32_bf16 v[32:35], v[156:159], v[172:175], v[32:35]
	v_mfma_f32_16x16x32_bf16 v[20:23], v[148:151], v[180:183], v[20:23]
	v_mfma_f32_16x16x32_bf16 v[16:19], v[156:159], v[180:183], v[16:19]
	v_mfma_f32_16x16x32_bf16 v[4:7], v[148:151], v[208:211], v[4:7]
	v_mfma_f32_16x16x32_bf16 v[0:3], v[156:159], v[208:211], v[0:3]
	v_mfma_f32_16x16x32_bf16 v[52:55], v[152:155], v[168:171], v[52:55]
	v_mfma_f32_16x16x32_bf16 v[48:51], v[160:163], v[168:171], v[48:51]
	v_mfma_f32_16x16x32_bf16 v[36:39], v[152:155], v[176:179], v[36:39]
	v_mfma_f32_16x16x32_bf16 v[32:35], v[160:163], v[176:179], v[32:35]
	v_mfma_f32_16x16x32_bf16 v[20:23], v[152:155], v[204:207], v[20:23]
	v_mfma_f32_16x16x32_bf16 v[16:19], v[160:163], v[204:207], v[16:19]
	v_mfma_f32_16x16x32_bf16 v[4:7], v[152:155], v[212:215], v[4:7]
	v_mfma_f32_16x16x32_bf16 v[0:3], v[160:163], v[212:215], v[0:3]
	s_barrier
	s_setprio 0
	s_add_i32 s10, s71, 2
	s_add_u32 s38, s38, 0x100
	s_addc_u32 s39, s39, 0
	s_cmp_gt_u32 s71, 13
	s_mov_b32 s71, s10
	s_cbranch_scc1 .LBB0_1025
	s_branch .LBB0_1019
.LBB0_1018:
	ds_read_b128 v[132:135], v216
	ds_read_b128 v[136:139], v216 offset:1024
	ds_read_b128 v[140:143], v216 offset:2048
	ds_read_b128 v[144:147], v216 offset:3072
	ds_read_b128 v[148:151], v216 offset:16384
	ds_read_b128 v[152:155], v216 offset:17408
	ds_read_b128 v[156:159], v216 offset:18432
	ds_read_b128 v[160:163], v216 offset:19456
	s_add_i32 m0, s25, 0xc000
	ds_read_b128 v[164:167], v221
	ds_read_b128 v[168:171], v221 offset:1024
	ds_read_b128 v[172:175], v221 offset:2048
	ds_read_b128 v[176:179], v221 offset:3072
	ds_read_b128 v[180:183], v221 offset:4096
	ds_read_b128 v[204:207], v221 offset:5120
	ds_read_b128 v[208:211], v221 offset:6144
	global_load_lds_dwordx4 v196, s[100:101]
	s_add_i32 m0, s25, 0xe000
	ds_read_b128 v[212:215], v221 offset:7168
	global_load_lds_dwordx4 v198, s[100:101]
	s_waitcnt vmcnt(8)
	s_waitcnt lgkmcnt(0)
	s_setprio 1
	s_barrier
	v_mfma_f32_16x16x32_bf16 v[124:127], v[132:135], v[164:167], v[124:127]
	v_mfma_f32_16x16x32_bf16 v[120:123], v[140:143], v[164:167], v[120:123]
	v_mfma_f32_16x16x32_bf16 v[108:111], v[132:135], v[172:175], v[108:111]
	v_mfma_f32_16x16x32_bf16 v[104:107], v[140:143], v[172:175], v[104:107]
	v_mfma_f32_16x16x32_bf16 v[92:95], v[132:135], v[180:183], v[92:95]
	v_mfma_f32_16x16x32_bf16 v[88:91], v[140:143], v[180:183], v[88:91]
	v_mfma_f32_16x16x32_bf16 v[76:79], v[132:135], v[208:211], v[76:79]
	v_mfma_f32_16x16x32_bf16 v[72:75], v[140:143], v[208:211], v[72:75]
	v_mfma_f32_16x16x32_bf16 v[124:127], v[136:139], v[168:171], v[124:127]
	v_mfma_f32_16x16x32_bf16 v[120:123], v[144:147], v[168:171], v[120:123]
	v_mfma_f32_16x16x32_bf16 v[108:111], v[136:139], v[176:179], v[108:111]
	v_mfma_f32_16x16x32_bf16 v[104:107], v[144:147], v[176:179], v[104:107]
	v_mfma_f32_16x16x32_bf16 v[92:95], v[136:139], v[204:207], v[92:95]
	v_mfma_f32_16x16x32_bf16 v[88:91], v[144:147], v[204:207], v[88:91]
	v_mfma_f32_16x16x32_bf16 v[76:79], v[136:139], v[212:215], v[76:79]
	v_mfma_f32_16x16x32_bf16 v[72:75], v[144:147], v[212:215], v[72:75]
	s_setprio 0
	s_setprio 1
	v_mfma_f32_16x16x32_bf16 v[116:119], v[148:151], v[164:167], v[116:119]
	v_mfma_f32_16x16x32_bf16 v[112:115], v[156:159], v[164:167], v[112:115]
	v_mfma_f32_16x16x32_bf16 v[100:103], v[148:151], v[172:175], v[100:103]
	v_mfma_f32_16x16x32_bf16 v[96:99], v[156:159], v[172:175], v[96:99]
	v_mfma_f32_16x16x32_bf16 v[84:87], v[148:151], v[180:183], v[84:87]
	v_mfma_f32_16x16x32_bf16 v[80:83], v[156:159], v[180:183], v[80:83]
	v_mfma_f32_16x16x32_bf16 v[68:71], v[148:151], v[208:211], v[68:71]
	v_mfma_f32_16x16x32_bf16 v[64:67], v[156:159], v[208:211], v[64:67]
	v_mfma_f32_16x16x32_bf16 v[116:119], v[152:155], v[168:171], v[116:119]
	v_mfma_f32_16x16x32_bf16 v[112:115], v[160:163], v[168:171], v[112:115]
	v_mfma_f32_16x16x32_bf16 v[100:103], v[152:155], v[176:179], v[100:103]
	v_mfma_f32_16x16x32_bf16 v[96:99], v[160:163], v[176:179], v[96:99]
	v_mfma_f32_16x16x32_bf16 v[84:87], v[152:155], v[204:207], v[84:87]
	v_mfma_f32_16x16x32_bf16 v[80:83], v[160:163], v[204:207], v[80:83]
	v_mfma_f32_16x16x32_bf16 v[68:71], v[152:155], v[212:215], v[68:71]
	v_mfma_f32_16x16x32_bf16 v[64:67], v[160:163], v[212:215], v[64:67]
	s_barrier
	s_setprio 0
	s_add_i32 s10, s61, s50
	s_mov_b32 m0, s10
	ds_read_b128 v[164:167], v221 offset:16384
	ds_read_b128 v[168:171], v221 offset:17408
	ds_read_b128 v[172:175], v221 offset:18432
	global_load_lds_dwordx4 v186, s[44:45]
	s_add_i32 m0, s10, 0x2000
	ds_read_b128 v[176:179], v221 offset:19456
	global_load_lds_dwordx4 v190, s[44:45]
	s_add_u32 s44, s44, 0x40000
	s_addc_u32 s45, s45, 0
	s_add_i32 s10, s62, s50
	s_mov_b32 m0, s10
	ds_read_b128 v[180:183], v221 offset:20480
	global_load_lds_dwordx4 v186, s[44:45]
	s_add_i32 m0, s10, 0x2000
	ds_read_b128 v[204:207], v221 offset:21504
	global_load_lds_dwordx4 v190, s[44:45]
	s_mov_b32 m0, s25
	ds_read_b128 v[208:211], v221 offset:22528
	global_load_lds_dwordx4 v184, s[46:47]
	s_mov_b32 m0, s51
	ds_read_b128 v[212:215], v221 offset:23552
	global_load_lds_dwordx4 v188, s[46:47]
	s_waitcnt vmcnt(8)
	s_waitcnt lgkmcnt(0)
	s_setprio 1
	s_barrier
	v_mfma_f32_16x16x32_bf16 v[60:63], v[132:135], v[164:167], v[60:63]
	v_mfma_f32_16x16x32_bf16 v[56:59], v[140:143], v[164:167], v[56:59]
	v_mfma_f32_16x16x32_bf16 v[44:47], v[132:135], v[172:175], v[44:47]
	v_mfma_f32_16x16x32_bf16 v[40:43], v[140:143], v[172:175], v[40:43]
	v_mfma_f32_16x16x32_bf16 v[28:31], v[132:135], v[180:183], v[28:31]
	v_mfma_f32_16x16x32_bf16 v[24:27], v[140:143], v[180:183], v[24:27]
	v_mfma_f32_16x16x32_bf16 v[12:15], v[132:135], v[208:211], v[12:15]
	v_mfma_f32_16x16x32_bf16 v[8:11], v[140:143], v[208:211], v[8:11]
	v_mfma_f32_16x16x32_bf16 v[60:63], v[136:139], v[168:171], v[60:63]
	v_mfma_f32_16x16x32_bf16 v[56:59], v[144:147], v[168:171], v[56:59]
	v_mfma_f32_16x16x32_bf16 v[44:47], v[136:139], v[176:179], v[44:47]
	v_mfma_f32_16x16x32_bf16 v[40:43], v[144:147], v[176:179], v[40:43]
	v_mfma_f32_16x16x32_bf16 v[28:31], v[136:139], v[204:207], v[28:31]
	v_mfma_f32_16x16x32_bf16 v[24:27], v[144:147], v[204:207], v[24:27]
	v_mfma_f32_16x16x32_bf16 v[12:15], v[136:139], v[212:215], v[12:15]
	v_mfma_f32_16x16x32_bf16 v[8:11], v[144:147], v[212:215], v[8:11]
	s_setprio 0
	s_setprio 1
	v_mfma_f32_16x16x32_bf16 v[52:55], v[148:151], v[164:167], v[52:55]
	v_mfma_f32_16x16x32_bf16 v[48:51], v[156:159], v[164:167], v[48:51]
	v_mfma_f32_16x16x32_bf16 v[36:39], v[148:151], v[172:175], v[36:39]
	v_mfma_f32_16x16x32_bf16 v[32:35], v[156:159], v[172:175], v[32:35]
	v_mfma_f32_16x16x32_bf16 v[20:23], v[148:151], v[180:183], v[20:23]
	v_mfma_f32_16x16x32_bf16 v[16:19], v[156:159], v[180:183], v[16:19]
	v_mfma_f32_16x16x32_bf16 v[4:7], v[148:151], v[208:211], v[4:7]
	v_mfma_f32_16x16x32_bf16 v[0:3], v[156:159], v[208:211], v[0:3]
	v_mfma_f32_16x16x32_bf16 v[52:55], v[152:155], v[168:171], v[52:55]
	v_mfma_f32_16x16x32_bf16 v[48:51], v[160:163], v[168:171], v[48:51]
	v_mfma_f32_16x16x32_bf16 v[36:39], v[152:155], v[176:179], v[36:39]
	v_mfma_f32_16x16x32_bf16 v[32:35], v[160:163], v[176:179], v[32:35]
	v_mfma_f32_16x16x32_bf16 v[20:23], v[152:155], v[204:207], v[20:23]
	v_mfma_f32_16x16x32_bf16 v[16:19], v[160:163], v[204:207], v[16:19]
	v_mfma_f32_16x16x32_bf16 v[4:7], v[152:155], v[212:215], v[4:7]
	v_mfma_f32_16x16x32_bf16 v[0:3], v[160:163], v[212:215], v[0:3]
	s_barrier
	s_setprio 0
	s_add_i32 s10, 0, 0x18000
	s_add_i32 s72, 0, 0x1c000
	ds_read_b128 v[132:135], v216 offset:32768
	ds_read_b128 v[136:139], v216 offset:33792
	ds_read_b128 v[140:143], v216 offset:34816
	ds_read_b128 v[144:147], v216 offset:35840
	ds_read_b128 v[148:151], v216 offset:49152
	ds_read_b128 v[152:155], v216 offset:50176
	ds_read_b128 v[156:159], v216 offset:51200
	ds_read_b128 v[160:163], v216 offset:52224
	s_add_u32 s44, s46, 0x40000
	s_addc_u32 s45, s47, 0
	s_mov_b32 m0, s52
	ds_read_b128 v[164:167], v221 offset:32768
	ds_read_b128 v[168:171], v221 offset:33792
	ds_read_b128 v[172:175], v221 offset:34816
	ds_read_b128 v[176:179], v221 offset:35840
	ds_read_b128 v[180:183], v221 offset:36864
	ds_read_b128 v[204:207], v221 offset:37888
	ds_read_b128 v[208:211], v221 offset:38912
	global_load_lds_dwordx4 v184, s[44:45]
	s_mov_b32 m0, s53
	ds_read_b128 v[212:215], v221 offset:39936
	global_load_lds_dwordx4 v188, s[44:45]
	s_waitcnt vmcnt(8)
	s_waitcnt lgkmcnt(0)
	s_setprio 1
	s_barrier
	v_mfma_f32_16x16x32_bf16 v[124:127], v[132:135], v[164:167], v[124:127]
	v_mfma_f32_16x16x32_bf16 v[120:123], v[140:143], v[164:167], v[120:123]
	v_mfma_f32_16x16x32_bf16 v[108:111], v[132:135], v[172:175], v[108:111]
	v_mfma_f32_16x16x32_bf16 v[104:107], v[140:143], v[172:175], v[104:107]
	v_mfma_f32_16x16x32_bf16 v[92:95], v[132:135], v[180:183], v[92:95]
	v_mfma_f32_16x16x32_bf16 v[88:91], v[140:143], v[180:183], v[88:91]
	v_mfma_f32_16x16x32_bf16 v[76:79], v[132:135], v[208:211], v[76:79]
	v_mfma_f32_16x16x32_bf16 v[72:75], v[140:143], v[208:211], v[72:75]
	v_mfma_f32_16x16x32_bf16 v[124:127], v[136:139], v[168:171], v[124:127]
	v_mfma_f32_16x16x32_bf16 v[120:123], v[144:147], v[168:171], v[120:123]
	v_mfma_f32_16x16x32_bf16 v[108:111], v[136:139], v[176:179], v[108:111]
	v_mfma_f32_16x16x32_bf16 v[104:107], v[144:147], v[176:179], v[104:107]
	v_mfma_f32_16x16x32_bf16 v[92:95], v[136:139], v[204:207], v[92:95]
	v_mfma_f32_16x16x32_bf16 v[88:91], v[144:147], v[204:207], v[88:91]
	v_mfma_f32_16x16x32_bf16 v[76:79], v[136:139], v[212:215], v[76:79]
	v_mfma_f32_16x16x32_bf16 v[72:75], v[144:147], v[212:215], v[72:75]
	s_setprio 0
	s_setprio 1
	v_mfma_f32_16x16x32_bf16 v[116:119], v[148:151], v[164:167], v[116:119]
	v_mfma_f32_16x16x32_bf16 v[112:115], v[156:159], v[164:167], v[112:115]
	v_mfma_f32_16x16x32_bf16 v[100:103], v[148:151], v[172:175], v[100:103]
	v_mfma_f32_16x16x32_bf16 v[96:99], v[156:159], v[172:175], v[96:99]
	v_mfma_f32_16x16x32_bf16 v[84:87], v[148:151], v[180:183], v[84:87]
	v_mfma_f32_16x16x32_bf16 v[80:83], v[156:159], v[180:183], v[80:83]
	v_mfma_f32_16x16x32_bf16 v[68:71], v[148:151], v[208:211], v[68:71]
	v_mfma_f32_16x16x32_bf16 v[64:67], v[156:159], v[208:211], v[64:67]
	v_mfma_f32_16x16x32_bf16 v[116:119], v[152:155], v[168:171], v[116:119]
	v_mfma_f32_16x16x32_bf16 v[112:115], v[160:163], v[168:171], v[112:115]
	v_mfma_f32_16x16x32_bf16 v[100:103], v[152:155], v[176:179], v[100:103]
	v_mfma_f32_16x16x32_bf16 v[96:99], v[160:163], v[176:179], v[96:99]
	v_mfma_f32_16x16x32_bf16 v[84:87], v[152:155], v[204:207], v[84:87]
	v_mfma_f32_16x16x32_bf16 v[80:83], v[160:163], v[204:207], v[80:83]
	v_mfma_f32_16x16x32_bf16 v[68:71], v[152:155], v[212:215], v[68:71]
	v_mfma_f32_16x16x32_bf16 v[64:67], v[160:163], v[212:215], v[64:67]
	s_barrier
	s_setprio 0
	s_add_i32 s10, s10, s50
	s_mov_b32 m0, s10
	ds_read_b128 v[164:167], v221 offset:49152
	ds_read_b128 v[168:171], v221 offset:50176
	ds_read_b128 v[172:175], v221 offset:51200
	global_load_lds_dwordx4 v186, s[42:43]
	s_add_i32 m0, s10, 0x2000
	ds_read_b128 v[176:179], v221 offset:52224
	global_load_lds_dwordx4 v190, s[42:43]
	s_add_u32 s42, s42, 0x40000
	s_addc_u32 s43, s43, 0
	s_add_i32 s10, s72, s50
	s_mov_b32 m0, s10
	ds_read_b128 v[180:183], v221 offset:53248
	global_load_lds_dwordx4 v186, s[42:43]
	s_add_i32 m0, s10, 0x2000
	ds_read_b128 v[204:207], v221 offset:54272
	global_load_lds_dwordx4 v190, s[42:43]
	s_mov_b32 m0, s58
	ds_read_b128 v[208:211], v221 offset:55296
	global_load_lds_dwordx4 v184, s[40:41]
	s_mov_b32 m0, s59
	ds_read_b128 v[212:215], v221 offset:56320
	global_load_lds_dwordx4 v188, s[40:41]
	s_waitcnt vmcnt(8)
	s_waitcnt lgkmcnt(0)
	s_setprio 1
	s_barrier
	v_mfma_f32_16x16x32_bf16 v[60:63], v[132:135], v[164:167], v[60:63]
	v_mfma_f32_16x16x32_bf16 v[56:59], v[140:143], v[164:167], v[56:59]
	v_mfma_f32_16x16x32_bf16 v[44:47], v[132:135], v[172:175], v[44:47]
	v_mfma_f32_16x16x32_bf16 v[40:43], v[140:143], v[172:175], v[40:43]
	v_mfma_f32_16x16x32_bf16 v[28:31], v[132:135], v[180:183], v[28:31]
	v_mfma_f32_16x16x32_bf16 v[24:27], v[140:143], v[180:183], v[24:27]
	v_mfma_f32_16x16x32_bf16 v[12:15], v[132:135], v[208:211], v[12:15]
	v_mfma_f32_16x16x32_bf16 v[8:11], v[140:143], v[208:211], v[8:11]
	v_mfma_f32_16x16x32_bf16 v[60:63], v[136:139], v[168:171], v[60:63]
	v_mfma_f32_16x16x32_bf16 v[56:59], v[144:147], v[168:171], v[56:59]
	v_mfma_f32_16x16x32_bf16 v[44:47], v[136:139], v[176:179], v[44:47]
	v_mfma_f32_16x16x32_bf16 v[40:43], v[144:147], v[176:179], v[40:43]
	v_mfma_f32_16x16x32_bf16 v[28:31], v[136:139], v[204:207], v[28:31]
	v_mfma_f32_16x16x32_bf16 v[24:27], v[144:147], v[204:207], v[24:27]
	v_mfma_f32_16x16x32_bf16 v[12:15], v[136:139], v[212:215], v[12:15]
	v_mfma_f32_16x16x32_bf16 v[8:11], v[144:147], v[212:215], v[8:11]
	s_setprio 0
	s_setprio 1
	v_mfma_f32_16x16x32_bf16 v[52:55], v[148:151], v[164:167], v[52:55]
	v_mfma_f32_16x16x32_bf16 v[48:51], v[156:159], v[164:167], v[48:51]
	v_mfma_f32_16x16x32_bf16 v[36:39], v[148:151], v[172:175], v[36:39]
	v_mfma_f32_16x16x32_bf16 v[32:35], v[156:159], v[172:175], v[32:35]
	v_mfma_f32_16x16x32_bf16 v[20:23], v[148:151], v[180:183], v[20:23]
	v_mfma_f32_16x16x32_bf16 v[16:19], v[156:159], v[180:183], v[16:19]
	v_mfma_f32_16x16x32_bf16 v[4:7], v[148:151], v[208:211], v[4:7]
	v_mfma_f32_16x16x32_bf16 v[0:3], v[156:159], v[208:211], v[0:3]
	v_mfma_f32_16x16x32_bf16 v[52:55], v[152:155], v[168:171], v[52:55]
	v_mfma_f32_16x16x32_bf16 v[48:51], v[160:163], v[168:171], v[48:51]
	v_mfma_f32_16x16x32_bf16 v[36:39], v[152:155], v[176:179], v[36:39]
	v_mfma_f32_16x16x32_bf16 v[32:35], v[160:163], v[176:179], v[32:35]
	v_mfma_f32_16x16x32_bf16 v[20:23], v[152:155], v[204:207], v[20:23]
	v_mfma_f32_16x16x32_bf16 v[16:19], v[160:163], v[204:207], v[16:19]
	v_mfma_f32_16x16x32_bf16 v[4:7], v[152:155], v[212:215], v[4:7]
	v_mfma_f32_16x16x32_bf16 v[0:3], v[160:163], v[212:215], v[0:3]
	s_barrier
	s_setprio 0
	s_add_i32 s10, s71, 2
	s_add_u32 s38, s38, 0x100
	s_addc_u32 s39, s39, 0
	s_cmp_gt_u32 s71, 13
	s_mov_b32 s71, s10
	s_cbranch_scc1 .LBB0_1025
